# overlap across segments: next tile first B-fragment ds_reads issued at the unit-loop header ahead of the scalar tile decode
# baseline (speedup 1.0000x reference)
.LBB0_251:
	ds_read_b128 v[162:165], v157
	ds_read_b128 v[166:169], v157 offset:1024
	ds_read_b128 v[170:173], v157 offset:2048
	ds_read_b128 v[174:177], v157 offset:3072
	ds_read_b128 v[182:185], v158
	ds_read_b128 v[186:189], v158 offset:1024
	ds_read_b128 v[190:193], v158 offset:2048
	ds_read_b128 v[194:197], v158 offset:3072
	s_add_i32 s61, s62, 1
	s_mul_i32 s2, s61, s56
	s_mul_hi_u32 s3, s61, s57
	s_add_i32 s3, s3, s2
	s_mul_i32 s2, s61, s57
	s_add_u32 s22, s2, s96
	s_addc_u32 s23, s3, s35
	v_cmp_gt_i64_e32 vcc, s[22:23], v[152:153]
	v_cmp_lt_i64_e64 s[2:3], s[22:23], v[150:151]
	s_cbranch_vccnz .LBB0_253
	s_ashr_i32 s12, s22, 31
	s_lshr_b32 s12, s12, 29
	s_add_i32 s12, s22, s12
	s_ashr_i32 s13, s12, 3
	s_and_b32 s12, s12, -8
	s_sub_i32 s12, s22, s12
	s_cmp_lt_i32 s12, 0
	s_movk_i32 s20, 0x2c1
	s_cselect_b32 s20, s20, 0x2c0
	s_mul_i32 s12, s12, s20
	s_add_i32 s12, s12, s13
	s_mul_hi_i32 s13, s12, 0x2e8ba2e9
	s_lshr_b32 s20, s13, 31
	s_ashr_i32 s13, s13, 5
	s_add_i32 s13, s13, s20
	s_lshl_b32 s20, s13, 3
	s_mulk_i32 s13, 0xb0
	s_sub_i32 s13, s12, s13
	s_ashr_i32 s12, s13, 3
	s_and_b32 s13, s13, 7
	s_add_i32 s20, s20, s13
.LBB0_253:
	s_ashr_i32 s21, s20, 31
	s_lshl_b64 s[22:23], s[20:21], 19
	s_add_u32 s22, s92, s22
	s_addc_u32 s23, s93, s23
	s_and_b64 s[24:25], s[2:3], exec
	s_cselect_b32 s21, s23, s15
	s_cselect_b32 s63, s22, s14
	s_ashr_i32 s13, s12, 31
	s_lshl_b64 s[24:25], s[12:13], 19
	s_add_u32 s24, s0, s24
	s_addc_u32 s25, s1, s25
	s_and_b64 s[30:31], s[2:3], exec
	s_cselect_b32 s13, s25, s41
	s_cselect_b32 s64, s24, s40
	s_add_u32 s30, s14, 0x40080
	s_addc_u32 s31, s15, 0
	s_add_u32 s65, s40, 0x100

	s_addc_u32 s66, s41, 0
	s_mov_b32 s67, -2


	s_add_u32 s14, s30, 0xfffc0080
	s_addc_u32 s15, s31, -1
	s_cmp_eq_u32 s67, 12
	s_cselect_b32 s41, s21, s15
	s_cselect_b32 s40, s63, s14
	s_cselect_b32 s15, s13, s66
	s_cselect_b32 s14, s64, s65
	v_lshl_add_u64 v[178:179], s[30:31], 0, v[146:147]
	s_add_i32 m0, s29, 0xc000
	ds_read_b128 v[198:201], v159
	ds_read_b128 v[202:205], v159 offset:1024
	ds_read_b128 v[206:209], v159 offset:2048
	ds_read_b128 v[210:213], v159 offset:3072
	ds_read_b128 v[214:217], v159 offset:4096
	ds_read_b128 v[218:221], v159 offset:5120
	ds_read_b128 v[222:225], v159 offset:6144
	ds_read_b128 v[226:229], v159 offset:7168
	global_load_lds_dwordx4 v[178:179], off
	v_lshl_add_u64 v[178:179], s[30:31], 0, v[148:149]
	s_add_i32 m0, s29, 0xe000
	s_nop 0
	global_load_lds_dwordx4 v[178:179], off
	s_waitcnt vmcnt(8)
	s_waitcnt lgkmcnt(0)
	s_barrier
	s_setprio 1
	s_waitcnt lgkmcnt(0)
	v_mfma_f32_16x16x32_bf16 v[126:129], v[162:165], v[198:201], 0
	v_mfma_f32_16x16x32_bf16 v[118:121], v[170:173], v[198:201], 0
	v_mfma_f32_16x16x32_bf16 v[110:113], v[162:165], v[206:209], 0
	v_mfma_f32_16x16x32_bf16 v[102:105], v[170:173], v[206:209], 0
	v_mfma_f32_16x16x32_bf16 v[94:97], v[162:165], v[214:217], 0
	v_mfma_f32_16x16x32_bf16 v[86:89], v[170:173], v[214:217], 0
	v_mfma_f32_16x16x32_bf16 v[78:81], v[162:165], v[222:225], 0
	v_mfma_f32_16x16x32_bf16 v[70:73], v[170:173], v[222:225], 0
	v_mfma_f32_16x16x32_bf16 v[126:129], v[166:169], v[202:205], v[126:129]
	v_mfma_f32_16x16x32_bf16 v[118:121], v[174:177], v[202:205], v[118:121]
	v_mfma_f32_16x16x32_bf16 v[110:113], v[166:169], v[210:213], v[110:113]
	v_mfma_f32_16x16x32_bf16 v[102:105], v[174:177], v[210:213], v[102:105]
	v_mfma_f32_16x16x32_bf16 v[94:97], v[166:169], v[218:221], v[94:97]
	v_mfma_f32_16x16x32_bf16 v[86:89], v[174:177], v[218:221], v[86:89]
	v_mfma_f32_16x16x32_bf16 v[78:81], v[166:169], v[226:229], v[78:81]
	v_mfma_f32_16x16x32_bf16 v[70:73], v[174:177], v[226:229], v[70:73]
	s_setprio 0
	s_setprio 1
	v_mfma_f32_16x16x32_bf16 v[122:125], v[182:185], v[198:201], 0
	v_mfma_f32_16x16x32_bf16 v[114:117], v[190:193], v[198:201], 0
	v_mfma_f32_16x16x32_bf16 v[106:109], v[182:185], v[206:209], 0
	v_mfma_f32_16x16x32_bf16 v[98:101], v[190:193], v[206:209], 0
	v_mfma_f32_16x16x32_bf16 v[90:93], v[182:185], v[214:217], 0
	v_mfma_f32_16x16x32_bf16 v[82:85], v[190:193], v[214:217], 0
	v_mfma_f32_16x16x32_bf16 v[74:77], v[182:185], v[222:225], 0
	v_mfma_f32_16x16x32_bf16 v[66:69], v[190:193], v[222:225], 0
	v_mfma_f32_16x16x32_bf16 v[122:125], v[186:189], v[202:205], v[122:125]
	v_mfma_f32_16x16x32_bf16 v[114:117], v[194:197], v[202:205], v[114:117]
	v_mfma_f32_16x16x32_bf16 v[106:109], v[186:189], v[210:213], v[106:109]
	v_mfma_f32_16x16x32_bf16 v[98:101], v[194:197], v[210:213], v[98:101]
	v_mfma_f32_16x16x32_bf16 v[90:93], v[186:189], v[218:221], v[90:93]
	v_mfma_f32_16x16x32_bf16 v[82:85], v[194:197], v[218:221], v[82:85]
	v_mfma_f32_16x16x32_bf16 v[74:77], v[186:189], v[226:229], v[74:77]
	v_mfma_f32_16x16x32_bf16 v[66:69], v[194:197], v[226:229], v[66:69]
	s_setprio 0
	s_barrier
	s_add_i32 s33, s58, s27
	v_lshl_add_u64 v[178:179], s[14:15], 0, v[132:133]
	s_mov_b32 m0, s33
	ds_read_b128 v[198:201], v159 offset:16384
	ds_read_b128 v[202:205], v159 offset:17408
	ds_read_b128 v[206:209], v159 offset:18432
	ds_read_b128 v[210:213], v159 offset:19456
	ds_read_b128 v[214:217], v159 offset:20480
	ds_read_b128 v[218:221], v159 offset:21504
	ds_read_b128 v[222:225], v159 offset:22528
	ds_read_b128 v[226:229], v159 offset:23552
	global_load_lds_dwordx4 v[178:179], off
	s_add_i32 m0, s33, 0x2000
	s_add_u32 s54, s14, 0x40000
	v_lshl_add_u64 v[230:231], s[14:15], 0, v[136:137]
	s_addc_u32 s55, s15, 0
	s_add_i32 s33, s59, s27
	global_load_lds_dwordx4 v[230:231], off
	v_lshl_add_u64 v[232:233], s[54:55], 0, v[132:133]
	s_mov_b32 m0, s33
	v_lshl_add_u64 v[234:235], s[40:41], 0, v[134:135]
	global_load_lds_dwordx4 v[232:233], off
	v_lshl_add_u64 v[232:233], s[54:55], 0, v[136:137]
	s_add_i32 m0, s33, 0x2000
	s_nop 0
	global_load_lds_dwordx4 v[232:233], off
	v_lshl_add_u64 v[232:233], s[40:41], 0, v[130:131]
	s_mov_b32 m0, s29
	s_nop 0
	global_load_lds_dwordx4 v[232:233], off
	s_mov_b32 m0, s42
	s_nop 0
	global_load_lds_dwordx4 v[234:235], off
	s_waitcnt vmcnt(8)
	s_waitcnt lgkmcnt(0)
	s_barrier
	s_setprio 1
	s_waitcnt lgkmcnt(0)
	v_mfma_f32_16x16x32_bf16 v[62:65], v[162:165], v[198:201], 0
	v_mfma_f32_16x16x32_bf16 v[54:57], v[170:173], v[198:201], 0
	v_mfma_f32_16x16x32_bf16 v[46:49], v[162:165], v[206:209], 0
	v_mfma_f32_16x16x32_bf16 v[38:41], v[170:173], v[206:209], 0
	v_mfma_f32_16x16x32_bf16 v[30:33], v[162:165], v[214:217], 0
	v_mfma_f32_16x16x32_bf16 v[22:25], v[170:173], v[214:217], 0
	v_mfma_f32_16x16x32_bf16 v[14:17], v[162:165], v[222:225], 0
	v_mfma_f32_16x16x32_bf16 v[6:9], v[170:173], v[222:225], 0
	v_mfma_f32_16x16x32_bf16 v[62:65], v[166:169], v[202:205], v[62:65]
	v_mfma_f32_16x16x32_bf16 v[54:57], v[174:177], v[202:205], v[54:57]
	v_mfma_f32_16x16x32_bf16 v[46:49], v[166:169], v[210:213], v[46:49]
	v_mfma_f32_16x16x32_bf16 v[38:41], v[174:177], v[210:213], v[38:41]
	v_mfma_f32_16x16x32_bf16 v[30:33], v[166:169], v[218:221], v[30:33]
	v_mfma_f32_16x16x32_bf16 v[22:25], v[174:177], v[218:221], v[22:25]
	v_mfma_f32_16x16x32_bf16 v[14:17], v[166:169], v[226:229], v[14:17]
	v_mfma_f32_16x16x32_bf16 v[6:9], v[174:177], v[226:229], v[6:9]
	s_setprio 0
	s_setprio 1
	v_mfma_f32_16x16x32_bf16 v[58:61], v[182:185], v[198:201], 0
	v_mfma_f32_16x16x32_bf16 v[50:53], v[190:193], v[198:201], 0
	v_mfma_f32_16x16x32_bf16 v[42:45], v[182:185], v[206:209], 0
	v_mfma_f32_16x16x32_bf16 v[34:37], v[190:193], v[206:209], 0
	v_mfma_f32_16x16x32_bf16 v[26:29], v[182:185], v[214:217], 0
	v_mfma_f32_16x16x32_bf16 v[18:21], v[190:193], v[214:217], 0
	v_mfma_f32_16x16x32_bf16 v[10:13], v[182:185], v[222:225], 0
	v_mfma_f32_16x16x32_bf16 v[2:5], v[190:193], v[222:225], 0
	v_mfma_f32_16x16x32_bf16 v[58:61], v[186:189], v[202:205], v[58:61]
	v_mfma_f32_16x16x32_bf16 v[50:53], v[194:197], v[202:205], v[50:53]
	v_mfma_f32_16x16x32_bf16 v[42:45], v[186:189], v[210:213], v[42:45]
	v_mfma_f32_16x16x32_bf16 v[34:37], v[194:197], v[210:213], v[34:37]
	v_mfma_f32_16x16x32_bf16 v[26:29], v[186:189], v[218:221], v[26:29]
	v_mfma_f32_16x16x32_bf16 v[18:21], v[194:197], v[218:221], v[18:21]
	v_mfma_f32_16x16x32_bf16 v[10:13], v[186:189], v[226:229], v[10:13]
	v_mfma_f32_16x16x32_bf16 v[2:5], v[194:197], v[226:229], v[2:5]
	s_setprio 0
	s_barrier
	s_add_i32 s33, 0, 0x18000
	v_add_u32_e32 v161, s33, v155
	s_add_i32 s51, 0, 0x1c000
	ds_read_b128 v[162:165], v161
	ds_read_b128 v[166:169], v161 offset:1024
	ds_read_b128 v[170:173], v161 offset:2048
	ds_read_b128 v[174:177], v161 offset:3072
	v_add_u32_e32 v161, s51, v155
	ds_read_b128 v[182:185], v161
	ds_read_b128 v[186:189], v161 offset:1024
	ds_read_b128 v[190:193], v161 offset:2048
	ds_read_b128 v[194:197], v161 offset:3072
	s_add_u32 s40, s40, 0x40000
	s_addc_u32 s41, s41, 0
	s_mov_b32 m0, s43
	v_lshl_add_u64 v[236:237], s[40:41], 0, v[130:131]
	ds_read_b128 v[198:201], v159 offset:32768
	ds_read_b128 v[202:205], v159 offset:33792
	ds_read_b128 v[206:209], v159 offset:34816
	ds_read_b128 v[210:213], v159 offset:35840
	ds_read_b128 v[214:217], v159 offset:36864
	ds_read_b128 v[218:221], v159 offset:37888
	ds_read_b128 v[222:225], v159 offset:38912
	ds_read_b128 v[226:229], v159 offset:39936
	global_load_lds_dwordx4 v[236:237], off
	v_lshl_add_u64 v[236:237], s[40:41], 0, v[134:135]
	s_mov_b32 m0, s46
	s_nop 0
	global_load_lds_dwordx4 v[236:237], off
	s_waitcnt vmcnt(8)
	s_waitcnt lgkmcnt(0)
	s_barrier
	s_setprio 1
	s_waitcnt lgkmcnt(0)
	v_mfma_f32_16x16x32_bf16 v[126:129], v[162:165], v[198:201], v[126:129]
	v_mfma_f32_16x16x32_bf16 v[118:121], v[170:173], v[198:201], v[118:121]
	v_mfma_f32_16x16x32_bf16 v[110:113], v[162:165], v[206:209], v[110:113]
	v_mfma_f32_16x16x32_bf16 v[102:105], v[170:173], v[206:209], v[102:105]
	v_mfma_f32_16x16x32_bf16 v[94:97], v[162:165], v[214:217], v[94:97]
	v_mfma_f32_16x16x32_bf16 v[86:89], v[170:173], v[214:217], v[86:89]
	v_mfma_f32_16x16x32_bf16 v[78:81], v[162:165], v[222:225], v[78:81]
	v_mfma_f32_16x16x32_bf16 v[70:73], v[170:173], v[222:225], v[70:73]
	v_mfma_f32_16x16x32_bf16 v[126:129], v[166:169], v[202:205], v[126:129]
	v_mfma_f32_16x16x32_bf16 v[118:121], v[174:177], v[202:205], v[118:121]
	v_mfma_f32_16x16x32_bf16 v[110:113], v[166:169], v[210:213], v[110:113]
	v_mfma_f32_16x16x32_bf16 v[102:105], v[174:177], v[210:213], v[102:105]
	v_mfma_f32_16x16x32_bf16 v[94:97], v[166:169], v[218:221], v[94:97]
	v_mfma_f32_16x16x32_bf16 v[86:89], v[174:177], v[218:221], v[86:89]
	v_mfma_f32_16x16x32_bf16 v[78:81], v[166:169], v[226:229], v[78:81]
	v_mfma_f32_16x16x32_bf16 v[70:73], v[174:177], v[226:229], v[70:73]
	s_setprio 0
	s_setprio 1
	v_mfma_f32_16x16x32_bf16 v[122:125], v[182:185], v[198:201], v[122:125]
	v_mfma_f32_16x16x32_bf16 v[114:117], v[190:193], v[198:201], v[114:117]
	v_mfma_f32_16x16x32_bf16 v[106:109], v[182:185], v[206:209], v[106:109]
	v_mfma_f32_16x16x32_bf16 v[98:101], v[190:193], v[206:209], v[98:101]
	v_mfma_f32_16x16x32_bf16 v[90:93], v[182:185], v[214:217], v[90:93]
	v_mfma_f32_16x16x32_bf16 v[82:85], v[190:193], v[214:217], v[82:85]
	v_mfma_f32_16x16x32_bf16 v[74:77], v[182:185], v[222:225], v[74:77]
	v_mfma_f32_16x16x32_bf16 v[66:69], v[190:193], v[222:225], v[66:69]
	v_mfma_f32_16x16x32_bf16 v[122:125], v[186:189], v[202:205], v[122:125]
	v_mfma_f32_16x16x32_bf16 v[114:117], v[194:197], v[202:205], v[114:117]
	v_mfma_f32_16x16x32_bf16 v[106:109], v[186:189], v[210:213], v[106:109]
	v_mfma_f32_16x16x32_bf16 v[98:101], v[194:197], v[210:213], v[98:101]
	v_mfma_f32_16x16x32_bf16 v[90:93], v[186:189], v[218:221], v[90:93]
	v_mfma_f32_16x16x32_bf16 v[82:85], v[194:197], v[218:221], v[82:85]
	v_mfma_f32_16x16x32_bf16 v[74:77], v[186:189], v[226:229], v[74:77]
	v_mfma_f32_16x16x32_bf16 v[66:69], v[194:197], v[226:229], v[66:69]
	s_setprio 0
	s_barrier
	s_add_i32 s33, s33, s27
	v_lshl_add_u64 v[178:179], v[178:179], 0, s[10:11]
	s_mov_b32 m0, s33
	ds_read_b128 v[198:201], v159 offset:49152
	ds_read_b128 v[202:205], v159 offset:50176
	ds_read_b128 v[206:209], v159 offset:51200
	ds_read_b128 v[210:213], v159 offset:52224
	ds_read_b128 v[214:217], v159 offset:53248
	ds_read_b128 v[218:221], v159 offset:54272
	ds_read_b128 v[222:225], v159 offset:55296
	ds_read_b128 v[226:229], v159 offset:56320
	global_load_lds_dwordx4 v[178:179], off
	s_add_i32 m0, s33, 0x2000
	s_add_u32 s14, s14, 0x40080
	v_lshl_add_u64 v[178:179], v[230:231], 0, s[10:11]
	s_addc_u32 s15, s15, 0
	s_add_i32 s33, s51, s27
	global_load_lds_dwordx4 v[178:179], off
	v_lshl_add_u64 v[178:179], s[14:15], 0, v[132:133]
	s_mov_b32 m0, s33
	s_nop 0
	global_load_lds_dwordx4 v[178:179], off
	v_lshl_add_u64 v[178:179], s[14:15], 0, v[136:137]
	s_add_i32 m0, s33, 0x2000
	s_nop 0
	global_load_lds_dwordx4 v[178:179], off
	v_lshl_add_u64 v[178:179], v[232:233], 0, s[10:11]
	s_mov_b32 m0, s49
	s_nop 0
	global_load_lds_dwordx4 v[178:179], off
	v_lshl_add_u64 v[178:179], v[234:235], 0, s[10:11]
	s_mov_b32 m0, s52
	s_nop 0
	global_load_lds_dwordx4 v[178:179], off
	s_waitcnt vmcnt(8)
	s_waitcnt lgkmcnt(0)
	s_barrier
	s_setprio 1
	s_waitcnt lgkmcnt(0)
	v_mfma_f32_16x16x32_bf16 v[62:65], v[162:165], v[198:201], v[62:65]
	v_mfma_f32_16x16x32_bf16 v[54:57], v[170:173], v[198:201], v[54:57]
	v_mfma_f32_16x16x32_bf16 v[46:49], v[162:165], v[206:209], v[46:49]
	v_mfma_f32_16x16x32_bf16 v[38:41], v[170:173], v[206:209], v[38:41]
	v_mfma_f32_16x16x32_bf16 v[30:33], v[162:165], v[214:217], v[30:33]
	v_mfma_f32_16x16x32_bf16 v[22:25], v[170:173], v[214:217], v[22:25]
	v_mfma_f32_16x16x32_bf16 v[14:17], v[162:165], v[222:225], v[14:17]
	v_mfma_f32_16x16x32_bf16 v[6:9], v[170:173], v[222:225], v[6:9]
	v_mfma_f32_16x16x32_bf16 v[62:65], v[166:169], v[202:205], v[62:65]
	v_mfma_f32_16x16x32_bf16 v[54:57], v[174:177], v[202:205], v[54:57]
	v_mfma_f32_16x16x32_bf16 v[46:49], v[166:169], v[210:213], v[46:49]
	v_mfma_f32_16x16x32_bf16 v[38:41], v[174:177], v[210:213], v[38:41]
	v_mfma_f32_16x16x32_bf16 v[30:33], v[166:169], v[218:221], v[30:33]
	v_mfma_f32_16x16x32_bf16 v[22:25], v[174:177], v[218:221], v[22:25]
	v_mfma_f32_16x16x32_bf16 v[14:17], v[166:169], v[226:229], v[14:17]
	v_mfma_f32_16x16x32_bf16 v[6:9], v[174:177], v[226:229], v[6:9]
	s_setprio 0
	s_setprio 1
	v_mfma_f32_16x16x32_bf16 v[58:61], v[182:185], v[198:201], v[58:61]
	v_mfma_f32_16x16x32_bf16 v[50:53], v[190:193], v[198:201], v[50:53]
	v_mfma_f32_16x16x32_bf16 v[42:45], v[182:185], v[206:209], v[42:45]
	v_mfma_f32_16x16x32_bf16 v[34:37], v[190:193], v[206:209], v[34:37]
	v_mfma_f32_16x16x32_bf16 v[26:29], v[182:185], v[214:217], v[26:29]
	v_mfma_f32_16x16x32_bf16 v[18:21], v[190:193], v[214:217], v[18:21]
	v_mfma_f32_16x16x32_bf16 v[10:13], v[182:185], v[222:225], v[10:13]
	v_mfma_f32_16x16x32_bf16 v[2:5], v[190:193], v[222:225], v[2:5]
	v_mfma_f32_16x16x32_bf16 v[58:61], v[186:189], v[202:205], v[58:61]
	v_mfma_f32_16x16x32_bf16 v[50:53], v[194:197], v[202:205], v[50:53]
	v_mfma_f32_16x16x32_bf16 v[42:45], v[186:189], v[210:213], v[42:45]
	v_mfma_f32_16x16x32_bf16 v[34:37], v[194:197], v[210:213], v[34:37]
	v_mfma_f32_16x16x32_bf16 v[26:29], v[186:189], v[218:221], v[26:29]
	v_mfma_f32_16x16x32_bf16 v[18:21], v[194:197], v[218:221], v[18:21]
	v_mfma_f32_16x16x32_bf16 v[10:13], v[186:189], v[226:229], v[10:13]
	v_mfma_f32_16x16x32_bf16 v[2:5], v[194:197], v[226:229], v[2:5]
	s_setprio 0
	s_barrier
	s_add_i32 s67, s67, 2
	s_add_u32 s30, s30, 0x100
	s_addc_u32 s31, s31, 0
	s_add_u32 s65, s65, 0x100
	s_addc_u32 s66, s66, 0

.LBB0_351:
	ds_read_b128 v[130:133], v170
	ds_read_b128 v[134:137], v170 offset:1024
	ds_read_b128 v[160:163], v170 offset:2048
	ds_read_b128 v[164:167], v170 offset:3072
	ds_read_b128 v[174:177], v171
	ds_read_b128 v[182:185], v171 offset:1024
	ds_read_b128 v[186:189], v171 offset:2048
	ds_read_b128 v[190:193], v171 offset:3072
	s_add_i32 s42, s42, 1
	s_mul_i32 s4, s42, s48
	s_mul_hi_u32 s5, s42, s49
	s_add_i32 s5, s5, s4
	s_mul_i32 s4, s42, s49
	s_add_u32 s4, s4, s96
	s_addc_u32 s5, s5, s52
	v_cmp_gt_i64_e32 vcc, s[4:5], v[158:159]
	v_cmp_lt_i64_e64 s[6:7], s[4:5], v[156:157]
	s_cbranch_vccnz .LBB0_357
	s_ashr_i32 s5, s4, 31
	s_lshr_b32 s5, s5, 29
	s_add_i32 s22, s4, s5
	s_and_b32 s5, s22, -8
	s_sub_i32 s23, s4, s5
	s_cmp_gt_i32 s23, -1
	s_mov_b64 s[4:5], -1
	s_cbranch_scc0 .LBB0_354
	s_lshl_b32 s26, s23, 7
	s_mov_b64 s[4:5], 0

.LBB0_361:
	s_add_u32 s62, s14, 0x100
	s_addc_u32 s63, s15, 0
	s_add_u32 s24, s24, 0xc000

	s_addc_u32 s25, s25, 0
	s_mov_b32 s64, -2
	s_waitcnt lgkmcnt(0)


	s_add_u32 s14, s24, 0x4000
	s_addc_u32 s15, s25, 0
	s_cmp_eq_u32 s64, 40
	s_cselect_b32 s28, s6, s14
	s_cselect_b32 s29, s7, s15
	s_cselect_b32 s26, s22, s62
	s_cselect_b32 s27, s23, s63
	s_add_u32 s14, s28, 0x8000
	s_addc_u32 s15, s29, 0
	v_lshl_add_u64 v[138:139], s[24:25], 0, v[152:153]
	s_add_i32 m0, s31, 0xc000
	ds_read_b128 v[194:197], v172
	ds_read_b128 v[198:201], v172 offset:1024
	ds_read_b128 v[202:205], v172 offset:2048
	ds_read_b128 v[206:209], v172 offset:3072
	ds_read_b128 v[210:213], v172 offset:4096
	ds_read_b128 v[214:217], v172 offset:5120
	ds_read_b128 v[218:221], v172 offset:6144
	ds_read_b128 v[222:225], v172 offset:7168
	global_load_lds_dwordx4 v[138:139], off
	v_lshl_add_u64 v[138:139], s[24:25], 0, v[154:155]
	s_add_i32 m0, s31, 0xe000
	s_nop 0
	global_load_lds_dwordx4 v[138:139], off
	s_waitcnt vmcnt(8)
	s_waitcnt lgkmcnt(0)
	s_barrier
	s_setprio 1
	s_waitcnt lgkmcnt(0)
	v_mfma_f32_16x16x32_bf16 v[126:129], v[130:133], v[194:197], 0
	v_mfma_f32_16x16x32_bf16 v[122:125], v[160:163], v[194:197], 0
	v_mfma_f32_16x16x32_bf16 v[110:113], v[130:133], v[202:205], 0
	v_mfma_f32_16x16x32_bf16 v[106:109], v[160:163], v[202:205], 0
	v_mfma_f32_16x16x32_bf16 v[94:97], v[130:133], v[210:213], 0
	v_mfma_f32_16x16x32_bf16 v[90:93], v[160:163], v[210:213], 0
	v_mfma_f32_16x16x32_bf16 v[78:81], v[130:133], v[218:221], 0
	v_mfma_f32_16x16x32_bf16 v[74:77], v[160:163], v[218:221], 0
	v_mfma_f32_16x16x32_bf16 v[126:129], v[134:137], v[198:201], v[126:129]
	v_mfma_f32_16x16x32_bf16 v[122:125], v[164:167], v[198:201], v[122:125]
	v_mfma_f32_16x16x32_bf16 v[110:113], v[134:137], v[206:209], v[110:113]
	v_mfma_f32_16x16x32_bf16 v[106:109], v[164:167], v[206:209], v[106:109]
	v_mfma_f32_16x16x32_bf16 v[94:97], v[134:137], v[214:217], v[94:97]
	v_mfma_f32_16x16x32_bf16 v[90:93], v[164:167], v[214:217], v[90:93]
	v_mfma_f32_16x16x32_bf16 v[78:81], v[134:137], v[222:225], v[78:81]
	v_mfma_f32_16x16x32_bf16 v[74:77], v[164:167], v[222:225], v[74:77]
	s_setprio 0
	s_setprio 1
	v_mfma_f32_16x16x32_bf16 v[118:121], v[174:177], v[194:197], 0
	v_mfma_f32_16x16x32_bf16 v[114:117], v[186:189], v[194:197], 0
	v_mfma_f32_16x16x32_bf16 v[102:105], v[174:177], v[202:205], 0
	v_mfma_f32_16x16x32_bf16 v[98:101], v[186:189], v[202:205], 0
	v_mfma_f32_16x16x32_bf16 v[86:89], v[174:177], v[210:213], 0
	v_mfma_f32_16x16x32_bf16 v[82:85], v[186:189], v[210:213], 0
	v_mfma_f32_16x16x32_bf16 v[70:73], v[174:177], v[218:221], 0
	v_mfma_f32_16x16x32_bf16 v[66:69], v[186:189], v[218:221], 0
	v_mfma_f32_16x16x32_bf16 v[118:121], v[182:185], v[198:201], v[118:121]
	v_mfma_f32_16x16x32_bf16 v[114:117], v[190:193], v[198:201], v[114:117]
	v_mfma_f32_16x16x32_bf16 v[102:105], v[182:185], v[206:209], v[102:105]
	v_mfma_f32_16x16x32_bf16 v[98:101], v[190:193], v[206:209], v[98:101]
	v_mfma_f32_16x16x32_bf16 v[86:89], v[182:185], v[214:217], v[86:89]
	v_mfma_f32_16x16x32_bf16 v[82:85], v[190:193], v[214:217], v[82:85]
	v_mfma_f32_16x16x32_bf16 v[70:73], v[182:185], v[222:225], v[70:73]
	v_mfma_f32_16x16x32_bf16 v[66:69], v[190:193], v[222:225], v[66:69]
	s_setprio 0
	s_barrier
	s_add_i32 s33, s53, s30
	v_lshl_add_u64 v[138:139], s[26:27], 0, v[144:145]
	s_mov_b32 m0, s33
	ds_read_b128 v[194:197], v172 offset:16384
	ds_read_b128 v[198:201], v172 offset:17408
	ds_read_b128 v[202:205], v172 offset:18432
	ds_read_b128 v[206:209], v172 offset:19456
	ds_read_b128 v[210:213], v172 offset:20480
	ds_read_b128 v[214:217], v172 offset:21504
	ds_read_b128 v[218:221], v172 offset:22528
	ds_read_b128 v[222:225], v172 offset:23552
	global_load_lds_dwordx4 v[138:139], off
	s_add_i32 m0, s33, 0x2000
	s_add_u32 s54, s26, 0xb0000
	v_lshl_add_u64 v[178:179], s[26:27], 0, v[148:149]
	s_addc_u32 s55, s27, 0
	s_add_i32 s33, s56, s30
	global_load_lds_dwordx4 v[178:179], off
	v_lshl_add_u64 v[226:227], s[54:55], 0, v[144:145]
	s_mov_b32 m0, s33
	s_nop 0
	global_load_lds_dwordx4 v[226:227], off
	v_lshl_add_u64 v[226:227], s[54:55], 0, v[148:149]
	s_add_i32 m0, s33, 0x2000
	s_nop 0
	global_load_lds_dwordx4 v[226:227], off
	v_lshl_add_u64 v[226:227], s[28:29], 0, v[142:143]
	s_mov_b32 m0, s31
	s_nop 0
	global_load_lds_dwordx4 v[226:227], off
	v_lshl_add_u64 v[226:227], s[28:29], 0, v[146:147]
	s_mov_b32 m0, s35
	s_nop 0
	global_load_lds_dwordx4 v[226:227], off
	s_waitcnt vmcnt(8)
	s_waitcnt lgkmcnt(0)
	s_barrier
	s_setprio 1
	s_waitcnt lgkmcnt(0)
	v_mfma_f32_16x16x32_bf16 v[62:65], v[130:133], v[194:197], 0
	v_mfma_f32_16x16x32_bf16 v[58:61], v[160:163], v[194:197], 0
	v_mfma_f32_16x16x32_bf16 v[46:49], v[130:133], v[202:205], 0
	v_mfma_f32_16x16x32_bf16 v[42:45], v[160:163], v[202:205], 0
	v_mfma_f32_16x16x32_bf16 v[30:33], v[130:133], v[210:213], 0
	v_mfma_f32_16x16x32_bf16 v[26:29], v[160:163], v[210:213], 0
	v_mfma_f32_16x16x32_bf16 v[14:17], v[130:133], v[218:221], 0
	v_mfma_f32_16x16x32_bf16 v[10:13], v[160:163], v[218:221], 0
	v_mfma_f32_16x16x32_bf16 v[62:65], v[134:137], v[198:201], v[62:65]
	v_mfma_f32_16x16x32_bf16 v[58:61], v[164:167], v[198:201], v[58:61]
	v_mfma_f32_16x16x32_bf16 v[46:49], v[134:137], v[206:209], v[46:49]
	v_mfma_f32_16x16x32_bf16 v[42:45], v[164:167], v[206:209], v[42:45]
	v_mfma_f32_16x16x32_bf16 v[30:33], v[134:137], v[214:217], v[30:33]
	v_mfma_f32_16x16x32_bf16 v[26:29], v[164:167], v[214:217], v[26:29]
	v_mfma_f32_16x16x32_bf16 v[14:17], v[134:137], v[222:225], v[14:17]
	v_mfma_f32_16x16x32_bf16 v[10:13], v[164:167], v[222:225], v[10:13]
	s_setprio 0
	s_setprio 1
	v_mfma_f32_16x16x32_bf16 v[54:57], v[174:177], v[194:197], 0
	v_mfma_f32_16x16x32_bf16 v[50:53], v[186:189], v[194:197], 0
	v_mfma_f32_16x16x32_bf16 v[38:41], v[174:177], v[202:205], 0
	v_mfma_f32_16x16x32_bf16 v[34:37], v[186:189], v[202:205], 0
	v_mfma_f32_16x16x32_bf16 v[22:25], v[174:177], v[210:213], 0
	v_mfma_f32_16x16x32_bf16 v[18:21], v[186:189], v[210:213], 0
	v_mfma_f32_16x16x32_bf16 v[6:9], v[174:177], v[218:221], 0
	v_mfma_f32_16x16x32_bf16 v[2:5], v[186:189], v[218:221], 0
	v_mfma_f32_16x16x32_bf16 v[54:57], v[182:185], v[198:201], v[54:57]
	v_mfma_f32_16x16x32_bf16 v[50:53], v[190:193], v[198:201], v[50:53]
	v_mfma_f32_16x16x32_bf16 v[38:41], v[182:185], v[206:209], v[38:41]
	v_mfma_f32_16x16x32_bf16 v[34:37], v[190:193], v[206:209], v[34:37]
	v_mfma_f32_16x16x32_bf16 v[22:25], v[182:185], v[214:217], v[22:25]
	v_mfma_f32_16x16x32_bf16 v[18:21], v[190:193], v[214:217], v[18:21]
	v_mfma_f32_16x16x32_bf16 v[6:9], v[182:185], v[222:225], v[6:9]
	v_mfma_f32_16x16x32_bf16 v[2:5], v[190:193], v[222:225], v[2:5]
	s_setprio 0
	s_barrier
	s_add_i32 s33, 0, 0x18000
	v_add_u32_e32 v150, s33, v168
	s_add_i32 s51, 0, 0x1c000
	ds_read_b128 v[130:133], v150
	ds_read_b128 v[134:137], v150 offset:1024
	ds_read_b128 v[160:163], v150 offset:2048
	ds_read_b128 v[164:167], v150 offset:3072
	v_add_u32_e32 v150, s51, v168
	ds_read_b128 v[174:177], v150
	ds_read_b128 v[182:185], v150 offset:1024
	ds_read_b128 v[186:189], v150 offset:2048
	ds_read_b128 v[190:193], v150 offset:3072
	s_add_u32 s28, s28, 0x4000
	s_addc_u32 s29, s29, 0
	s_mov_b32 m0, s40
	v_lshl_add_u64 v[226:227], s[28:29], 0, v[142:143]
	ds_read_b128 v[194:197], v172 offset:32768
	ds_read_b128 v[198:201], v172 offset:33792
	ds_read_b128 v[202:205], v172 offset:34816
	ds_read_b128 v[206:209], v172 offset:35840
	ds_read_b128 v[210:213], v172 offset:36864
	ds_read_b128 v[214:217], v172 offset:37888
	ds_read_b128 v[218:221], v172 offset:38912
	ds_read_b128 v[222:225], v172 offset:39936
	global_load_lds_dwordx4 v[226:227], off
	v_lshl_add_u64 v[226:227], s[28:29], 0, v[146:147]
	s_mov_b32 m0, s41
	s_nop 0
	global_load_lds_dwordx4 v[226:227], off
	s_waitcnt vmcnt(8)
	s_waitcnt lgkmcnt(0)
	s_barrier
	s_setprio 1
	s_waitcnt lgkmcnt(0)
	v_mfma_f32_16x16x32_bf16 v[126:129], v[130:133], v[194:197], v[126:129]
	v_mfma_f32_16x16x32_bf16 v[122:125], v[160:163], v[194:197], v[122:125]
	v_mfma_f32_16x16x32_bf16 v[110:113], v[130:133], v[202:205], v[110:113]
	v_mfma_f32_16x16x32_bf16 v[106:109], v[160:163], v[202:205], v[106:109]
	v_mfma_f32_16x16x32_bf16 v[94:97], v[130:133], v[210:213], v[94:97]
	v_mfma_f32_16x16x32_bf16 v[90:93], v[160:163], v[210:213], v[90:93]
	v_mfma_f32_16x16x32_bf16 v[78:81], v[130:133], v[218:221], v[78:81]
	v_mfma_f32_16x16x32_bf16 v[74:77], v[160:163], v[218:221], v[74:77]
	v_mfma_f32_16x16x32_bf16 v[126:129], v[134:137], v[198:201], v[126:129]
	v_mfma_f32_16x16x32_bf16 v[122:125], v[164:167], v[198:201], v[122:125]
	v_mfma_f32_16x16x32_bf16 v[110:113], v[134:137], v[206:209], v[110:113]
	v_mfma_f32_16x16x32_bf16 v[106:109], v[164:167], v[206:209], v[106:109]
	v_mfma_f32_16x16x32_bf16 v[94:97], v[134:137], v[214:217], v[94:97]
	v_mfma_f32_16x16x32_bf16 v[90:93], v[164:167], v[214:217], v[90:93]
	v_mfma_f32_16x16x32_bf16 v[78:81], v[134:137], v[222:225], v[78:81]
	v_mfma_f32_16x16x32_bf16 v[74:77], v[164:167], v[222:225], v[74:77]
	s_setprio 0
	s_setprio 1
	v_mfma_f32_16x16x32_bf16 v[118:121], v[174:177], v[194:197], v[118:121]
	v_mfma_f32_16x16x32_bf16 v[114:117], v[186:189], v[194:197], v[114:117]
	v_mfma_f32_16x16x32_bf16 v[102:105], v[174:177], v[202:205], v[102:105]
	v_mfma_f32_16x16x32_bf16 v[98:101], v[186:189], v[202:205], v[98:101]
	v_mfma_f32_16x16x32_bf16 v[86:89], v[174:177], v[210:213], v[86:89]
	v_mfma_f32_16x16x32_bf16 v[82:85], v[186:189], v[210:213], v[82:85]
	v_mfma_f32_16x16x32_bf16 v[70:73], v[174:177], v[218:221], v[70:73]
	v_mfma_f32_16x16x32_bf16 v[66:69], v[186:189], v[218:221], v[66:69]
	v_mfma_f32_16x16x32_bf16 v[118:121], v[182:185], v[198:201], v[118:121]
	v_mfma_f32_16x16x32_bf16 v[114:117], v[190:193], v[198:201], v[114:117]
	v_mfma_f32_16x16x32_bf16 v[102:105], v[182:185], v[206:209], v[102:105]
	v_mfma_f32_16x16x32_bf16 v[98:101], v[190:193], v[206:209], v[98:101]
	v_mfma_f32_16x16x32_bf16 v[86:89], v[182:185], v[214:217], v[86:89]
	v_mfma_f32_16x16x32_bf16 v[82:85], v[190:193], v[214:217], v[82:85]
	v_mfma_f32_16x16x32_bf16 v[70:73], v[182:185], v[222:225], v[70:73]
	v_mfma_f32_16x16x32_bf16 v[66:69], v[190:193], v[222:225], v[66:69]
	s_setprio 0
	s_barrier
	s_add_i32 s28, s33, s30
	v_lshl_add_u64 v[138:139], v[138:139], 0, s[12:13]
	s_mov_b32 m0, s28
	ds_read_b128 v[194:197], v172 offset:49152
	ds_read_b128 v[198:201], v172 offset:50176
	ds_read_b128 v[202:205], v172 offset:51200
	ds_read_b128 v[206:209], v172 offset:52224
	ds_read_b128 v[210:213], v172 offset:53248
	ds_read_b128 v[214:217], v172 offset:54272
	ds_read_b128 v[218:221], v172 offset:55296
	ds_read_b128 v[222:225], v172 offset:56320
	global_load_lds_dwordx4 v[138:139], off
	s_add_i32 m0, s28, 0x2000
	s_add_u32 s26, s26, 0xb0080
	v_lshl_add_u64 v[138:139], v[178:179], 0, s[12:13]
	s_addc_u32 s27, s27, 0
	s_add_i32 s28, s51, s30
	global_load_lds_dwordx4 v[138:139], off
	v_lshl_add_u64 v[138:139], s[26:27], 0, v[144:145]
	s_mov_b32 m0, s28
	s_nop 0
	global_load_lds_dwordx4 v[138:139], off
	v_lshl_add_u64 v[138:139], s[26:27], 0, v[148:149]
	s_add_i32 m0, s28, 0x2000
	s_nop 0
	global_load_lds_dwordx4 v[138:139], off
	v_lshl_add_u64 v[138:139], s[14:15], 0, v[142:143]
	s_mov_b32 m0, s46
	s_nop 0
	global_load_lds_dwordx4 v[138:139], off
	v_lshl_add_u64 v[138:139], s[14:15], 0, v[146:147]
	s_mov_b32 m0, s47
	s_nop 0
	global_load_lds_dwordx4 v[138:139], off
	s_waitcnt vmcnt(8)
	s_waitcnt lgkmcnt(0)
	s_barrier
	s_setprio 1
	s_waitcnt lgkmcnt(0)
	v_mfma_f32_16x16x32_bf16 v[62:65], v[130:133], v[194:197], v[62:65]
	v_mfma_f32_16x16x32_bf16 v[58:61], v[160:163], v[194:197], v[58:61]
	v_mfma_f32_16x16x32_bf16 v[46:49], v[130:133], v[202:205], v[46:49]
	v_mfma_f32_16x16x32_bf16 v[42:45], v[160:163], v[202:205], v[42:45]
	v_mfma_f32_16x16x32_bf16 v[30:33], v[130:133], v[210:213], v[30:33]
	v_mfma_f32_16x16x32_bf16 v[26:29], v[160:163], v[210:213], v[26:29]
	v_mfma_f32_16x16x32_bf16 v[14:17], v[130:133], v[218:221], v[14:17]
	v_mfma_f32_16x16x32_bf16 v[10:13], v[160:163], v[218:221], v[10:13]
	v_mfma_f32_16x16x32_bf16 v[62:65], v[134:137], v[198:201], v[62:65]
	v_mfma_f32_16x16x32_bf16 v[58:61], v[164:167], v[198:201], v[58:61]
	v_mfma_f32_16x16x32_bf16 v[46:49], v[134:137], v[206:209], v[46:49]
	v_mfma_f32_16x16x32_bf16 v[42:45], v[164:167], v[206:209], v[42:45]
	v_mfma_f32_16x16x32_bf16 v[30:33], v[134:137], v[214:217], v[30:33]
	v_mfma_f32_16x16x32_bf16 v[26:29], v[164:167], v[214:217], v[26:29]
	v_mfma_f32_16x16x32_bf16 v[14:17], v[134:137], v[222:225], v[14:17]
	v_mfma_f32_16x16x32_bf16 v[10:13], v[164:167], v[222:225], v[10:13]
	s_setprio 0
	s_setprio 1
	v_mfma_f32_16x16x32_bf16 v[54:57], v[174:177], v[194:197], v[54:57]
	v_mfma_f32_16x16x32_bf16 v[50:53], v[186:189], v[194:197], v[50:53]
	v_mfma_f32_16x16x32_bf16 v[38:41], v[174:177], v[202:205], v[38:41]
	v_mfma_f32_16x16x32_bf16 v[34:37], v[186:189], v[202:205], v[34:37]
	v_mfma_f32_16x16x32_bf16 v[22:25], v[174:177], v[210:213], v[22:25]
	v_mfma_f32_16x16x32_bf16 v[18:21], v[186:189], v[210:213], v[18:21]
	v_mfma_f32_16x16x32_bf16 v[6:9], v[174:177], v[218:221], v[6:9]
	v_mfma_f32_16x16x32_bf16 v[2:5], v[186:189], v[218:221], v[2:5]
	v_mfma_f32_16x16x32_bf16 v[54:57], v[182:185], v[198:201], v[54:57]
	v_mfma_f32_16x16x32_bf16 v[50:53], v[190:193], v[198:201], v[50:53]
	v_mfma_f32_16x16x32_bf16 v[38:41], v[182:185], v[206:209], v[38:41]
	v_mfma_f32_16x16x32_bf16 v[34:37], v[190:193], v[206:209], v[34:37]
	v_mfma_f32_16x16x32_bf16 v[22:25], v[182:185], v[214:217], v[22:25]
	v_mfma_f32_16x16x32_bf16 v[18:21], v[190:193], v[214:217], v[18:21]
	v_mfma_f32_16x16x32_bf16 v[6:9], v[182:185], v[222:225], v[6:9]
	v_mfma_f32_16x16x32_bf16 v[2:5], v[190:193], v[222:225], v[2:5]
	s_setprio 0
	s_barrier
	s_add_i32 s64, s64, 2
	s_add_u32 s62, s62, 0x100
	s_addc_u32 s63, s63, 0
	s_add_u32 s24, s24, 0x10000
	s_addc_u32 s25, s25, 0

.LBB0_543:
	ds_read_b128 v[158:161], v170
	ds_read_b128 v[174:177], v170 offset:1024
	ds_read_b128 v[182:185], v170 offset:2048
	ds_read_b128 v[186:189], v170 offset:3072
	ds_read_b128 v[190:193], v171
	ds_read_b128 v[194:197], v171 offset:1024
	ds_read_b128 v[198:201], v171 offset:2048
	ds_read_b128 v[202:205], v171 offset:3072
	s_add_i32 s56, s56, 1
	s_mul_i32 s2, s56, s60
	s_mul_hi_u32 s3, s56, s61
	s_add_i32 s3, s3, s2
	s_mul_i32 s2, s56, s61
	s_add_u32 s28, s2, s96
	s_addc_u32 s29, s3, s62
	v_cmp_gt_i64_e32 vcc, s[28:29], v[156:157]
	v_cmp_lt_i64_e64 s[2:3], s[28:29], v[154:155]
	s_cbranch_vccnz .LBB0_549
	s_ashr_i32 s5, s28, 31
	s_lshr_b32 s5, s5, 29
	s_add_i32 s5, s28, s5
	s_and_b32 s7, s5, -8
	s_sub_i32 s7, s28, s7
	s_cmp_gt_i32 s7, -1
	s_mov_b64 s[24:25], -1
	s_cbranch_scc0 .LBB0_546
	s_lshl_b32 s26, s7, 6
	s_mov_b64 s[24:25], 0

.LBB0_549:
	s_ashr_i32 s27, s26, 31
	s_lshl_b64 s[28:29], s[26:27], 19
	s_add_u32 s28, s92, s28
	s_addc_u32 s29, s93, s29
	s_and_b64 s[30:31], s[2:3], exec
	s_cselect_b32 s5, s29, s41
	s_cselect_b32 s7, s28, s40
	s_ashr_i32 s25, s24, 31
	s_lshl_b64 s[30:31], s[24:25], 19
	v_readlane_b32 s36, v244, 35
	v_readlane_b32 s37, v244, 36
	s_add_u32 s30, s36, s30
	s_addc_u32 s31, s37, s31
	s_and_b64 s[42:43], s[2:3], exec
	s_cselect_b32 s25, s31, s15
	s_cselect_b32 s27, s30, s14
	s_add_u32 s40, s40, 0x40080
	s_addc_u32 s41, s41, 0
	s_add_u32 s74, s14, 0x100

	s_addc_u32 s75, s15, 0
	s_mov_b32 s86, -2


	s_add_u32 s14, s40, 0xfffc0080
	s_addc_u32 s15, s41, -1
	s_cmp_eq_u32 s86, 12
	s_cselect_b32 s43, s5, s15
	s_cselect_b32 s42, s7, s14
	s_cselect_b32 s15, s25, s75
	s_cselect_b32 s14, s27, s74
	v_lshl_add_u64 v[162:163], s[40:41], 0, v[150:151]
	s_add_i32 m0, s48, 0xc000
	ds_read_b128 v[206:209], v172
	ds_read_b128 v[210:213], v172 offset:1024
	ds_read_b128 v[214:217], v172 offset:2048
	ds_read_b128 v[218:221], v172 offset:3072
	ds_read_b128 v[222:225], v172 offset:4096
	ds_read_b128 v[226:229], v172 offset:5120
	ds_read_b128 v[230:233], v172 offset:6144
	ds_read_b128 v[234:237], v172 offset:7168
	global_load_lds_dwordx4 v[162:163], off
	v_lshl_add_u64 v[162:163], s[40:41], 0, v[152:153]
	s_add_i32 m0, s48, 0xe000
	s_nop 0
	global_load_lds_dwordx4 v[162:163], off
	s_waitcnt vmcnt(8)
	s_waitcnt lgkmcnt(0)
	s_barrier
	s_setprio 1
	s_waitcnt lgkmcnt(0)
	v_mfma_f32_16x16x32_bf16 v[126:129], v[158:161], v[206:209], 0
	v_mfma_f32_16x16x32_bf16 v[122:125], v[182:185], v[206:209], 0
	v_mfma_f32_16x16x32_bf16 v[110:113], v[158:161], v[214:217], 0
	v_mfma_f32_16x16x32_bf16 v[106:109], v[182:185], v[214:217], 0
	v_mfma_f32_16x16x32_bf16 v[94:97], v[158:161], v[222:225], 0
	v_mfma_f32_16x16x32_bf16 v[90:93], v[182:185], v[222:225], 0
	v_mfma_f32_16x16x32_bf16 v[78:81], v[158:161], v[230:233], 0
	v_mfma_f32_16x16x32_bf16 v[74:77], v[182:185], v[230:233], 0
	v_mfma_f32_16x16x32_bf16 v[126:129], v[174:177], v[210:213], v[126:129]
	v_mfma_f32_16x16x32_bf16 v[122:125], v[186:189], v[210:213], v[122:125]
	v_mfma_f32_16x16x32_bf16 v[110:113], v[174:177], v[218:221], v[110:113]
	v_mfma_f32_16x16x32_bf16 v[106:109], v[186:189], v[218:221], v[106:109]
	v_mfma_f32_16x16x32_bf16 v[94:97], v[174:177], v[226:229], v[94:97]
	v_mfma_f32_16x16x32_bf16 v[90:93], v[186:189], v[226:229], v[90:93]
	v_mfma_f32_16x16x32_bf16 v[78:81], v[174:177], v[234:237], v[78:81]
	v_mfma_f32_16x16x32_bf16 v[74:77], v[186:189], v[234:237], v[74:77]
	s_setprio 0
	s_setprio 1
	v_mfma_f32_16x16x32_bf16 v[118:121], v[190:193], v[206:209], 0
	v_mfma_f32_16x16x32_bf16 v[114:117], v[198:201], v[206:209], 0
	v_mfma_f32_16x16x32_bf16 v[102:105], v[190:193], v[214:217], 0
	v_mfma_f32_16x16x32_bf16 v[98:101], v[198:201], v[214:217], 0
	v_mfma_f32_16x16x32_bf16 v[86:89], v[190:193], v[222:225], 0
	v_mfma_f32_16x16x32_bf16 v[82:85], v[198:201], v[222:225], 0
	v_mfma_f32_16x16x32_bf16 v[70:73], v[190:193], v[230:233], 0
	v_mfma_f32_16x16x32_bf16 v[66:69], v[198:201], v[230:233], 0
	v_mfma_f32_16x16x32_bf16 v[118:121], v[194:197], v[210:213], v[118:121]
	v_mfma_f32_16x16x32_bf16 v[114:117], v[202:205], v[210:213], v[114:117]
	v_mfma_f32_16x16x32_bf16 v[102:105], v[194:197], v[218:221], v[102:105]
	v_mfma_f32_16x16x32_bf16 v[98:101], v[202:205], v[218:221], v[98:101]
	v_mfma_f32_16x16x32_bf16 v[86:89], v[194:197], v[226:229], v[86:89]
	v_mfma_f32_16x16x32_bf16 v[82:85], v[202:205], v[226:229], v[82:85]
	v_mfma_f32_16x16x32_bf16 v[70:73], v[194:197], v[234:237], v[70:73]
	v_mfma_f32_16x16x32_bf16 v[66:69], v[202:205], v[234:237], v[66:69]
	s_setprio 0
	s_barrier
	s_add_i32 s33, s63, s35
	v_lshl_add_u64 v[162:163], s[14:15], 0, v[132:133]
	s_mov_b32 m0, s33
	ds_read_b128 v[206:209], v172 offset:16384
	ds_read_b128 v[210:213], v172 offset:17408
	ds_read_b128 v[214:217], v172 offset:18432
	ds_read_b128 v[218:221], v172 offset:19456
	ds_read_b128 v[222:225], v172 offset:20480
	ds_read_b128 v[226:229], v172 offset:21504
	ds_read_b128 v[230:233], v172 offset:22528
	ds_read_b128 v[234:237], v172 offset:23552
	global_load_lds_dwordx4 v[162:163], off
	s_add_i32 m0, s33, 0x2000
	s_add_u32 s54, s14, 0x40000
	v_lshl_add_u64 v[178:179], s[14:15], 0, v[136:137]
	s_addc_u32 s55, s15, 0
	s_add_i32 s33, s64, s35
	global_load_lds_dwordx4 v[178:179], off
	v_lshl_add_u64 v[238:239], s[54:55], 0, v[132:133]
	s_mov_b32 m0, s33
	v_lshl_add_u64 v[240:241], s[42:43], 0, v[134:135]
	global_load_lds_dwordx4 v[238:239], off
	v_lshl_add_u64 v[238:239], s[54:55], 0, v[136:137]
	s_add_i32 m0, s33, 0x2000
	s_nop 0
	global_load_lds_dwordx4 v[238:239], off
	v_lshl_add_u64 v[238:239], s[42:43], 0, v[130:131]
	s_mov_b32 m0, s48
	s_nop 0
	global_load_lds_dwordx4 v[238:239], off
	s_mov_b32 m0, s49
	s_nop 0
	global_load_lds_dwordx4 v[240:241], off
	s_waitcnt vmcnt(8)
	s_waitcnt lgkmcnt(0)
	s_barrier
	s_setprio 1
	s_waitcnt lgkmcnt(0)
	v_mfma_f32_16x16x32_bf16 v[62:65], v[158:161], v[206:209], 0
	v_mfma_f32_16x16x32_bf16 v[58:61], v[182:185], v[206:209], 0
	v_mfma_f32_16x16x32_bf16 v[46:49], v[158:161], v[214:217], 0
	v_mfma_f32_16x16x32_bf16 v[42:45], v[182:185], v[214:217], 0
	v_mfma_f32_16x16x32_bf16 v[30:33], v[158:161], v[222:225], 0
	v_mfma_f32_16x16x32_bf16 v[26:29], v[182:185], v[222:225], 0
	v_mfma_f32_16x16x32_bf16 v[14:17], v[158:161], v[230:233], 0
	v_mfma_f32_16x16x32_bf16 v[10:13], v[182:185], v[230:233], 0
	v_mfma_f32_16x16x32_bf16 v[62:65], v[174:177], v[210:213], v[62:65]
	v_mfma_f32_16x16x32_bf16 v[58:61], v[186:189], v[210:213], v[58:61]
	v_mfma_f32_16x16x32_bf16 v[46:49], v[174:177], v[218:221], v[46:49]
	v_mfma_f32_16x16x32_bf16 v[42:45], v[186:189], v[218:221], v[42:45]
	v_mfma_f32_16x16x32_bf16 v[30:33], v[174:177], v[226:229], v[30:33]
	v_mfma_f32_16x16x32_bf16 v[26:29], v[186:189], v[226:229], v[26:29]
	v_mfma_f32_16x16x32_bf16 v[14:17], v[174:177], v[234:237], v[14:17]
	v_mfma_f32_16x16x32_bf16 v[10:13], v[186:189], v[234:237], v[10:13]
	s_setprio 0
	s_setprio 1
	v_mfma_f32_16x16x32_bf16 v[54:57], v[190:193], v[206:209], 0
	v_mfma_f32_16x16x32_bf16 v[50:53], v[198:201], v[206:209], 0
	v_mfma_f32_16x16x32_bf16 v[38:41], v[190:193], v[214:217], 0
	v_mfma_f32_16x16x32_bf16 v[34:37], v[198:201], v[214:217], 0
	v_mfma_f32_16x16x32_bf16 v[22:25], v[190:193], v[222:225], 0
	v_mfma_f32_16x16x32_bf16 v[18:21], v[198:201], v[222:225], 0
	v_mfma_f32_16x16x32_bf16 v[6:9], v[190:193], v[230:233], 0
	v_mfma_f32_16x16x32_bf16 v[2:5], v[198:201], v[230:233], 0
	v_mfma_f32_16x16x32_bf16 v[54:57], v[194:197], v[210:213], v[54:57]
	v_mfma_f32_16x16x32_bf16 v[50:53], v[202:205], v[210:213], v[50:53]
	v_mfma_f32_16x16x32_bf16 v[38:41], v[194:197], v[218:221], v[38:41]
	v_mfma_f32_16x16x32_bf16 v[34:37], v[202:205], v[218:221], v[34:37]
	v_mfma_f32_16x16x32_bf16 v[22:25], v[194:197], v[226:229], v[22:25]
	v_mfma_f32_16x16x32_bf16 v[18:21], v[202:205], v[226:229], v[18:21]
	v_mfma_f32_16x16x32_bf16 v[6:9], v[194:197], v[234:237], v[6:9]
	v_mfma_f32_16x16x32_bf16 v[2:5], v[202:205], v[234:237], v[2:5]
	s_setprio 0
	s_barrier
	s_add_i32 s33, 0, 0x18000
	v_add_u32_e32 v138, s33, v165
	s_add_i32 s51, 0, 0x1c000
	ds_read_b128 v[158:161], v138
	ds_read_b128 v[174:177], v138 offset:1024
	ds_read_b128 v[182:185], v138 offset:2048
	ds_read_b128 v[186:189], v138 offset:3072
	v_add_u32_e32 v138, s51, v165
	ds_read_b128 v[190:193], v138
	ds_read_b128 v[194:197], v138 offset:1024
	ds_read_b128 v[198:201], v138 offset:2048
	ds_read_b128 v[202:205], v138 offset:3072
	s_add_u32 s42, s42, 0x40000
	s_addc_u32 s43, s43, 0
	s_mov_b32 m0, s52
	v_lshl_add_u64 v[242:243], s[42:43], 0, v[130:131]
	ds_read_b128 v[206:209], v172 offset:32768
	ds_read_b128 v[210:213], v172 offset:33792
	ds_read_b128 v[214:217], v172 offset:34816
	ds_read_b128 v[218:221], v172 offset:35840
	ds_read_b128 v[222:225], v172 offset:36864
	ds_read_b128 v[226:229], v172 offset:37888
	ds_read_b128 v[230:233], v172 offset:38912
	ds_read_b128 v[234:237], v172 offset:39936
	global_load_lds_dwordx4 v[242:243], off
	v_lshl_add_u64 v[242:243], s[42:43], 0, v[134:135]
	s_mov_b32 m0, s53
	s_nop 0
	global_load_lds_dwordx4 v[242:243], off
	s_waitcnt vmcnt(8)
	s_waitcnt lgkmcnt(0)
	s_barrier
	s_setprio 1
	s_waitcnt lgkmcnt(0)
	v_mfma_f32_16x16x32_bf16 v[126:129], v[158:161], v[206:209], v[126:129]
	v_mfma_f32_16x16x32_bf16 v[122:125], v[182:185], v[206:209], v[122:125]
	v_mfma_f32_16x16x32_bf16 v[110:113], v[158:161], v[214:217], v[110:113]
	v_mfma_f32_16x16x32_bf16 v[106:109], v[182:185], v[214:217], v[106:109]
	v_mfma_f32_16x16x32_bf16 v[94:97], v[158:161], v[222:225], v[94:97]
	v_mfma_f32_16x16x32_bf16 v[90:93], v[182:185], v[222:225], v[90:93]
	v_mfma_f32_16x16x32_bf16 v[78:81], v[158:161], v[230:233], v[78:81]
	v_mfma_f32_16x16x32_bf16 v[74:77], v[182:185], v[230:233], v[74:77]
	v_mfma_f32_16x16x32_bf16 v[126:129], v[174:177], v[210:213], v[126:129]
	v_mfma_f32_16x16x32_bf16 v[122:125], v[186:189], v[210:213], v[122:125]
	v_mfma_f32_16x16x32_bf16 v[110:113], v[174:177], v[218:221], v[110:113]
	v_mfma_f32_16x16x32_bf16 v[106:109], v[186:189], v[218:221], v[106:109]
	v_mfma_f32_16x16x32_bf16 v[94:97], v[174:177], v[226:229], v[94:97]
	v_mfma_f32_16x16x32_bf16 v[90:93], v[186:189], v[226:229], v[90:93]
	v_mfma_f32_16x16x32_bf16 v[78:81], v[174:177], v[234:237], v[78:81]
	v_mfma_f32_16x16x32_bf16 v[74:77], v[186:189], v[234:237], v[74:77]
	s_setprio 0
	s_setprio 1
	v_mfma_f32_16x16x32_bf16 v[118:121], v[190:193], v[206:209], v[118:121]
	v_mfma_f32_16x16x32_bf16 v[114:117], v[198:201], v[206:209], v[114:117]
	v_mfma_f32_16x16x32_bf16 v[102:105], v[190:193], v[214:217], v[102:105]
	v_mfma_f32_16x16x32_bf16 v[98:101], v[198:201], v[214:217], v[98:101]
	v_mfma_f32_16x16x32_bf16 v[86:89], v[190:193], v[222:225], v[86:89]
	v_mfma_f32_16x16x32_bf16 v[82:85], v[198:201], v[222:225], v[82:85]
	v_mfma_f32_16x16x32_bf16 v[70:73], v[190:193], v[230:233], v[70:73]
	v_mfma_f32_16x16x32_bf16 v[66:69], v[198:201], v[230:233], v[66:69]
	v_mfma_f32_16x16x32_bf16 v[118:121], v[194:197], v[210:213], v[118:121]
	v_mfma_f32_16x16x32_bf16 v[114:117], v[202:205], v[210:213], v[114:117]
	v_mfma_f32_16x16x32_bf16 v[102:105], v[194:197], v[218:221], v[102:105]
	v_mfma_f32_16x16x32_bf16 v[98:101], v[202:205], v[218:221], v[98:101]
	v_mfma_f32_16x16x32_bf16 v[86:89], v[194:197], v[226:229], v[86:89]
	v_mfma_f32_16x16x32_bf16 v[82:85], v[202:205], v[226:229], v[82:85]
	v_mfma_f32_16x16x32_bf16 v[70:73], v[194:197], v[234:237], v[70:73]
	v_mfma_f32_16x16x32_bf16 v[66:69], v[202:205], v[234:237], v[66:69]
	s_setprio 0
	s_barrier
	s_add_i32 s33, s33, s35
	v_lshl_add_u64 v[162:163], v[162:163], 0, s[20:21]
	s_mov_b32 m0, s33
	ds_read_b128 v[206:209], v172 offset:49152
	ds_read_b128 v[210:213], v172 offset:50176
	ds_read_b128 v[214:217], v172 offset:51200
	ds_read_b128 v[218:221], v172 offset:52224
	ds_read_b128 v[222:225], v172 offset:53248
	ds_read_b128 v[226:229], v172 offset:54272
	ds_read_b128 v[230:233], v172 offset:55296
	ds_read_b128 v[234:237], v172 offset:56320
	global_load_lds_dwordx4 v[162:163], off
	s_add_i32 m0, s33, 0x2000
	s_add_u32 s14, s14, 0x40080
	v_lshl_add_u64 v[162:163], v[178:179], 0, s[20:21]
	s_addc_u32 s15, s15, 0
	s_add_i32 s33, s51, s35
	global_load_lds_dwordx4 v[162:163], off
	v_lshl_add_u64 v[162:163], s[14:15], 0, v[132:133]
	s_mov_b32 m0, s33
	s_nop 0
	global_load_lds_dwordx4 v[162:163], off
	v_lshl_add_u64 v[162:163], s[14:15], 0, v[136:137]
	s_add_i32 m0, s33, 0x2000
	s_nop 0
	global_load_lds_dwordx4 v[162:163], off
	v_lshl_add_u64 v[162:163], v[238:239], 0, s[20:21]
	s_mov_b32 m0, s58
	s_nop 0
	global_load_lds_dwordx4 v[162:163], off
	v_lshl_add_u64 v[162:163], v[240:241], 0, s[20:21]
	s_mov_b32 m0, s59
	s_nop 0
	global_load_lds_dwordx4 v[162:163], off
	s_waitcnt vmcnt(8)
	s_waitcnt lgkmcnt(0)
	s_barrier
	s_setprio 1
	s_waitcnt lgkmcnt(0)
	v_mfma_f32_16x16x32_bf16 v[62:65], v[158:161], v[206:209], v[62:65]
	v_mfma_f32_16x16x32_bf16 v[58:61], v[182:185], v[206:209], v[58:61]
	v_mfma_f32_16x16x32_bf16 v[46:49], v[158:161], v[214:217], v[46:49]
	v_mfma_f32_16x16x32_bf16 v[42:45], v[182:185], v[214:217], v[42:45]
	v_mfma_f32_16x16x32_bf16 v[30:33], v[158:161], v[222:225], v[30:33]
	v_mfma_f32_16x16x32_bf16 v[26:29], v[182:185], v[222:225], v[26:29]
	v_mfma_f32_16x16x32_bf16 v[14:17], v[158:161], v[230:233], v[14:17]
	v_mfma_f32_16x16x32_bf16 v[10:13], v[182:185], v[230:233], v[10:13]
	v_mfma_f32_16x16x32_bf16 v[62:65], v[174:177], v[210:213], v[62:65]
	v_mfma_f32_16x16x32_bf16 v[58:61], v[186:189], v[210:213], v[58:61]
	v_mfma_f32_16x16x32_bf16 v[46:49], v[174:177], v[218:221], v[46:49]
	v_mfma_f32_16x16x32_bf16 v[42:45], v[186:189], v[218:221], v[42:45]
	v_mfma_f32_16x16x32_bf16 v[30:33], v[174:177], v[226:229], v[30:33]
	v_mfma_f32_16x16x32_bf16 v[26:29], v[186:189], v[226:229], v[26:29]
	v_mfma_f32_16x16x32_bf16 v[14:17], v[174:177], v[234:237], v[14:17]
	v_mfma_f32_16x16x32_bf16 v[10:13], v[186:189], v[234:237], v[10:13]
	s_setprio 0
	s_setprio 1
	v_mfma_f32_16x16x32_bf16 v[54:57], v[190:193], v[206:209], v[54:57]
	v_mfma_f32_16x16x32_bf16 v[50:53], v[198:201], v[206:209], v[50:53]
	v_mfma_f32_16x16x32_bf16 v[38:41], v[190:193], v[214:217], v[38:41]
	v_mfma_f32_16x16x32_bf16 v[34:37], v[198:201], v[214:217], v[34:37]
	v_mfma_f32_16x16x32_bf16 v[22:25], v[190:193], v[222:225], v[22:25]
	v_mfma_f32_16x16x32_bf16 v[18:21], v[198:201], v[222:225], v[18:21]
	v_mfma_f32_16x16x32_bf16 v[6:9], v[190:193], v[230:233], v[6:9]
	v_mfma_f32_16x16x32_bf16 v[2:5], v[198:201], v[230:233], v[2:5]
	v_mfma_f32_16x16x32_bf16 v[54:57], v[194:197], v[210:213], v[54:57]
	v_mfma_f32_16x16x32_bf16 v[50:53], v[202:205], v[210:213], v[50:53]
	v_mfma_f32_16x16x32_bf16 v[38:41], v[194:197], v[218:221], v[38:41]
	v_mfma_f32_16x16x32_bf16 v[34:37], v[202:205], v[218:221], v[34:37]
	v_mfma_f32_16x16x32_bf16 v[22:25], v[194:197], v[226:229], v[22:25]
	v_mfma_f32_16x16x32_bf16 v[18:21], v[202:205], v[226:229], v[18:21]
	v_mfma_f32_16x16x32_bf16 v[6:9], v[194:197], v[234:237], v[6:9]
	v_mfma_f32_16x16x32_bf16 v[2:5], v[202:205], v[234:237], v[2:5]
	s_setprio 0
	s_barrier
	s_add_i32 s86, s86, 2
	s_add_u32 s40, s40, 0x100
	s_addc_u32 s41, s41, 0
	s_add_u32 s74, s74, 0x100
	s_addc_u32 s75, s75, 0

.LBB0_749:
	ds_read_b128 v[86:89], v82
	ds_read_b128 v[90:93], v82 offset:1024
	ds_read_b128 v[94:97], v82 offset:2048
	ds_read_b128 v[98:101], v82 offset:3072
	v_readlane_b32 s52, v244, 8
	s_add_i32 s31, s31, 1
	v_readlane_b32 s54, v244, 10
	s_mul_i32 s2, s31, s54
	s_add_i32 s2, s2, s96
	s_cmpk_lt_i32 s2, 0x80
	s_cselect_b64 s[24:25], -1, 0
	s_cmpk_gt_i32 s2, 0x7f
	v_readlane_b32 s53, v244, 9
	v_readlane_b32 s55, v244, 11
	s_cbranch_scc1 .LBB0_751
	s_ashr_i32 s3, s2, 31
	s_lshr_b32 s3, s3, 30
	s_add_i32 s3, s2, s3
	s_ashr_i32 s16, s3, 2
	s_mov_b32 s48, s2

.LBB0_753:
	s_ashr_i32 s17, s16, 31
	s_lshl_b64 s[20:21], s[16:17], 19
	s_add_u32 s20, s8, s20
	s_addc_u32 s21, s9, s21
	s_and_b64 s[24:25], s[24:25], exec
	s_cselect_b32 s17, s21, s15
	s_cselect_b32 s52, s20, s14
	s_add_u32 s22, s22, 0x48080
	s_addc_u32 s23, s23, 0
	s_add_u32 s53, s14, 0x100

	s_addc_u32 s56, s15, 0
	s_mov_b32 s57, -2


	s_add_u32 s14, s22, 0xfffb8080
	s_addc_u32 s15, s23, -1
	s_cmp_eq_u32 s57, 12
	s_cselect_b32 s25, s19, s15
	s_cselect_b32 s24, s18, s14
	s_cselect_b32 s15, s17, s56
	s_cselect_b32 s14, s52, s53
	s_mov_b32 m0, s38
	v_lshl_add_u64 v[134:135], s[22:23], 0, v[76:77]
	ds_read_b128 v[102:105], v83
	ds_read_b128 v[106:109], v83 offset:1024
	ds_read_b128 v[110:113], v83 offset:2048
	ds_read_b128 v[114:117], v83 offset:3072
	ds_read_b128 v[118:121], v83 offset:4096
	ds_read_b128 v[122:125], v83 offset:5120
	ds_read_b128 v[126:129], v83 offset:6144
	ds_read_b128 v[130:133], v83 offset:7168
	global_load_lds_dwordx4 v[134:135], off
	v_lshl_add_u64 v[134:135], s[22:23], 0, v[78:79]
	s_mov_b32 m0, s39
	s_nop 0
	global_load_lds_dwordx4 v[134:135], off
	s_waitcnt vmcnt(8)
	s_waitcnt lgkmcnt(0)
	s_barrier
	s_setprio 1
	s_waitcnt lgkmcnt(0)
	v_mfma_f32_16x16x32_bf16 v[62:65], v[86:89], v[102:105], 0
	v_mfma_f32_16x16x32_bf16 v[58:61], v[94:97], v[102:105], 0
	v_mfma_f32_16x16x32_bf16 v[54:57], v[86:89], v[110:113], 0
	v_mfma_f32_16x16x32_bf16 v[50:53], v[94:97], v[110:113], 0
	v_mfma_f32_16x16x32_bf16 v[46:49], v[86:89], v[118:121], 0
	v_mfma_f32_16x16x32_bf16 v[42:45], v[94:97], v[118:121], 0
	v_mfma_f32_16x16x32_bf16 v[38:41], v[86:89], v[126:129], 0
	v_mfma_f32_16x16x32_bf16 v[34:37], v[94:97], v[126:129], 0
	v_mfma_f32_16x16x32_bf16 v[62:65], v[90:93], v[106:109], v[62:65]
	v_mfma_f32_16x16x32_bf16 v[58:61], v[98:101], v[106:109], v[58:61]
	v_mfma_f32_16x16x32_bf16 v[54:57], v[90:93], v[114:117], v[54:57]
	v_mfma_f32_16x16x32_bf16 v[50:53], v[98:101], v[114:117], v[50:53]
	v_mfma_f32_16x16x32_bf16 v[46:49], v[90:93], v[122:125], v[46:49]
	v_mfma_f32_16x16x32_bf16 v[42:45], v[98:101], v[122:125], v[42:45]
	v_mfma_f32_16x16x32_bf16 v[38:41], v[90:93], v[130:133], v[38:41]
	v_mfma_f32_16x16x32_bf16 v[34:37], v[98:101], v[130:133], v[34:37]
	s_setprio 0
	s_setprio 1
	s_setprio 0
	s_barrier
	s_mov_b32 m0, s40
	v_lshl_add_u64 v[134:135], s[14:15], 0, v[70:71]
	s_add_u32 s54, s14, 0x40000
	ds_read_b128 v[102:105], v83 offset:16384
	ds_read_b128 v[106:109], v83 offset:17408
	ds_read_b128 v[110:113], v83 offset:18432
	ds_read_b128 v[114:117], v83 offset:19456
	ds_read_b128 v[118:121], v83 offset:20480
	ds_read_b128 v[122:125], v83 offset:21504
	ds_read_b128 v[126:129], v83 offset:22528
	ds_read_b128 v[130:133], v83 offset:23552
	global_load_lds_dwordx4 v[134:135], off
	v_lshl_add_u64 v[136:137], s[14:15], 0, v[66:67]
	s_mov_b32 m0, s41
	s_addc_u32 s55, s15, 0
	global_load_lds_dwordx4 v[136:137], off
	v_lshl_add_u64 v[138:139], s[54:55], 0, v[70:71]
	s_mov_b32 m0, s26
	v_lshl_add_u64 v[140:141], s[24:25], 0, v[68:69]
	global_load_lds_dwordx4 v[138:139], off
	v_lshl_add_u64 v[138:139], s[54:55], 0, v[66:67]
	s_mov_b32 m0, s27
	s_nop 0
	global_load_lds_dwordx4 v[138:139], off
	v_lshl_add_u64 v[138:139], s[24:25], 0, v[72:73]
	s_mov_b32 m0, s7
	s_nop 0
	global_load_lds_dwordx4 v[138:139], off
	s_mov_b32 m0, s28
	s_nop 0
	global_load_lds_dwordx4 v[140:141], off
	s_waitcnt vmcnt(8)
	s_waitcnt lgkmcnt(0)
	s_barrier
	s_setprio 1
	s_waitcnt lgkmcnt(0)
	v_mfma_f32_16x16x32_bf16 v[30:33], v[86:89], v[102:105], 0
	v_mfma_f32_16x16x32_bf16 v[26:29], v[94:97], v[102:105], 0
	v_mfma_f32_16x16x32_bf16 v[22:25], v[86:89], v[110:113], 0
	v_mfma_f32_16x16x32_bf16 v[18:21], v[94:97], v[110:113], 0
	v_mfma_f32_16x16x32_bf16 v[14:17], v[86:89], v[118:121], 0
	v_mfma_f32_16x16x32_bf16 v[10:13], v[94:97], v[118:121], 0
	v_mfma_f32_16x16x32_bf16 v[6:9], v[86:89], v[126:129], 0
	v_mfma_f32_16x16x32_bf16 v[2:5], v[94:97], v[126:129], 0
	v_mfma_f32_16x16x32_bf16 v[30:33], v[90:93], v[106:109], v[30:33]
	v_mfma_f32_16x16x32_bf16 v[26:29], v[98:101], v[106:109], v[26:29]
	v_mfma_f32_16x16x32_bf16 v[22:25], v[90:93], v[114:117], v[22:25]
	v_mfma_f32_16x16x32_bf16 v[18:21], v[98:101], v[114:117], v[18:21]
	v_mfma_f32_16x16x32_bf16 v[14:17], v[90:93], v[122:125], v[14:17]
	v_mfma_f32_16x16x32_bf16 v[10:13], v[98:101], v[122:125], v[10:13]
	v_mfma_f32_16x16x32_bf16 v[6:9], v[90:93], v[130:133], v[6:9]
	v_mfma_f32_16x16x32_bf16 v[2:5], v[98:101], v[130:133], v[2:5]
	s_setprio 0
	s_setprio 1
	s_setprio 0
	s_barrier
	ds_read_b128 v[86:89], v84
	ds_read_b128 v[90:93], v84 offset:1024
	ds_read_b128 v[94:97], v84 offset:2048
	ds_read_b128 v[98:101], v84 offset:3072
	s_add_u32 s24, s24, 0x48000
	s_addc_u32 s25, s25, 0
	s_mov_b32 m0, s29
	v_lshl_add_u64 v[142:143], s[24:25], 0, v[72:73]
	ds_read_b128 v[102:105], v83 offset:32768
	ds_read_b128 v[106:109], v83 offset:33792
	ds_read_b128 v[110:113], v83 offset:34816
	ds_read_b128 v[114:117], v83 offset:35840
	ds_read_b128 v[118:121], v83 offset:36864
	ds_read_b128 v[122:125], v83 offset:37888
	ds_read_b128 v[126:129], v83 offset:38912
	ds_read_b128 v[130:133], v83 offset:39936
	global_load_lds_dwordx4 v[142:143], off
	v_lshl_add_u64 v[142:143], s[24:25], 0, v[68:69]
	s_mov_b32 m0, s30
	s_nop 0
	global_load_lds_dwordx4 v[142:143], off
	s_waitcnt vmcnt(8)
	s_waitcnt lgkmcnt(0)
	s_barrier
	s_setprio 1
	s_waitcnt lgkmcnt(0)
	v_mfma_f32_16x16x32_bf16 v[62:65], v[86:89], v[102:105], v[62:65]
	v_mfma_f32_16x16x32_bf16 v[58:61], v[94:97], v[102:105], v[58:61]
	v_mfma_f32_16x16x32_bf16 v[54:57], v[86:89], v[110:113], v[54:57]
	v_mfma_f32_16x16x32_bf16 v[50:53], v[94:97], v[110:113], v[50:53]
	v_mfma_f32_16x16x32_bf16 v[46:49], v[86:89], v[118:121], v[46:49]
	v_mfma_f32_16x16x32_bf16 v[42:45], v[94:97], v[118:121], v[42:45]
	v_mfma_f32_16x16x32_bf16 v[38:41], v[86:89], v[126:129], v[38:41]
	v_mfma_f32_16x16x32_bf16 v[34:37], v[94:97], v[126:129], v[34:37]
	v_mfma_f32_16x16x32_bf16 v[62:65], v[90:93], v[106:109], v[62:65]
	v_mfma_f32_16x16x32_bf16 v[58:61], v[98:101], v[106:109], v[58:61]
	v_mfma_f32_16x16x32_bf16 v[54:57], v[90:93], v[114:117], v[54:57]
	v_mfma_f32_16x16x32_bf16 v[50:53], v[98:101], v[114:117], v[50:53]
	v_mfma_f32_16x16x32_bf16 v[46:49], v[90:93], v[122:125], v[46:49]
	v_mfma_f32_16x16x32_bf16 v[42:45], v[98:101], v[122:125], v[42:45]
	v_mfma_f32_16x16x32_bf16 v[38:41], v[90:93], v[130:133], v[38:41]
	v_mfma_f32_16x16x32_bf16 v[34:37], v[98:101], v[130:133], v[34:37]
	s_setprio 0
	s_setprio 1
	s_setprio 0
	s_barrier
	s_mov_b32 m0, s42
	v_lshl_add_u64 v[134:135], v[134:135], 0, s[10:11]
	s_add_u32 s14, s14, 0x40080
	ds_read_b128 v[102:105], v83 offset:49152
	ds_read_b128 v[106:109], v83 offset:50176
	ds_read_b128 v[110:113], v83 offset:51200
	ds_read_b128 v[114:117], v83 offset:52224
	ds_read_b128 v[118:121], v83 offset:53248
	ds_read_b128 v[122:125], v83 offset:54272
	ds_read_b128 v[126:129], v83 offset:55296
	ds_read_b128 v[130:133], v83 offset:56320
	global_load_lds_dwordx4 v[134:135], off
	v_lshl_add_u64 v[134:135], v[136:137], 0, s[10:11]
	s_mov_b32 m0, s43
	s_addc_u32 s15, s15, 0
	global_load_lds_dwordx4 v[134:135], off
	v_lshl_add_u64 v[134:135], s[14:15], 0, v[70:71]
	s_mov_b32 m0, s36
	s_nop 0
	global_load_lds_dwordx4 v[134:135], off
	v_lshl_add_u64 v[134:135], s[14:15], 0, v[66:67]
	s_mov_b32 m0, s37
	s_nop 0
	global_load_lds_dwordx4 v[134:135], off
	v_lshl_add_u64 v[134:135], v[138:139], 0, s[10:11]
	s_mov_b32 m0, s34
	s_nop 0
	global_load_lds_dwordx4 v[134:135], off
	v_lshl_add_u64 v[134:135], v[140:141], 0, s[10:11]
	s_mov_b32 m0, s35
	s_nop 0
	global_load_lds_dwordx4 v[134:135], off
	s_waitcnt vmcnt(8)
	s_waitcnt lgkmcnt(0)
	s_barrier
	s_setprio 1
	s_waitcnt lgkmcnt(0)
	v_mfma_f32_16x16x32_bf16 v[30:33], v[86:89], v[102:105], v[30:33]
	v_mfma_f32_16x16x32_bf16 v[26:29], v[94:97], v[102:105], v[26:29]
	v_mfma_f32_16x16x32_bf16 v[22:25], v[86:89], v[110:113], v[22:25]
	v_mfma_f32_16x16x32_bf16 v[18:21], v[94:97], v[110:113], v[18:21]
	v_mfma_f32_16x16x32_bf16 v[14:17], v[86:89], v[118:121], v[14:17]
	v_mfma_f32_16x16x32_bf16 v[10:13], v[94:97], v[118:121], v[10:13]
	v_mfma_f32_16x16x32_bf16 v[6:9], v[86:89], v[126:129], v[6:9]
	v_mfma_f32_16x16x32_bf16 v[2:5], v[94:97], v[126:129], v[2:5]
	v_mfma_f32_16x16x32_bf16 v[30:33], v[90:93], v[106:109], v[30:33]
	v_mfma_f32_16x16x32_bf16 v[26:29], v[98:101], v[106:109], v[26:29]
	v_mfma_f32_16x16x32_bf16 v[22:25], v[90:93], v[114:117], v[22:25]
	v_mfma_f32_16x16x32_bf16 v[18:21], v[98:101], v[114:117], v[18:21]
	v_mfma_f32_16x16x32_bf16 v[14:17], v[90:93], v[122:125], v[14:17]
	v_mfma_f32_16x16x32_bf16 v[10:13], v[98:101], v[122:125], v[10:13]
	v_mfma_f32_16x16x32_bf16 v[6:9], v[90:93], v[130:133], v[6:9]
	v_mfma_f32_16x16x32_bf16 v[2:5], v[98:101], v[130:133], v[2:5]
	s_setprio 0
	s_setprio 1
	s_setprio 0
	s_barrier
	s_add_i32 s57, s57, 2
	s_add_u32 s22, s22, 0x100
	s_addc_u32 s23, s23, 0
	s_add_u32 s53, s53, 0x100
	s_addc_u32 s56, s56, 0

.LBB0_855:
	ds_read_b128 v[152:155], v146
	ds_read_b128 v[156:159], v146 offset:1024
	ds_read_b128 v[160:163], v146 offset:2048
	ds_read_b128 v[164:167], v146 offset:3072
	ds_read_b128 v[168:171], v147
	ds_read_b128 v[172:175], v147 offset:1024
	ds_read_b128 v[176:179], v147 offset:2048
	ds_read_b128 v[182:185], v147 offset:3072
	v_readlane_b32 s12, v244, 8
	s_add_i32 s26, s26, 1
	v_readlane_b32 s14, v244, 10
	s_mul_i32 s2, s26, s14
	s_add_i32 s2, s2, s96
	v_readlane_b32 s13, v244, 9
	s_cmpk_lt_i32 s2, 0x200
	s_cselect_b64 s[12:13], -1, 0
	s_cmpk_gt_i32 s2, 0x1ff
	v_readlane_b32 s15, v244, 11
	s_cbranch_scc1 .LBB0_857
	s_ashr_i32 s3, s2, 31
	s_lshr_b32 s3, s3, 28
	s_add_i32 s3, s2, s3
	s_ashr_i32 s14, s3, 4
	s_and_b32 s3, s3, 0xfff0
	s_sub_i32 s2, s2, s3
	s_lshl_b32 s3, s14, 2
	s_bfe_i32 s14, s2, 0x80000
	s_bfe_u32 s14, s14, 0x2000d
	s_add_i32 s14, s2, s14
	s_bfe_i32 s15, s14, 0x80000
	s_and_b32 s14, s14, 0xfc
	s_sub_i32 s2, s2, s14
	s_sext_i32_i16 s15, s15
	s_sext_i32_i8 s2, s2
	s_add_i32 s41, s3, s2
	s_ashr_i32 s2, s15, 2
	s_add_i32 s42, s3, s2

.LBB0_861:
	s_add_u32 s16, s16, 0x48080
	s_addc_u32 s17, s17, 0
	s_add_u32 s49, s18, 0x100

	s_addc_u32 s52, s19, 0
	s_mov_b32 s53, -2


	s_add_u32 s18, s16, 0xfffb8080
	s_addc_u32 s19, s17, -1
	s_cmp_eq_u32 s53, 14
	s_cselect_b32 s21, s13, s19
	s_cselect_b32 s20, s12, s18
	s_cselect_b32 s19, s15, s52
	s_cselect_b32 s18, s14, s49
	s_mov_b32 m0, s29
	v_lshl_add_u64 v[218:219], s[16:17], 0, v[140:141]
	ds_read_b128 v[186:189], v148
	ds_read_b128 v[190:193], v148 offset:1024
	ds_read_b128 v[194:197], v148 offset:2048
	ds_read_b128 v[198:201], v148 offset:3072
	ds_read_b128 v[202:205], v148 offset:4096
	ds_read_b128 v[206:209], v148 offset:5120
	ds_read_b128 v[210:213], v148 offset:6144
	ds_read_b128 v[214:217], v148 offset:7168
	global_load_lds_dwordx4 v[218:219], off
	v_lshl_add_u64 v[218:219], s[16:17], 0, v[142:143]
	s_mov_b32 m0, s30
	s_nop 0
	global_load_lds_dwordx4 v[218:219], off
	s_waitcnt vmcnt(8)
	s_waitcnt lgkmcnt(0)
	s_barrier
	s_setprio 1
	s_waitcnt lgkmcnt(0)
	v_mfma_f32_16x16x32_bf16 v[126:129], v[152:155], v[186:189], 0
	v_mfma_f32_16x16x32_bf16 v[122:125], v[160:163], v[186:189], 0
	v_mfma_f32_16x16x32_bf16 v[110:113], v[152:155], v[194:197], 0
	v_mfma_f32_16x16x32_bf16 v[106:109], v[160:163], v[194:197], 0
	v_mfma_f32_16x16x32_bf16 v[94:97], v[152:155], v[202:205], 0
	v_mfma_f32_16x16x32_bf16 v[90:93], v[160:163], v[202:205], 0
	v_mfma_f32_16x16x32_bf16 v[78:81], v[152:155], v[210:213], 0
	v_mfma_f32_16x16x32_bf16 v[74:77], v[160:163], v[210:213], 0
	v_mfma_f32_16x16x32_bf16 v[126:129], v[156:159], v[190:193], v[126:129]
	v_mfma_f32_16x16x32_bf16 v[122:125], v[164:167], v[190:193], v[122:125]
	v_mfma_f32_16x16x32_bf16 v[110:113], v[156:159], v[198:201], v[110:113]
	v_mfma_f32_16x16x32_bf16 v[106:109], v[164:167], v[198:201], v[106:109]
	v_mfma_f32_16x16x32_bf16 v[94:97], v[156:159], v[206:209], v[94:97]
	v_mfma_f32_16x16x32_bf16 v[90:93], v[164:167], v[206:209], v[90:93]
	v_mfma_f32_16x16x32_bf16 v[78:81], v[156:159], v[214:217], v[78:81]
	v_mfma_f32_16x16x32_bf16 v[74:77], v[164:167], v[214:217], v[74:77]
	s_setprio 0
	s_setprio 1
	v_mfma_f32_16x16x32_bf16 v[118:121], v[168:171], v[186:189], 0
	v_mfma_f32_16x16x32_bf16 v[114:117], v[176:179], v[186:189], 0
	v_mfma_f32_16x16x32_bf16 v[102:105], v[168:171], v[194:197], 0
	v_mfma_f32_16x16x32_bf16 v[98:101], v[176:179], v[194:197], 0
	v_mfma_f32_16x16x32_bf16 v[86:89], v[168:171], v[202:205], 0
	v_mfma_f32_16x16x32_bf16 v[82:85], v[176:179], v[202:205], 0
	v_mfma_f32_16x16x32_bf16 v[70:73], v[168:171], v[210:213], 0
	v_mfma_f32_16x16x32_bf16 v[66:69], v[176:179], v[210:213], 0
	v_mfma_f32_16x16x32_bf16 v[118:121], v[172:175], v[190:193], v[118:121]
	v_mfma_f32_16x16x32_bf16 v[114:117], v[182:185], v[190:193], v[114:117]
	v_mfma_f32_16x16x32_bf16 v[102:105], v[172:175], v[198:201], v[102:105]
	v_mfma_f32_16x16x32_bf16 v[98:101], v[182:185], v[198:201], v[98:101]
	v_mfma_f32_16x16x32_bf16 v[86:89], v[172:175], v[206:209], v[86:89]
	v_mfma_f32_16x16x32_bf16 v[82:85], v[182:185], v[206:209], v[82:85]
	v_mfma_f32_16x16x32_bf16 v[70:73], v[172:175], v[214:217], v[70:73]
	v_mfma_f32_16x16x32_bf16 v[66:69], v[182:185], v[214:217], v[66:69]
	s_setprio 0
	s_barrier
	s_mov_b32 m0, s31
	v_lshl_add_u64 v[218:219], s[18:19], 0, v[134:135]
	s_add_u32 s54, s18, 0x48000
	ds_read_b128 v[186:189], v148 offset:16384
	ds_read_b128 v[190:193], v148 offset:17408
	ds_read_b128 v[194:197], v148 offset:18432
	ds_read_b128 v[198:201], v148 offset:19456
	ds_read_b128 v[202:205], v148 offset:20480
	ds_read_b128 v[206:209], v148 offset:21504
	ds_read_b128 v[210:213], v148 offset:22528
	ds_read_b128 v[214:217], v148 offset:23552
	global_load_lds_dwordx4 v[218:219], off
	v_lshl_add_u64 v[220:221], s[18:19], 0, v[130:131]
	s_mov_b32 m0, s34
	s_addc_u32 s55, s19, 0
	global_load_lds_dwordx4 v[220:221], off
	v_lshl_add_u64 v[222:223], s[54:55], 0, v[134:135]
	s_mov_b32 m0, s35
	v_lshl_add_u64 v[224:225], s[20:21], 0, v[132:133]
	global_load_lds_dwordx4 v[222:223], off
	v_lshl_add_u64 v[222:223], s[54:55], 0, v[130:131]
	s_mov_b32 m0, s36
	s_nop 0
	global_load_lds_dwordx4 v[222:223], off
	v_lshl_add_u64 v[222:223], s[20:21], 0, v[136:137]
	s_mov_b32 m0, s22
	s_nop 0
	global_load_lds_dwordx4 v[222:223], off
	s_mov_b32 m0, s23
	s_nop 0
	global_load_lds_dwordx4 v[224:225], off
	s_waitcnt vmcnt(8)
	s_waitcnt lgkmcnt(0)
	s_barrier
	s_setprio 1
	s_waitcnt lgkmcnt(0)
	v_mfma_f32_16x16x32_bf16 v[62:65], v[152:155], v[186:189], 0
	v_mfma_f32_16x16x32_bf16 v[58:61], v[160:163], v[186:189], 0
	v_mfma_f32_16x16x32_bf16 v[46:49], v[152:155], v[194:197], 0
	v_mfma_f32_16x16x32_bf16 v[42:45], v[160:163], v[194:197], 0
	v_mfma_f32_16x16x32_bf16 v[30:33], v[152:155], v[202:205], 0
	v_mfma_f32_16x16x32_bf16 v[26:29], v[160:163], v[202:205], 0
	v_mfma_f32_16x16x32_bf16 v[14:17], v[152:155], v[210:213], 0
	v_mfma_f32_16x16x32_bf16 v[10:13], v[160:163], v[210:213], 0
	v_mfma_f32_16x16x32_bf16 v[62:65], v[156:159], v[190:193], v[62:65]
	v_mfma_f32_16x16x32_bf16 v[58:61], v[164:167], v[190:193], v[58:61]
	v_mfma_f32_16x16x32_bf16 v[46:49], v[156:159], v[198:201], v[46:49]
	v_mfma_f32_16x16x32_bf16 v[42:45], v[164:167], v[198:201], v[42:45]
	v_mfma_f32_16x16x32_bf16 v[30:33], v[156:159], v[206:209], v[30:33]
	v_mfma_f32_16x16x32_bf16 v[26:29], v[164:167], v[206:209], v[26:29]
	v_mfma_f32_16x16x32_bf16 v[14:17], v[156:159], v[214:217], v[14:17]
	v_mfma_f32_16x16x32_bf16 v[10:13], v[164:167], v[214:217], v[10:13]
	s_setprio 0
	s_setprio 1
	v_mfma_f32_16x16x32_bf16 v[54:57], v[168:171], v[186:189], 0
	v_mfma_f32_16x16x32_bf16 v[50:53], v[176:179], v[186:189], 0
	v_mfma_f32_16x16x32_bf16 v[38:41], v[168:171], v[194:197], 0
	v_mfma_f32_16x16x32_bf16 v[34:37], v[176:179], v[194:197], 0
	v_mfma_f32_16x16x32_bf16 v[22:25], v[168:171], v[202:205], 0
	v_mfma_f32_16x16x32_bf16 v[18:21], v[176:179], v[202:205], 0
	v_mfma_f32_16x16x32_bf16 v[6:9], v[168:171], v[210:213], 0
	v_mfma_f32_16x16x32_bf16 v[2:5], v[176:179], v[210:213], 0
	v_mfma_f32_16x16x32_bf16 v[54:57], v[172:175], v[190:193], v[54:57]
	v_mfma_f32_16x16x32_bf16 v[50:53], v[182:185], v[190:193], v[50:53]
	v_mfma_f32_16x16x32_bf16 v[38:41], v[172:175], v[198:201], v[38:41]
	v_mfma_f32_16x16x32_bf16 v[34:37], v[182:185], v[198:201], v[34:37]
	v_mfma_f32_16x16x32_bf16 v[22:25], v[172:175], v[206:209], v[22:25]
	v_mfma_f32_16x16x32_bf16 v[18:21], v[182:185], v[206:209], v[18:21]
	v_mfma_f32_16x16x32_bf16 v[6:9], v[172:175], v[214:217], v[6:9]
	v_mfma_f32_16x16x32_bf16 v[2:5], v[182:185], v[214:217], v[2:5]
	s_setprio 0
	s_barrier
	ds_read_b128 v[152:155], v150
	ds_read_b128 v[156:159], v150 offset:1024
	ds_read_b128 v[160:163], v150 offset:2048
	ds_read_b128 v[164:167], v150 offset:3072
	ds_read_b128 v[168:171], v151
	ds_read_b128 v[172:175], v151 offset:1024
	ds_read_b128 v[176:179], v151 offset:2048
	ds_read_b128 v[182:185], v151 offset:3072
	s_add_u32 s20, s20, 0x48000
	s_addc_u32 s21, s21, 0
	s_mov_b32 m0, s24
	v_lshl_add_u64 v[226:227], s[20:21], 0, v[136:137]
	ds_read_b128 v[186:189], v148 offset:32768
	ds_read_b128 v[190:193], v148 offset:33792
	ds_read_b128 v[194:197], v148 offset:34816
	ds_read_b128 v[198:201], v148 offset:35840
	ds_read_b128 v[202:205], v148 offset:36864
	ds_read_b128 v[206:209], v148 offset:37888
	ds_read_b128 v[210:213], v148 offset:38912
	ds_read_b128 v[214:217], v148 offset:39936
	global_load_lds_dwordx4 v[226:227], off
	v_lshl_add_u64 v[226:227], s[20:21], 0, v[132:133]
	s_mov_b32 m0, s25
	s_nop 0
	global_load_lds_dwordx4 v[226:227], off
	s_waitcnt vmcnt(8)
	s_waitcnt lgkmcnt(0)
	s_barrier
	s_setprio 1
	s_waitcnt lgkmcnt(0)
	v_mfma_f32_16x16x32_bf16 v[126:129], v[152:155], v[186:189], v[126:129]
	v_mfma_f32_16x16x32_bf16 v[122:125], v[160:163], v[186:189], v[122:125]
	v_mfma_f32_16x16x32_bf16 v[110:113], v[152:155], v[194:197], v[110:113]
	v_mfma_f32_16x16x32_bf16 v[106:109], v[160:163], v[194:197], v[106:109]
	v_mfma_f32_16x16x32_bf16 v[94:97], v[152:155], v[202:205], v[94:97]
	v_mfma_f32_16x16x32_bf16 v[90:93], v[160:163], v[202:205], v[90:93]
	v_mfma_f32_16x16x32_bf16 v[78:81], v[152:155], v[210:213], v[78:81]
	v_mfma_f32_16x16x32_bf16 v[74:77], v[160:163], v[210:213], v[74:77]
	v_mfma_f32_16x16x32_bf16 v[126:129], v[156:159], v[190:193], v[126:129]
	v_mfma_f32_16x16x32_bf16 v[122:125], v[164:167], v[190:193], v[122:125]
	v_mfma_f32_16x16x32_bf16 v[110:113], v[156:159], v[198:201], v[110:113]
	v_mfma_f32_16x16x32_bf16 v[106:109], v[164:167], v[198:201], v[106:109]
	v_mfma_f32_16x16x32_bf16 v[94:97], v[156:159], v[206:209], v[94:97]
	v_mfma_f32_16x16x32_bf16 v[90:93], v[164:167], v[206:209], v[90:93]
	v_mfma_f32_16x16x32_bf16 v[78:81], v[156:159], v[214:217], v[78:81]
	v_mfma_f32_16x16x32_bf16 v[74:77], v[164:167], v[214:217], v[74:77]
	s_setprio 0
	s_setprio 1
	v_mfma_f32_16x16x32_bf16 v[118:121], v[168:171], v[186:189], v[118:121]
	v_mfma_f32_16x16x32_bf16 v[114:117], v[176:179], v[186:189], v[114:117]
	v_mfma_f32_16x16x32_bf16 v[102:105], v[168:171], v[194:197], v[102:105]
	v_mfma_f32_16x16x32_bf16 v[98:101], v[176:179], v[194:197], v[98:101]
	v_mfma_f32_16x16x32_bf16 v[86:89], v[168:171], v[202:205], v[86:89]
	v_mfma_f32_16x16x32_bf16 v[82:85], v[176:179], v[202:205], v[82:85]
	v_mfma_f32_16x16x32_bf16 v[70:73], v[168:171], v[210:213], v[70:73]
	v_mfma_f32_16x16x32_bf16 v[66:69], v[176:179], v[210:213], v[66:69]
	v_mfma_f32_16x16x32_bf16 v[118:121], v[172:175], v[190:193], v[118:121]
	v_mfma_f32_16x16x32_bf16 v[114:117], v[182:185], v[190:193], v[114:117]
	v_mfma_f32_16x16x32_bf16 v[102:105], v[172:175], v[198:201], v[102:105]
	v_mfma_f32_16x16x32_bf16 v[98:101], v[182:185], v[198:201], v[98:101]
	v_mfma_f32_16x16x32_bf16 v[86:89], v[172:175], v[206:209], v[86:89]
	v_mfma_f32_16x16x32_bf16 v[82:85], v[182:185], v[206:209], v[82:85]
	v_mfma_f32_16x16x32_bf16 v[70:73], v[172:175], v[214:217], v[70:73]
	v_mfma_f32_16x16x32_bf16 v[66:69], v[182:185], v[214:217], v[66:69]
	s_setprio 0
	s_barrier
	s_mov_b32 m0, s37
	v_lshl_add_u64 v[218:219], v[218:219], 0, s[8:9]
	s_add_u32 s18, s18, 0x48080
	ds_read_b128 v[186:189], v148 offset:49152
	ds_read_b128 v[190:193], v148 offset:50176
	ds_read_b128 v[194:197], v148 offset:51200
	ds_read_b128 v[198:201], v148 offset:52224
	ds_read_b128 v[202:205], v148 offset:53248
	ds_read_b128 v[206:209], v148 offset:54272
	ds_read_b128 v[210:213], v148 offset:55296
	ds_read_b128 v[214:217], v148 offset:56320
	global_load_lds_dwordx4 v[218:219], off
	v_lshl_add_u64 v[218:219], v[220:221], 0, s[8:9]
	s_mov_b32 m0, s38
	s_addc_u32 s19, s19, 0
	global_load_lds_dwordx4 v[218:219], off
	v_lshl_add_u64 v[218:219], s[18:19], 0, v[134:135]
	s_mov_b32 m0, s39
	s_nop 0
	global_load_lds_dwordx4 v[218:219], off
	v_lshl_add_u64 v[218:219], s[18:19], 0, v[130:131]
	s_mov_b32 m0, s40
	s_nop 0
	global_load_lds_dwordx4 v[218:219], off
	v_lshl_add_u64 v[218:219], v[222:223], 0, s[8:9]
	s_mov_b32 m0, s27
	s_nop 0
	global_load_lds_dwordx4 v[218:219], off
	v_lshl_add_u64 v[218:219], v[224:225], 0, s[8:9]
	s_mov_b32 m0, s28
	s_nop 0
	global_load_lds_dwordx4 v[218:219], off
	s_waitcnt vmcnt(8)
	s_waitcnt lgkmcnt(0)
	s_barrier
	s_setprio 1
	s_waitcnt lgkmcnt(0)
	v_mfma_f32_16x16x32_bf16 v[62:65], v[152:155], v[186:189], v[62:65]
	v_mfma_f32_16x16x32_bf16 v[58:61], v[160:163], v[186:189], v[58:61]
	v_mfma_f32_16x16x32_bf16 v[46:49], v[152:155], v[194:197], v[46:49]
	v_mfma_f32_16x16x32_bf16 v[42:45], v[160:163], v[194:197], v[42:45]
	v_mfma_f32_16x16x32_bf16 v[30:33], v[152:155], v[202:205], v[30:33]
	v_mfma_f32_16x16x32_bf16 v[26:29], v[160:163], v[202:205], v[26:29]
	v_mfma_f32_16x16x32_bf16 v[14:17], v[152:155], v[210:213], v[14:17]
	v_mfma_f32_16x16x32_bf16 v[10:13], v[160:163], v[210:213], v[10:13]
	v_mfma_f32_16x16x32_bf16 v[62:65], v[156:159], v[190:193], v[62:65]
	v_mfma_f32_16x16x32_bf16 v[58:61], v[164:167], v[190:193], v[58:61]
	v_mfma_f32_16x16x32_bf16 v[46:49], v[156:159], v[198:201], v[46:49]
	v_mfma_f32_16x16x32_bf16 v[42:45], v[164:167], v[198:201], v[42:45]
	v_mfma_f32_16x16x32_bf16 v[30:33], v[156:159], v[206:209], v[30:33]
	v_mfma_f32_16x16x32_bf16 v[26:29], v[164:167], v[206:209], v[26:29]
	v_mfma_f32_16x16x32_bf16 v[14:17], v[156:159], v[214:217], v[14:17]
	v_mfma_f32_16x16x32_bf16 v[10:13], v[164:167], v[214:217], v[10:13]
	s_setprio 0
	s_setprio 1
	v_mfma_f32_16x16x32_bf16 v[54:57], v[168:171], v[186:189], v[54:57]
	v_mfma_f32_16x16x32_bf16 v[50:53], v[176:179], v[186:189], v[50:53]
	v_mfma_f32_16x16x32_bf16 v[38:41], v[168:171], v[194:197], v[38:41]
	v_mfma_f32_16x16x32_bf16 v[34:37], v[176:179], v[194:197], v[34:37]
	v_mfma_f32_16x16x32_bf16 v[22:25], v[168:171], v[202:205], v[22:25]
	v_mfma_f32_16x16x32_bf16 v[18:21], v[176:179], v[202:205], v[18:21]
	v_mfma_f32_16x16x32_bf16 v[6:9], v[168:171], v[210:213], v[6:9]
	v_mfma_f32_16x16x32_bf16 v[2:5], v[176:179], v[210:213], v[2:5]
	v_mfma_f32_16x16x32_bf16 v[54:57], v[172:175], v[190:193], v[54:57]
	v_mfma_f32_16x16x32_bf16 v[50:53], v[182:185], v[190:193], v[50:53]
	v_mfma_f32_16x16x32_bf16 v[38:41], v[172:175], v[198:201], v[38:41]
	v_mfma_f32_16x16x32_bf16 v[34:37], v[182:185], v[198:201], v[34:37]
	v_mfma_f32_16x16x32_bf16 v[22:25], v[172:175], v[206:209], v[22:25]
	v_mfma_f32_16x16x32_bf16 v[18:21], v[182:185], v[206:209], v[18:21]
	v_mfma_f32_16x16x32_bf16 v[6:9], v[172:175], v[214:217], v[6:9]
	v_mfma_f32_16x16x32_bf16 v[2:5], v[182:185], v[214:217], v[2:5]
	s_setprio 0
	s_barrier
	s_add_i32 s53, s53, 2
	s_add_u32 s16, s16, 0x100
	s_addc_u32 s17, s17, 0
	s_add_u32 s49, s49, 0x100
	s_addc_u32 s52, s52, 0

.LBB0_947:
	ds_read_b128 v[146:149], v154
	ds_read_b128 v[158:161], v154 offset:1024
	ds_read_b128 v[162:165], v154 offset:2048
	ds_read_b128 v[166:169], v154 offset:3072
	ds_read_b128 v[170:173], v155
	ds_read_b128 v[174:177], v155 offset:1024
	ds_read_b128 v[182:185], v155 offset:2048
	ds_read_b128 v[186:189], v155 offset:3072
	s_add_i32 s40, s40, 1
	s_mul_i32 s4, s40, s43
	s_mul_hi_u32 s5, s40, s46
	s_add_i32 s5, s5, s4
	s_mul_i32 s4, s40, s46
	s_add_u32 s20, s4, s96
	s_addc_u32 s21, s5, s47
	v_cmp_gt_i64_e32 vcc, s[20:21], v[144:145]
	v_cmp_lt_i64_e64 s[4:5], s[20:21], v[142:143]
	s_cbranch_vccnz .LBB0_953
	s_ashr_i32 s16, s20, 31
	s_lshr_b32 s16, s16, 29
	s_add_i32 s18, s20, s16
	s_and_b32 s16, s18, -8
	s_sub_i32 s19, s20, s16
	s_cmp_gt_i32 s19, -1
	s_mov_b64 s[16:17], -1
	s_cbranch_scc0 .LBB0_950
	s_lshl_b32 s20, s19, 8
	s_mov_b64 s[16:17], 0

.LBB0_953:
	s_ashr_i32 s19, s18, 31
	s_lshl_b64 s[20:21], s[18:19], 18
	s_add_u32 s20, s0, s20
	s_addc_u32 s21, s1, s21
	s_and_b64 s[22:23], s[4:5], exec
	s_cselect_b32 s19, s21, s29
	s_cselect_b32 s25, s20, s28
	s_ashr_i32 s17, s16, 31
	s_lshl_b64 s[22:23], s[16:17], 18
	v_readlane_b32 s34, v244, 37
	v_readlane_b32 s35, v244, 38
	s_add_u32 s22, s34, s22
	s_addc_u32 s23, s35, s23
	s_and_b64 s[34:35], s[4:5], exec
	s_cselect_b32 s17, s23, s31
	s_cselect_b32 s52, s22, s30
	s_add_u32 s28, s28, 0x20080
	s_addc_u32 s29, s29, 0
	s_add_u32 s53, s30, 0x100

	s_addc_u32 s56, s31, 0
	s_mov_b32 s57, -2


	s_waitcnt lgkmcnt(0)


	s_add_u32 s30, s28, 0xfffe0080
	s_addc_u32 s31, s29, -1
	s_cmp_eq_u32 s57, 4
	s_cselect_b32 s35, s19, s31
	s_cselect_b32 s34, s25, s30
	s_cselect_b32 s31, s17, s56
	s_cselect_b32 s30, s52, s53
	v_lshl_add_u64 v[178:179], s[28:29], 0, v[138:139]
	s_add_i32 m0, s27, 0xc000
	ds_read_b128 v[190:193], v156
	ds_read_b128 v[194:197], v156 offset:1024
	ds_read_b128 v[198:201], v156 offset:2048
	ds_read_b128 v[202:205], v156 offset:3072
	ds_read_b128 v[206:209], v156 offset:4096
	ds_read_b128 v[210:213], v156 offset:5120
	ds_read_b128 v[214:217], v156 offset:6144
	ds_read_b128 v[218:221], v156 offset:7168
	global_load_lds_dwordx4 v[178:179], off
	v_lshl_add_u64 v[178:179], s[28:29], 0, v[140:141]
	s_add_i32 m0, s27, 0xe000
	s_nop 0
	global_load_lds_dwordx4 v[178:179], off
	s_waitcnt vmcnt(8)
	s_waitcnt lgkmcnt(0)
	s_barrier
	s_setprio 1
	s_waitcnt lgkmcnt(0)
	v_mfma_f32_16x16x32_bf16 v[118:121], v[146:149], v[190:193], 0
	v_mfma_f32_16x16x32_bf16 v[114:117], v[162:165], v[190:193], 0
	v_mfma_f32_16x16x32_bf16 v[102:105], v[146:149], v[198:201], 0
	v_mfma_f32_16x16x32_bf16 v[98:101], v[162:165], v[198:201], 0
	v_mfma_f32_16x16x32_bf16 v[86:89], v[146:149], v[206:209], 0
	v_mfma_f32_16x16x32_bf16 v[82:85], v[162:165], v[206:209], 0
	v_mfma_f32_16x16x32_bf16 v[70:73], v[146:149], v[214:217], 0
	v_mfma_f32_16x16x32_bf16 v[66:69], v[162:165], v[214:217], 0
	v_mfma_f32_16x16x32_bf16 v[118:121], v[158:161], v[194:197], v[118:121]
	v_mfma_f32_16x16x32_bf16 v[114:117], v[166:169], v[194:197], v[114:117]
	v_mfma_f32_16x16x32_bf16 v[102:105], v[158:161], v[202:205], v[102:105]
	v_mfma_f32_16x16x32_bf16 v[98:101], v[166:169], v[202:205], v[98:101]
	v_mfma_f32_16x16x32_bf16 v[86:89], v[158:161], v[210:213], v[86:89]
	v_mfma_f32_16x16x32_bf16 v[82:85], v[166:169], v[210:213], v[82:85]
	v_mfma_f32_16x16x32_bf16 v[70:73], v[158:161], v[218:221], v[70:73]
	v_mfma_f32_16x16x32_bf16 v[66:69], v[166:169], v[218:221], v[66:69]
	s_setprio 0
	s_setprio 1
	v_mfma_f32_16x16x32_bf16 v[126:129], v[170:173], v[190:193], 0
	v_mfma_f32_16x16x32_bf16 v[122:125], v[182:185], v[190:193], 0
	v_mfma_f32_16x16x32_bf16 v[110:113], v[170:173], v[198:201], 0
	v_mfma_f32_16x16x32_bf16 v[106:109], v[182:185], v[198:201], 0
	v_mfma_f32_16x16x32_bf16 v[94:97], v[170:173], v[206:209], 0
	v_mfma_f32_16x16x32_bf16 v[90:93], v[182:185], v[206:209], 0
	v_mfma_f32_16x16x32_bf16 v[78:81], v[170:173], v[214:217], 0
	v_mfma_f32_16x16x32_bf16 v[74:77], v[182:185], v[214:217], 0
	v_mfma_f32_16x16x32_bf16 v[126:129], v[174:177], v[194:197], v[126:129]
	v_mfma_f32_16x16x32_bf16 v[122:125], v[186:189], v[194:197], v[122:125]
	v_mfma_f32_16x16x32_bf16 v[110:113], v[174:177], v[202:205], v[110:113]
	v_mfma_f32_16x16x32_bf16 v[106:109], v[186:189], v[202:205], v[106:109]
	v_mfma_f32_16x16x32_bf16 v[94:97], v[174:177], v[210:213], v[94:97]
	v_mfma_f32_16x16x32_bf16 v[90:93], v[186:189], v[210:213], v[90:93]
	v_mfma_f32_16x16x32_bf16 v[78:81], v[174:177], v[218:221], v[78:81]
	v_mfma_f32_16x16x32_bf16 v[74:77], v[186:189], v[218:221], v[74:77]
	s_setprio 0
	s_barrier
	s_add_i32 s33, s48, s36
	v_lshl_add_u64 v[178:179], s[30:31], 0, v[132:133]
	s_mov_b32 m0, s33
	ds_read_b128 v[190:193], v156 offset:16384
	ds_read_b128 v[194:197], v156 offset:17408
	ds_read_b128 v[198:201], v156 offset:18432
	ds_read_b128 v[202:205], v156 offset:19456
	ds_read_b128 v[206:209], v156 offset:20480
	ds_read_b128 v[210:213], v156 offset:21504
	ds_read_b128 v[214:217], v156 offset:22528
	ds_read_b128 v[218:221], v156 offset:23552
	global_load_lds_dwordx4 v[178:179], off
	s_add_i32 m0, s33, 0x2000
	s_add_u32 s54, s30, 0x20000
	v_lshl_add_u64 v[222:223], s[30:31], 0, v[136:137]
	s_addc_u32 s55, s31, 0
	s_add_i32 s33, s49, s36
	global_load_lds_dwordx4 v[222:223], off
	v_lshl_add_u64 v[224:225], s[54:55], 0, v[132:133]
	s_mov_b32 m0, s33
	v_lshl_add_u64 v[226:227], s[34:35], 0, v[134:135]
	global_load_lds_dwordx4 v[224:225], off
	v_lshl_add_u64 v[224:225], s[54:55], 0, v[136:137]
	s_add_i32 m0, s33, 0x2000
	s_nop 0
	global_load_lds_dwordx4 v[224:225], off
	v_lshl_add_u64 v[224:225], s[34:35], 0, v[130:131]
	s_mov_b32 m0, s27
	s_nop 0
	global_load_lds_dwordx4 v[224:225], off
	s_mov_b32 m0, s37
	s_nop 0
	global_load_lds_dwordx4 v[226:227], off
	s_waitcnt vmcnt(8)
	s_waitcnt lgkmcnt(0)
	s_barrier
	s_setprio 1
	s_waitcnt lgkmcnt(0)
	v_mfma_f32_16x16x32_bf16 v[54:57], v[146:149], v[190:193], 0
	v_mfma_f32_16x16x32_bf16 v[50:53], v[162:165], v[190:193], 0
	v_mfma_f32_16x16x32_bf16 v[38:41], v[146:149], v[198:201], 0
	v_mfma_f32_16x16x32_bf16 v[34:37], v[162:165], v[198:201], 0
	v_mfma_f32_16x16x32_bf16 v[22:25], v[146:149], v[206:209], 0
	v_mfma_f32_16x16x32_bf16 v[18:21], v[162:165], v[206:209], 0
	v_mfma_f32_16x16x32_bf16 v[10:13], v[146:149], v[214:217], 0
	v_mfma_f32_16x16x32_bf16 v[2:5], v[162:165], v[214:217], 0
	v_mfma_f32_16x16x32_bf16 v[54:57], v[158:161], v[194:197], v[54:57]
	v_mfma_f32_16x16x32_bf16 v[50:53], v[166:169], v[194:197], v[50:53]
	v_mfma_f32_16x16x32_bf16 v[38:41], v[158:161], v[202:205], v[38:41]
	v_mfma_f32_16x16x32_bf16 v[34:37], v[166:169], v[202:205], v[34:37]
	v_mfma_f32_16x16x32_bf16 v[22:25], v[158:161], v[210:213], v[22:25]
	v_mfma_f32_16x16x32_bf16 v[18:21], v[166:169], v[210:213], v[18:21]
	v_mfma_f32_16x16x32_bf16 v[10:13], v[158:161], v[218:221], v[10:13]
	v_mfma_f32_16x16x32_bf16 v[2:5], v[166:169], v[218:221], v[2:5]
	s_setprio 0
	s_setprio 1
	v_mfma_f32_16x16x32_bf16 v[62:65], v[170:173], v[190:193], 0
	v_mfma_f32_16x16x32_bf16 v[58:61], v[182:185], v[190:193], 0
	v_mfma_f32_16x16x32_bf16 v[46:49], v[170:173], v[198:201], 0
	v_mfma_f32_16x16x32_bf16 v[42:45], v[182:185], v[198:201], 0
	v_mfma_f32_16x16x32_bf16 v[30:33], v[170:173], v[206:209], 0
	v_mfma_f32_16x16x32_bf16 v[26:29], v[182:185], v[206:209], 0
	v_mfma_f32_16x16x32_bf16 v[14:17], v[170:173], v[214:217], 0
	v_mfma_f32_16x16x32_bf16 v[6:9], v[182:185], v[214:217], 0
	v_mfma_f32_16x16x32_bf16 v[62:65], v[174:177], v[194:197], v[62:65]
	v_mfma_f32_16x16x32_bf16 v[58:61], v[186:189], v[194:197], v[58:61]
	v_mfma_f32_16x16x32_bf16 v[46:49], v[174:177], v[202:205], v[46:49]
	v_mfma_f32_16x16x32_bf16 v[42:45], v[186:189], v[202:205], v[42:45]
	v_mfma_f32_16x16x32_bf16 v[30:33], v[174:177], v[210:213], v[30:33]
	v_mfma_f32_16x16x32_bf16 v[26:29], v[186:189], v[210:213], v[26:29]
	v_mfma_f32_16x16x32_bf16 v[14:17], v[174:177], v[218:221], v[14:17]
	v_mfma_f32_16x16x32_bf16 v[6:9], v[186:189], v[218:221], v[6:9]
	s_setprio 0
	s_barrier
	s_add_i32 s33, 0, 0x18000
	s_add_i32 s51, 0, 0x1c000
	v_add_u32_e32 v166, s33, v152
	v_add_u32_e32 v186, s51, v152
	ds_read_b128 v[146:149], v166
	ds_read_b128 v[158:161], v166 offset:1024
	ds_read_b128 v[162:165], v166 offset:2048
	ds_read_b128 v[166:169], v166 offset:3072
	ds_read_b128 v[170:173], v186
	ds_read_b128 v[174:177], v186 offset:1024
	ds_read_b128 v[182:185], v186 offset:2048
	ds_read_b128 v[186:189], v186 offset:3072
	s_add_u32 s34, s34, 0x20000
	s_addc_u32 s35, s35, 0
	s_mov_b32 m0, s38
	v_lshl_add_u64 v[228:229], s[34:35], 0, v[130:131]
	ds_read_b128 v[190:193], v156 offset:32768
	ds_read_b128 v[194:197], v156 offset:33792
	ds_read_b128 v[198:201], v156 offset:34816
	ds_read_b128 v[202:205], v156 offset:35840
	ds_read_b128 v[206:209], v156 offset:36864
	ds_read_b128 v[210:213], v156 offset:37888
	ds_read_b128 v[214:217], v156 offset:38912
	ds_read_b128 v[218:221], v156 offset:39936
	global_load_lds_dwordx4 v[228:229], off
	v_lshl_add_u64 v[228:229], s[34:35], 0, v[134:135]
	s_mov_b32 m0, s39
	s_nop 0
	global_load_lds_dwordx4 v[228:229], off
	s_waitcnt vmcnt(8)
	s_waitcnt lgkmcnt(0)
	s_barrier
	s_setprio 1
	s_waitcnt lgkmcnt(0)
	v_mfma_f32_16x16x32_bf16 v[118:121], v[146:149], v[190:193], v[118:121]
	v_mfma_f32_16x16x32_bf16 v[114:117], v[162:165], v[190:193], v[114:117]
	v_mfma_f32_16x16x32_bf16 v[102:105], v[146:149], v[198:201], v[102:105]
	v_mfma_f32_16x16x32_bf16 v[98:101], v[162:165], v[198:201], v[98:101]
	v_mfma_f32_16x16x32_bf16 v[86:89], v[146:149], v[206:209], v[86:89]
	v_mfma_f32_16x16x32_bf16 v[82:85], v[162:165], v[206:209], v[82:85]
	v_mfma_f32_16x16x32_bf16 v[70:73], v[146:149], v[214:217], v[70:73]
	v_mfma_f32_16x16x32_bf16 v[66:69], v[162:165], v[214:217], v[66:69]
	v_mfma_f32_16x16x32_bf16 v[118:121], v[158:161], v[194:197], v[118:121]
	v_mfma_f32_16x16x32_bf16 v[114:117], v[166:169], v[194:197], v[114:117]
	v_mfma_f32_16x16x32_bf16 v[102:105], v[158:161], v[202:205], v[102:105]
	v_mfma_f32_16x16x32_bf16 v[98:101], v[166:169], v[202:205], v[98:101]
	v_mfma_f32_16x16x32_bf16 v[86:89], v[158:161], v[210:213], v[86:89]
	v_mfma_f32_16x16x32_bf16 v[82:85], v[166:169], v[210:213], v[82:85]
	v_mfma_f32_16x16x32_bf16 v[70:73], v[158:161], v[218:221], v[70:73]
	v_mfma_f32_16x16x32_bf16 v[66:69], v[166:169], v[218:221], v[66:69]
	s_setprio 0
	s_setprio 1
	v_mfma_f32_16x16x32_bf16 v[126:129], v[170:173], v[190:193], v[126:129]
	v_mfma_f32_16x16x32_bf16 v[122:125], v[182:185], v[190:193], v[122:125]
	v_mfma_f32_16x16x32_bf16 v[110:113], v[170:173], v[198:201], v[110:113]
	v_mfma_f32_16x16x32_bf16 v[106:109], v[182:185], v[198:201], v[106:109]
	v_mfma_f32_16x16x32_bf16 v[94:97], v[170:173], v[206:209], v[94:97]
	v_mfma_f32_16x16x32_bf16 v[90:93], v[182:185], v[206:209], v[90:93]
	v_mfma_f32_16x16x32_bf16 v[78:81], v[170:173], v[214:217], v[78:81]
	v_mfma_f32_16x16x32_bf16 v[74:77], v[182:185], v[214:217], v[74:77]
	v_mfma_f32_16x16x32_bf16 v[126:129], v[174:177], v[194:197], v[126:129]
	v_mfma_f32_16x16x32_bf16 v[122:125], v[186:189], v[194:197], v[122:125]
	v_mfma_f32_16x16x32_bf16 v[110:113], v[174:177], v[202:205], v[110:113]
	v_mfma_f32_16x16x32_bf16 v[106:109], v[186:189], v[202:205], v[106:109]
	v_mfma_f32_16x16x32_bf16 v[94:97], v[174:177], v[210:213], v[94:97]
	v_mfma_f32_16x16x32_bf16 v[90:93], v[186:189], v[210:213], v[90:93]
	v_mfma_f32_16x16x32_bf16 v[78:81], v[174:177], v[218:221], v[78:81]
	v_mfma_f32_16x16x32_bf16 v[74:77], v[186:189], v[218:221], v[74:77]
	s_setprio 0
	s_barrier
	s_add_i32 s33, s33, s36
	v_lshl_add_u64 v[178:179], v[178:179], 0, s[12:13]
	s_mov_b32 m0, s33
	ds_read_b128 v[190:193], v156 offset:49152
	ds_read_b128 v[194:197], v156 offset:50176
	ds_read_b128 v[198:201], v156 offset:51200
	ds_read_b128 v[202:205], v156 offset:52224
	ds_read_b128 v[206:209], v156 offset:53248
	ds_read_b128 v[210:213], v156 offset:54272
	ds_read_b128 v[214:217], v156 offset:55296
	ds_read_b128 v[218:221], v156 offset:56320
	global_load_lds_dwordx4 v[178:179], off
	s_add_i32 m0, s33, 0x2000
	s_add_u32 s30, s30, 0x20080
	v_lshl_add_u64 v[178:179], v[222:223], 0, s[12:13]
	s_addc_u32 s31, s31, 0
	s_add_i32 s33, s51, s36
	global_load_lds_dwordx4 v[178:179], off
	v_lshl_add_u64 v[178:179], s[30:31], 0, v[132:133]
	s_mov_b32 m0, s33
	s_nop 0
	global_load_lds_dwordx4 v[178:179], off
	v_lshl_add_u64 v[178:179], s[30:31], 0, v[136:137]
	s_add_i32 m0, s33, 0x2000
	s_nop 0
	global_load_lds_dwordx4 v[178:179], off
	v_lshl_add_u64 v[178:179], v[224:225], 0, s[12:13]
	s_mov_b32 m0, s41
	s_nop 0
	global_load_lds_dwordx4 v[178:179], off
	v_lshl_add_u64 v[178:179], v[226:227], 0, s[12:13]
	s_mov_b32 m0, s42
	s_nop 0
	global_load_lds_dwordx4 v[178:179], off
	s_waitcnt vmcnt(8)
	s_waitcnt lgkmcnt(0)
	s_barrier
	s_setprio 1
	s_waitcnt lgkmcnt(0)
	v_mfma_f32_16x16x32_bf16 v[54:57], v[146:149], v[190:193], v[54:57]
	v_mfma_f32_16x16x32_bf16 v[50:53], v[162:165], v[190:193], v[50:53]
	v_mfma_f32_16x16x32_bf16 v[38:41], v[146:149], v[198:201], v[38:41]
	v_mfma_f32_16x16x32_bf16 v[34:37], v[162:165], v[198:201], v[34:37]
	v_mfma_f32_16x16x32_bf16 v[22:25], v[146:149], v[206:209], v[22:25]
	v_mfma_f32_16x16x32_bf16 v[18:21], v[162:165], v[206:209], v[18:21]
	v_mfma_f32_16x16x32_bf16 v[10:13], v[146:149], v[214:217], v[10:13]
	v_mfma_f32_16x16x32_bf16 v[2:5], v[162:165], v[214:217], v[2:5]
	v_mfma_f32_16x16x32_bf16 v[54:57], v[158:161], v[194:197], v[54:57]
	v_mfma_f32_16x16x32_bf16 v[50:53], v[166:169], v[194:197], v[50:53]
	v_mfma_f32_16x16x32_bf16 v[38:41], v[158:161], v[202:205], v[38:41]
	v_mfma_f32_16x16x32_bf16 v[34:37], v[166:169], v[202:205], v[34:37]
	v_mfma_f32_16x16x32_bf16 v[22:25], v[158:161], v[210:213], v[22:25]
	v_mfma_f32_16x16x32_bf16 v[18:21], v[166:169], v[210:213], v[18:21]
	v_mfma_f32_16x16x32_bf16 v[10:13], v[158:161], v[218:221], v[10:13]
	v_mfma_f32_16x16x32_bf16 v[2:5], v[166:169], v[218:221], v[2:5]
	s_setprio 0
	s_setprio 1
	v_mfma_f32_16x16x32_bf16 v[62:65], v[170:173], v[190:193], v[62:65]
	v_mfma_f32_16x16x32_bf16 v[58:61], v[182:185], v[190:193], v[58:61]
	v_mfma_f32_16x16x32_bf16 v[46:49], v[170:173], v[198:201], v[46:49]
	v_mfma_f32_16x16x32_bf16 v[42:45], v[182:185], v[198:201], v[42:45]
	v_mfma_f32_16x16x32_bf16 v[30:33], v[170:173], v[206:209], v[30:33]
	v_mfma_f32_16x16x32_bf16 v[26:29], v[182:185], v[206:209], v[26:29]
	v_mfma_f32_16x16x32_bf16 v[14:17], v[170:173], v[214:217], v[14:17]
	v_mfma_f32_16x16x32_bf16 v[6:9], v[182:185], v[214:217], v[6:9]
	v_mfma_f32_16x16x32_bf16 v[62:65], v[174:177], v[194:197], v[62:65]
	v_mfma_f32_16x16x32_bf16 v[58:61], v[186:189], v[194:197], v[58:61]
	v_mfma_f32_16x16x32_bf16 v[46:49], v[174:177], v[202:205], v[46:49]
	v_mfma_f32_16x16x32_bf16 v[42:45], v[186:189], v[202:205], v[42:45]
	v_mfma_f32_16x16x32_bf16 v[30:33], v[174:177], v[210:213], v[30:33]
	v_mfma_f32_16x16x32_bf16 v[26:29], v[186:189], v[210:213], v[26:29]
	v_mfma_f32_16x16x32_bf16 v[14:17], v[174:177], v[218:221], v[14:17]
	v_mfma_f32_16x16x32_bf16 v[6:9], v[186:189], v[218:221], v[6:9]
	s_setprio 0
	s_barrier
	s_add_i32 s57, s57, 2
	s_add_u32 s28, s28, 0x100
	s_addc_u32 s29, s29, 0
	s_add_u32 s53, s53, 0x100
	s_addc_u32 s56, s56, 0

.LBB0_1066:
	ds_read_b128 v[160:163], v156
	ds_read_b128 v[164:167], v156 offset:1024
	ds_read_b128 v[168:171], v156 offset:2048
	ds_read_b128 v[172:175], v156 offset:3072
	ds_read_b128 v[176:179], v157
	ds_read_b128 v[182:185], v157 offset:1024
	ds_read_b128 v[186:189], v157 offset:2048
	ds_read_b128 v[190:193], v157 offset:3072
	s_add_i32 s53, s56, 1
	s_mul_i32 s2, s53, s43
	s_mul_hi_u32 s3, s53, s46
	s_add_i32 s3, s3, s2
	s_mul_i32 s2, s53, s46
	s_add_u32 s18, s2, s96
	s_addc_u32 s19, s3, s34
	v_cmp_gt_i64_e32 vcc, s[18:19], v[150:151]
	v_cmp_lt_i64_e64 s[2:3], s[18:19], v[148:149]
	s_cbranch_vccnz .LBB0_1068
	s_ashr_i32 s14, s18, 31
	s_lshr_b32 s14, s14, 29
	s_add_i32 s14, s18, s14
	s_ashr_i32 s15, s14, 3
	s_and_b32 s14, s14, -8
	s_sub_i32 s14, s18, s14
	s_cmp_lt_i32 s14, 0
	s_cselect_b32 s16, s47, 0x2c0
	s_mul_i32 s14, s14, s16
	s_add_i32 s14, s14, s15
	s_mul_hi_i32 s15, s14, 0x2e8ba2e9
	s_lshr_b32 s16, s15, 31
	s_ashr_i32 s15, s15, 5
	s_add_i32 s15, s15, s16
	s_lshl_b32 s16, s15, 3
	s_mulk_i32 s15, 0xb0
	s_sub_i32 s15, s14, s15
	s_ashr_i32 s14, s15, 3
	s_and_b32 s15, s15, 7
	s_add_i32 s16, s16, s15
.LBB0_1068:
	s_ashr_i32 s17, s16, 31
	s_lshl_b64 s[18:19], s[16:17], 19
	s_add_u32 s18, s92, s18
	s_addc_u32 s19, s93, s19
	s_and_b64 s[20:21], s[2:3], exec
	s_cselect_b32 s17, s19, s27
	s_cselect_b32 s57, s18, s26
	s_ashr_i32 s15, s14, 31
	s_lshl_b64 s[20:21], s[14:15], 19
	s_add_u32 s20, s6, s20
	s_addc_u32 s21, s7, s21
	s_and_b64 s[30:31], s[2:3], exec
	s_cselect_b32 s15, s21, s29
	s_cselect_b32 s58, s20, s28
	s_add_u32 s26, s26, 0x40080
	s_addc_u32 s27, s27, 0
	s_add_u32 s59, s28, 0x100

	s_addc_u32 s60, s29, 0
	s_mov_b32 s61, -2


	s_add_u32 s28, s26, 0xfffc0080
	s_addc_u32 s29, s27, -1
	s_cmp_eq_u32 s61, 12
	s_cselect_b32 s31, s17, s29
	s_cselect_b32 s30, s57, s28
	s_cselect_b32 s29, s15, s60
	s_cselect_b32 s28, s58, s59
	v_lshl_add_u64 v[226:227], s[26:27], 0, v[144:145]
	s_add_i32 m0, s25, 0xc000
	ds_read_b128 v[194:197], v158
	ds_read_b128 v[198:201], v158 offset:1024
	ds_read_b128 v[202:205], v158 offset:2048
	ds_read_b128 v[206:209], v158 offset:3072
	ds_read_b128 v[210:213], v158 offset:4096
	ds_read_b128 v[214:217], v158 offset:5120
	ds_read_b128 v[218:221], v158 offset:6144
	ds_read_b128 v[222:225], v158 offset:7168
	global_load_lds_dwordx4 v[226:227], off
	v_lshl_add_u64 v[226:227], s[26:27], 0, v[146:147]
	s_add_i32 m0, s25, 0xe000
	s_nop 0
	global_load_lds_dwordx4 v[226:227], off
	s_waitcnt vmcnt(8)
	s_waitcnt lgkmcnt(0)
	s_barrier
	s_setprio 1
	s_waitcnt lgkmcnt(0)
	v_mfma_f32_16x16x32_bf16 v[126:129], v[160:163], v[194:197], 0
	v_mfma_f32_16x16x32_bf16 v[118:121], v[168:171], v[194:197], 0
	v_mfma_f32_16x16x32_bf16 v[110:113], v[160:163], v[202:205], 0
	v_mfma_f32_16x16x32_bf16 v[102:105], v[168:171], v[202:205], 0
	v_mfma_f32_16x16x32_bf16 v[94:97], v[160:163], v[210:213], 0
	v_mfma_f32_16x16x32_bf16 v[86:89], v[168:171], v[210:213], 0
	v_mfma_f32_16x16x32_bf16 v[78:81], v[160:163], v[218:221], 0
	v_mfma_f32_16x16x32_bf16 v[70:73], v[168:171], v[218:221], 0
	v_mfma_f32_16x16x32_bf16 v[126:129], v[164:167], v[198:201], v[126:129]
	v_mfma_f32_16x16x32_bf16 v[118:121], v[172:175], v[198:201], v[118:121]
	v_mfma_f32_16x16x32_bf16 v[110:113], v[164:167], v[206:209], v[110:113]
	v_mfma_f32_16x16x32_bf16 v[102:105], v[172:175], v[206:209], v[102:105]
	v_mfma_f32_16x16x32_bf16 v[94:97], v[164:167], v[214:217], v[94:97]
	v_mfma_f32_16x16x32_bf16 v[86:89], v[172:175], v[214:217], v[86:89]
	v_mfma_f32_16x16x32_bf16 v[78:81], v[164:167], v[222:225], v[78:81]
	v_mfma_f32_16x16x32_bf16 v[70:73], v[172:175], v[222:225], v[70:73]
	s_setprio 0
	s_setprio 1
	v_mfma_f32_16x16x32_bf16 v[122:125], v[176:179], v[194:197], 0
	v_mfma_f32_16x16x32_bf16 v[114:117], v[186:189], v[194:197], 0
	v_mfma_f32_16x16x32_bf16 v[106:109], v[176:179], v[202:205], 0
	v_mfma_f32_16x16x32_bf16 v[98:101], v[186:189], v[202:205], 0
	v_mfma_f32_16x16x32_bf16 v[90:93], v[176:179], v[210:213], 0
	v_mfma_f32_16x16x32_bf16 v[82:85], v[186:189], v[210:213], 0
	v_mfma_f32_16x16x32_bf16 v[74:77], v[176:179], v[218:221], 0
	v_mfma_f32_16x16x32_bf16 v[66:69], v[186:189], v[218:221], 0
	v_mfma_f32_16x16x32_bf16 v[122:125], v[182:185], v[198:201], v[122:125]
	v_mfma_f32_16x16x32_bf16 v[114:117], v[190:193], v[198:201], v[114:117]
	v_mfma_f32_16x16x32_bf16 v[106:109], v[182:185], v[206:209], v[106:109]
	v_mfma_f32_16x16x32_bf16 v[98:101], v[190:193], v[206:209], v[98:101]
	v_mfma_f32_16x16x32_bf16 v[90:93], v[182:185], v[214:217], v[90:93]
	v_mfma_f32_16x16x32_bf16 v[82:85], v[190:193], v[214:217], v[82:85]
	v_mfma_f32_16x16x32_bf16 v[74:77], v[182:185], v[222:225], v[74:77]
	v_mfma_f32_16x16x32_bf16 v[66:69], v[190:193], v[222:225], v[66:69]
	s_setprio 0
	s_barrier
	s_add_i32 s33, s48, s23
	v_lshl_add_u64 v[226:227], s[28:29], 0, v[132:133]
	s_mov_b32 m0, s33
	ds_read_b128 v[194:197], v158 offset:16384
	ds_read_b128 v[198:201], v158 offset:17408
	ds_read_b128 v[202:205], v158 offset:18432
	ds_read_b128 v[206:209], v158 offset:19456
	ds_read_b128 v[210:213], v158 offset:20480
	ds_read_b128 v[214:217], v158 offset:21504
	ds_read_b128 v[218:221], v158 offset:22528
	ds_read_b128 v[222:225], v158 offset:23552
	global_load_lds_dwordx4 v[226:227], off
	s_add_i32 m0, s33, 0x2000
	s_add_u32 s54, s28, 0x40000
	v_lshl_add_u64 v[228:229], s[28:29], 0, v[136:137]
	s_addc_u32 s55, s29, 0
	s_add_i32 s33, s49, s23
	global_load_lds_dwordx4 v[228:229], off
	v_lshl_add_u64 v[230:231], s[54:55], 0, v[132:133]
	s_mov_b32 m0, s33
	v_lshl_add_u64 v[232:233], s[30:31], 0, v[134:135]
	global_load_lds_dwordx4 v[230:231], off
	v_lshl_add_u64 v[230:231], s[54:55], 0, v[136:137]
	s_add_i32 m0, s33, 0x2000
	s_nop 0
	global_load_lds_dwordx4 v[230:231], off
	v_lshl_add_u64 v[230:231], s[30:31], 0, v[130:131]
	s_mov_b32 m0, s25
	s_nop 0
	global_load_lds_dwordx4 v[230:231], off
	s_mov_b32 m0, s35
	s_nop 0
	global_load_lds_dwordx4 v[232:233], off
	s_waitcnt vmcnt(8)
	s_waitcnt lgkmcnt(0)
	s_barrier
	s_setprio 1
	s_waitcnt lgkmcnt(0)
	v_mfma_f32_16x16x32_bf16 v[62:65], v[160:163], v[194:197], 0
	v_mfma_f32_16x16x32_bf16 v[54:57], v[168:171], v[194:197], 0
	v_mfma_f32_16x16x32_bf16 v[46:49], v[160:163], v[202:205], 0
	v_mfma_f32_16x16x32_bf16 v[38:41], v[168:171], v[202:205], 0
	v_mfma_f32_16x16x32_bf16 v[30:33], v[160:163], v[210:213], 0
	v_mfma_f32_16x16x32_bf16 v[22:25], v[168:171], v[210:213], 0
	v_mfma_f32_16x16x32_bf16 v[14:17], v[160:163], v[218:221], 0
	v_mfma_f32_16x16x32_bf16 v[6:9], v[168:171], v[218:221], 0
	v_mfma_f32_16x16x32_bf16 v[62:65], v[164:167], v[198:201], v[62:65]
	v_mfma_f32_16x16x32_bf16 v[54:57], v[172:175], v[198:201], v[54:57]
	v_mfma_f32_16x16x32_bf16 v[46:49], v[164:167], v[206:209], v[46:49]
	v_mfma_f32_16x16x32_bf16 v[38:41], v[172:175], v[206:209], v[38:41]
	v_mfma_f32_16x16x32_bf16 v[30:33], v[164:167], v[214:217], v[30:33]
	v_mfma_f32_16x16x32_bf16 v[22:25], v[172:175], v[214:217], v[22:25]
	v_mfma_f32_16x16x32_bf16 v[14:17], v[164:167], v[222:225], v[14:17]
	v_mfma_f32_16x16x32_bf16 v[6:9], v[172:175], v[222:225], v[6:9]
	s_setprio 0
	s_setprio 1
	v_mfma_f32_16x16x32_bf16 v[58:61], v[176:179], v[194:197], 0
	v_mfma_f32_16x16x32_bf16 v[50:53], v[186:189], v[194:197], 0
	v_mfma_f32_16x16x32_bf16 v[42:45], v[176:179], v[202:205], 0
	v_mfma_f32_16x16x32_bf16 v[34:37], v[186:189], v[202:205], 0
	v_mfma_f32_16x16x32_bf16 v[26:29], v[176:179], v[210:213], 0
	v_mfma_f32_16x16x32_bf16 v[18:21], v[186:189], v[210:213], 0
	v_mfma_f32_16x16x32_bf16 v[10:13], v[176:179], v[218:221], 0
	v_mfma_f32_16x16x32_bf16 v[2:5], v[186:189], v[218:221], 0
	v_mfma_f32_16x16x32_bf16 v[58:61], v[182:185], v[198:201], v[58:61]
	v_mfma_f32_16x16x32_bf16 v[50:53], v[190:193], v[198:201], v[50:53]
	v_mfma_f32_16x16x32_bf16 v[42:45], v[182:185], v[206:209], v[42:45]
	v_mfma_f32_16x16x32_bf16 v[34:37], v[190:193], v[206:209], v[34:37]
	v_mfma_f32_16x16x32_bf16 v[26:29], v[182:185], v[214:217], v[26:29]
	v_mfma_f32_16x16x32_bf16 v[18:21], v[190:193], v[214:217], v[18:21]
	v_mfma_f32_16x16x32_bf16 v[10:13], v[182:185], v[222:225], v[10:13]
	v_mfma_f32_16x16x32_bf16 v[2:5], v[190:193], v[222:225], v[2:5]
	s_setprio 0
	s_barrier
	s_add_i32 s33, 0, 0x18000
	s_add_i32 s51, 0, 0x1c000
	v_add_u32_e32 v172, s33, v154
	v_add_u32_e32 v190, s51, v154
	ds_read_b128 v[160:163], v172
	ds_read_b128 v[164:167], v172 offset:1024
	ds_read_b128 v[168:171], v172 offset:2048
	ds_read_b128 v[172:175], v172 offset:3072
	ds_read_b128 v[176:179], v190
	ds_read_b128 v[182:185], v190 offset:1024
	ds_read_b128 v[186:189], v190 offset:2048
	ds_read_b128 v[190:193], v190 offset:3072
	s_add_u32 s30, s30, 0x40000
	s_addc_u32 s31, s31, 0
	s_mov_b32 m0, s36
	v_lshl_add_u64 v[234:235], s[30:31], 0, v[130:131]
	ds_read_b128 v[194:197], v158 offset:32768
	ds_read_b128 v[198:201], v158 offset:33792
	ds_read_b128 v[202:205], v158 offset:34816
	ds_read_b128 v[206:209], v158 offset:35840
	ds_read_b128 v[210:213], v158 offset:36864
	ds_read_b128 v[214:217], v158 offset:37888
	ds_read_b128 v[218:221], v158 offset:38912
	ds_read_b128 v[222:225], v158 offset:39936
	global_load_lds_dwordx4 v[234:235], off
	v_lshl_add_u64 v[234:235], s[30:31], 0, v[134:135]
	s_mov_b32 m0, s37
	s_nop 0
	global_load_lds_dwordx4 v[234:235], off
	s_waitcnt vmcnt(8)
	s_waitcnt lgkmcnt(0)
	s_barrier
	s_setprio 1
	s_waitcnt lgkmcnt(0)
	v_mfma_f32_16x16x32_bf16 v[126:129], v[160:163], v[194:197], v[126:129]
	v_mfma_f32_16x16x32_bf16 v[118:121], v[168:171], v[194:197], v[118:121]
	v_mfma_f32_16x16x32_bf16 v[110:113], v[160:163], v[202:205], v[110:113]
	v_mfma_f32_16x16x32_bf16 v[102:105], v[168:171], v[202:205], v[102:105]
	v_mfma_f32_16x16x32_bf16 v[94:97], v[160:163], v[210:213], v[94:97]
	v_mfma_f32_16x16x32_bf16 v[86:89], v[168:171], v[210:213], v[86:89]
	v_mfma_f32_16x16x32_bf16 v[78:81], v[160:163], v[218:221], v[78:81]
	v_mfma_f32_16x16x32_bf16 v[70:73], v[168:171], v[218:221], v[70:73]
	v_mfma_f32_16x16x32_bf16 v[126:129], v[164:167], v[198:201], v[126:129]
	v_mfma_f32_16x16x32_bf16 v[118:121], v[172:175], v[198:201], v[118:121]
	v_mfma_f32_16x16x32_bf16 v[110:113], v[164:167], v[206:209], v[110:113]
	v_mfma_f32_16x16x32_bf16 v[102:105], v[172:175], v[206:209], v[102:105]
	v_mfma_f32_16x16x32_bf16 v[94:97], v[164:167], v[214:217], v[94:97]
	v_mfma_f32_16x16x32_bf16 v[86:89], v[172:175], v[214:217], v[86:89]
	v_mfma_f32_16x16x32_bf16 v[78:81], v[164:167], v[222:225], v[78:81]
	v_mfma_f32_16x16x32_bf16 v[70:73], v[172:175], v[222:225], v[70:73]
	s_setprio 0
	s_setprio 1
	v_mfma_f32_16x16x32_bf16 v[122:125], v[176:179], v[194:197], v[122:125]
	v_mfma_f32_16x16x32_bf16 v[114:117], v[186:189], v[194:197], v[114:117]
	v_mfma_f32_16x16x32_bf16 v[106:109], v[176:179], v[202:205], v[106:109]
	v_mfma_f32_16x16x32_bf16 v[98:101], v[186:189], v[202:205], v[98:101]
	v_mfma_f32_16x16x32_bf16 v[90:93], v[176:179], v[210:213], v[90:93]
	v_mfma_f32_16x16x32_bf16 v[82:85], v[186:189], v[210:213], v[82:85]
	v_mfma_f32_16x16x32_bf16 v[74:77], v[176:179], v[218:221], v[74:77]
	v_mfma_f32_16x16x32_bf16 v[66:69], v[186:189], v[218:221], v[66:69]
	v_mfma_f32_16x16x32_bf16 v[122:125], v[182:185], v[198:201], v[122:125]
	v_mfma_f32_16x16x32_bf16 v[114:117], v[190:193], v[198:201], v[114:117]
	v_mfma_f32_16x16x32_bf16 v[106:109], v[182:185], v[206:209], v[106:109]
	v_mfma_f32_16x16x32_bf16 v[98:101], v[190:193], v[206:209], v[98:101]
	v_mfma_f32_16x16x32_bf16 v[90:93], v[182:185], v[214:217], v[90:93]
	v_mfma_f32_16x16x32_bf16 v[82:85], v[190:193], v[214:217], v[82:85]
	v_mfma_f32_16x16x32_bf16 v[74:77], v[182:185], v[222:225], v[74:77]
	v_mfma_f32_16x16x32_bf16 v[66:69], v[190:193], v[222:225], v[66:69]
	s_setprio 0
	s_barrier
	s_add_i32 s30, s33, s23
	v_lshl_add_u64 v[226:227], v[226:227], 0, s[12:13]
	s_mov_b32 m0, s30
	ds_read_b128 v[194:197], v158 offset:49152
	ds_read_b128 v[198:201], v158 offset:50176
	ds_read_b128 v[202:205], v158 offset:51200
	ds_read_b128 v[206:209], v158 offset:52224
	ds_read_b128 v[210:213], v158 offset:53248
	ds_read_b128 v[214:217], v158 offset:54272
	ds_read_b128 v[218:221], v158 offset:55296
	ds_read_b128 v[222:225], v158 offset:56320
	global_load_lds_dwordx4 v[226:227], off
	s_add_i32 m0, s30, 0x2000
	s_add_u32 s28, s28, 0x40080
	v_lshl_add_u64 v[226:227], v[228:229], 0, s[12:13]
	s_addc_u32 s29, s29, 0
	s_add_i32 s30, s51, s23
	global_load_lds_dwordx4 v[226:227], off
	v_lshl_add_u64 v[226:227], s[28:29], 0, v[132:133]
	s_mov_b32 m0, s30
	s_nop 0
	global_load_lds_dwordx4 v[226:227], off
	v_lshl_add_u64 v[226:227], s[28:29], 0, v[136:137]
	s_add_i32 m0, s30, 0x2000
	s_nop 0
	global_load_lds_dwordx4 v[226:227], off
	v_lshl_add_u64 v[226:227], v[230:231], 0, s[12:13]
	s_mov_b32 m0, s40
	s_nop 0
	global_load_lds_dwordx4 v[226:227], off
	v_lshl_add_u64 v[226:227], v[232:233], 0, s[12:13]
	s_mov_b32 m0, s41
	s_nop 0
	global_load_lds_dwordx4 v[226:227], off
	s_waitcnt vmcnt(8)
	s_waitcnt lgkmcnt(0)
	s_barrier
	s_setprio 1
	s_waitcnt lgkmcnt(0)
	v_mfma_f32_16x16x32_bf16 v[62:65], v[160:163], v[194:197], v[62:65]
	v_mfma_f32_16x16x32_bf16 v[54:57], v[168:171], v[194:197], v[54:57]
	v_mfma_f32_16x16x32_bf16 v[46:49], v[160:163], v[202:205], v[46:49]
	v_mfma_f32_16x16x32_bf16 v[38:41], v[168:171], v[202:205], v[38:41]
	v_mfma_f32_16x16x32_bf16 v[30:33], v[160:163], v[210:213], v[30:33]
	v_mfma_f32_16x16x32_bf16 v[22:25], v[168:171], v[210:213], v[22:25]
	v_mfma_f32_16x16x32_bf16 v[14:17], v[160:163], v[218:221], v[14:17]
	v_mfma_f32_16x16x32_bf16 v[6:9], v[168:171], v[218:221], v[6:9]
	v_mfma_f32_16x16x32_bf16 v[62:65], v[164:167], v[198:201], v[62:65]
	v_mfma_f32_16x16x32_bf16 v[54:57], v[172:175], v[198:201], v[54:57]
	v_mfma_f32_16x16x32_bf16 v[46:49], v[164:167], v[206:209], v[46:49]
	v_mfma_f32_16x16x32_bf16 v[38:41], v[172:175], v[206:209], v[38:41]
	v_mfma_f32_16x16x32_bf16 v[30:33], v[164:167], v[214:217], v[30:33]
	v_mfma_f32_16x16x32_bf16 v[22:25], v[172:175], v[214:217], v[22:25]
	v_mfma_f32_16x16x32_bf16 v[14:17], v[164:167], v[222:225], v[14:17]
	v_mfma_f32_16x16x32_bf16 v[6:9], v[172:175], v[222:225], v[6:9]
	s_setprio 0
	s_setprio 1
	v_mfma_f32_16x16x32_bf16 v[58:61], v[176:179], v[194:197], v[58:61]
	v_mfma_f32_16x16x32_bf16 v[50:53], v[186:189], v[194:197], v[50:53]
	v_mfma_f32_16x16x32_bf16 v[42:45], v[176:179], v[202:205], v[42:45]
	v_mfma_f32_16x16x32_bf16 v[34:37], v[186:189], v[202:205], v[34:37]
	v_mfma_f32_16x16x32_bf16 v[26:29], v[176:179], v[210:213], v[26:29]
	v_mfma_f32_16x16x32_bf16 v[18:21], v[186:189], v[210:213], v[18:21]
	v_mfma_f32_16x16x32_bf16 v[10:13], v[176:179], v[218:221], v[10:13]
	v_mfma_f32_16x16x32_bf16 v[2:5], v[186:189], v[218:221], v[2:5]
	v_mfma_f32_16x16x32_bf16 v[58:61], v[182:185], v[198:201], v[58:61]
	v_mfma_f32_16x16x32_bf16 v[50:53], v[190:193], v[198:201], v[50:53]
	v_mfma_f32_16x16x32_bf16 v[42:45], v[182:185], v[206:209], v[42:45]
	v_mfma_f32_16x16x32_bf16 v[34:37], v[190:193], v[206:209], v[34:37]
	v_mfma_f32_16x16x32_bf16 v[26:29], v[182:185], v[214:217], v[26:29]
	v_mfma_f32_16x16x32_bf16 v[18:21], v[190:193], v[214:217], v[18:21]
	v_mfma_f32_16x16x32_bf16 v[10:13], v[182:185], v[222:225], v[10:13]
	v_mfma_f32_16x16x32_bf16 v[2:5], v[190:193], v[222:225], v[2:5]
	s_setprio 0
	s_barrier
	s_add_i32 s61, s61, 2
	s_add_u32 s26, s26, 0x100
	s_addc_u32 s27, s27, 0
	s_add_u32 s59, s59, 0x100
	s_addc_u32 s60, s60, 0

.LBB0_1166:
	ds_read_b128 v[146:149], v154
	ds_read_b128 v[158:161], v154 offset:1024
	ds_read_b128 v[162:165], v154 offset:2048
	ds_read_b128 v[166:169], v154 offset:3072
	ds_read_b128 v[170:173], v155
	ds_read_b128 v[174:177], v155 offset:1024
	ds_read_b128 v[182:185], v155 offset:2048
	ds_read_b128 v[186:189], v155 offset:3072
	s_add_i32 s35, s35, 1
	s_mul_i32 s4, s35, s38
	s_mul_hi_u32 s5, s35, s39
	s_add_i32 s5, s5, s4
	s_mul_i32 s4, s35, s39
	s_add_u32 s4, s4, s96
	s_addc_u32 s5, s5, s40
	v_cmp_gt_i64_e32 vcc, s[4:5], v[144:145]
	v_cmp_lt_i64_e64 s[6:7], s[4:5], v[142:143]
	s_cbranch_vccnz .LBB0_1172
	s_ashr_i32 s5, s4, 31
	s_lshr_b32 s5, s5, 29
	s_add_i32 s18, s4, s5
	s_and_b32 s5, s18, -8
	s_sub_i32 s19, s4, s5
	s_cmp_gt_i32 s19, -1
	s_mov_b64 s[4:5], -1
	s_cbranch_scc0 .LBB0_1169
	s_lshl_b32 s24, s19, 7
	s_mov_b64 s[4:5], 0

.LBB0_1176:
	s_add_u32 s20, s20, 0xc000
	s_addc_u32 s21, s21, 0
	s_add_u32 s49, s22, 0x100

	s_addc_u32 s52, s23, 0
	s_mov_b32 s53, -2
	s_waitcnt lgkmcnt(0)


	s_add_u32 s22, s20, 0x4000
	s_addc_u32 s23, s21, 0
	s_cmp_eq_u32 s53, 40
	s_cselect_b32 s26, s6, s22
	s_cselect_b32 s27, s7, s23
	s_cselect_b32 s24, s18, s49
	s_cselect_b32 s25, s19, s52
	s_add_u32 s22, s26, 0x8000
	s_addc_u32 s23, s27, 0
	v_lshl_add_u64 v[178:179], s[20:21], 0, v[138:139]
	s_add_i32 m0, s29, 0xc000
	ds_read_b128 v[190:193], v156
	ds_read_b128 v[194:197], v156 offset:1024
	ds_read_b128 v[198:201], v156 offset:2048
	ds_read_b128 v[202:205], v156 offset:3072
	ds_read_b128 v[206:209], v156 offset:4096
	ds_read_b128 v[210:213], v156 offset:5120
	ds_read_b128 v[214:217], v156 offset:6144
	ds_read_b128 v[218:221], v156 offset:7168
	global_load_lds_dwordx4 v[178:179], off
	v_lshl_add_u64 v[178:179], s[20:21], 0, v[140:141]
	s_add_i32 m0, s29, 0xe000
	s_nop 0
	global_load_lds_dwordx4 v[178:179], off
	s_waitcnt vmcnt(8)
	s_waitcnt lgkmcnt(0)
	s_barrier
	s_setprio 1
	s_waitcnt lgkmcnt(0)
	v_mfma_f32_16x16x32_bf16 v[126:129], v[146:149], v[190:193], 0
	v_mfma_f32_16x16x32_bf16 v[122:125], v[162:165], v[190:193], 0
	v_mfma_f32_16x16x32_bf16 v[110:113], v[146:149], v[198:201], 0
	v_mfma_f32_16x16x32_bf16 v[106:109], v[162:165], v[198:201], 0
	v_mfma_f32_16x16x32_bf16 v[94:97], v[146:149], v[206:209], 0
	v_mfma_f32_16x16x32_bf16 v[90:93], v[162:165], v[206:209], 0
	v_mfma_f32_16x16x32_bf16 v[78:81], v[146:149], v[214:217], 0
	v_mfma_f32_16x16x32_bf16 v[74:77], v[162:165], v[214:217], 0
	v_mfma_f32_16x16x32_bf16 v[126:129], v[158:161], v[194:197], v[126:129]
	v_mfma_f32_16x16x32_bf16 v[122:125], v[166:169], v[194:197], v[122:125]
	v_mfma_f32_16x16x32_bf16 v[110:113], v[158:161], v[202:205], v[110:113]
	v_mfma_f32_16x16x32_bf16 v[106:109], v[166:169], v[202:205], v[106:109]
	v_mfma_f32_16x16x32_bf16 v[94:97], v[158:161], v[210:213], v[94:97]
	v_mfma_f32_16x16x32_bf16 v[90:93], v[166:169], v[210:213], v[90:93]
	v_mfma_f32_16x16x32_bf16 v[78:81], v[158:161], v[218:221], v[78:81]
	v_mfma_f32_16x16x32_bf16 v[74:77], v[166:169], v[218:221], v[74:77]
	s_setprio 0
	s_setprio 1
	v_mfma_f32_16x16x32_bf16 v[118:121], v[170:173], v[190:193], 0
	v_mfma_f32_16x16x32_bf16 v[114:117], v[182:185], v[190:193], 0
	v_mfma_f32_16x16x32_bf16 v[102:105], v[170:173], v[198:201], 0
	v_mfma_f32_16x16x32_bf16 v[98:101], v[182:185], v[198:201], 0
	v_mfma_f32_16x16x32_bf16 v[86:89], v[170:173], v[206:209], 0
	v_mfma_f32_16x16x32_bf16 v[82:85], v[182:185], v[206:209], 0
	v_mfma_f32_16x16x32_bf16 v[70:73], v[170:173], v[214:217], 0
	v_mfma_f32_16x16x32_bf16 v[66:69], v[182:185], v[214:217], 0
	v_mfma_f32_16x16x32_bf16 v[118:121], v[174:177], v[194:197], v[118:121]
	v_mfma_f32_16x16x32_bf16 v[114:117], v[186:189], v[194:197], v[114:117]
	v_mfma_f32_16x16x32_bf16 v[102:105], v[174:177], v[202:205], v[102:105]
	v_mfma_f32_16x16x32_bf16 v[98:101], v[186:189], v[202:205], v[98:101]
	v_mfma_f32_16x16x32_bf16 v[86:89], v[174:177], v[210:213], v[86:89]
	v_mfma_f32_16x16x32_bf16 v[82:85], v[186:189], v[210:213], v[82:85]
	v_mfma_f32_16x16x32_bf16 v[70:73], v[174:177], v[218:221], v[70:73]
	v_mfma_f32_16x16x32_bf16 v[66:69], v[186:189], v[218:221], v[66:69]
	s_setprio 0
	s_barrier
	s_add_i32 s33, s41, s28
	v_lshl_add_u64 v[178:179], s[24:25], 0, v[132:133]
	s_mov_b32 m0, s33
	ds_read_b128 v[190:193], v156 offset:16384
	ds_read_b128 v[194:197], v156 offset:17408
	ds_read_b128 v[198:201], v156 offset:18432
	ds_read_b128 v[202:205], v156 offset:19456
	ds_read_b128 v[206:209], v156 offset:20480
	ds_read_b128 v[210:213], v156 offset:21504
	ds_read_b128 v[214:217], v156 offset:22528
	ds_read_b128 v[218:221], v156 offset:23552
	global_load_lds_dwordx4 v[178:179], off
	s_add_i32 m0, s33, 0x2000
	s_add_u32 s54, s24, 0xb0000
	v_lshl_add_u64 v[222:223], s[24:25], 0, v[136:137]
	s_addc_u32 s55, s25, 0
	s_add_i32 s33, s42, s28
	global_load_lds_dwordx4 v[222:223], off
	v_lshl_add_u64 v[224:225], s[54:55], 0, v[132:133]
	s_mov_b32 m0, s33
	s_nop 0
	global_load_lds_dwordx4 v[224:225], off
	v_lshl_add_u64 v[224:225], s[54:55], 0, v[136:137]
	s_add_i32 m0, s33, 0x2000
	s_nop 0
	global_load_lds_dwordx4 v[224:225], off
	v_lshl_add_u64 v[224:225], s[26:27], 0, v[130:131]
	s_mov_b32 m0, s29
	s_nop 0
	global_load_lds_dwordx4 v[224:225], off
	v_lshl_add_u64 v[224:225], s[26:27], 0, v[134:135]
	s_mov_b32 m0, s30
	s_nop 0
	global_load_lds_dwordx4 v[224:225], off
	s_waitcnt vmcnt(8)
	s_waitcnt lgkmcnt(0)
	s_barrier
	s_setprio 1
	s_waitcnt lgkmcnt(0)
	v_mfma_f32_16x16x32_bf16 v[62:65], v[146:149], v[190:193], 0
	v_mfma_f32_16x16x32_bf16 v[58:61], v[162:165], v[190:193], 0
	v_mfma_f32_16x16x32_bf16 v[46:49], v[146:149], v[198:201], 0
	v_mfma_f32_16x16x32_bf16 v[42:45], v[162:165], v[198:201], 0
	v_mfma_f32_16x16x32_bf16 v[30:33], v[146:149], v[206:209], 0
	v_mfma_f32_16x16x32_bf16 v[26:29], v[162:165], v[206:209], 0
	v_mfma_f32_16x16x32_bf16 v[14:17], v[146:149], v[214:217], 0
	v_mfma_f32_16x16x32_bf16 v[10:13], v[162:165], v[214:217], 0
	v_mfma_f32_16x16x32_bf16 v[62:65], v[158:161], v[194:197], v[62:65]
	v_mfma_f32_16x16x32_bf16 v[58:61], v[166:169], v[194:197], v[58:61]
	v_mfma_f32_16x16x32_bf16 v[46:49], v[158:161], v[202:205], v[46:49]
	v_mfma_f32_16x16x32_bf16 v[42:45], v[166:169], v[202:205], v[42:45]
	v_mfma_f32_16x16x32_bf16 v[30:33], v[158:161], v[210:213], v[30:33]
	v_mfma_f32_16x16x32_bf16 v[26:29], v[166:169], v[210:213], v[26:29]
	v_mfma_f32_16x16x32_bf16 v[14:17], v[158:161], v[218:221], v[14:17]
	v_mfma_f32_16x16x32_bf16 v[10:13], v[166:169], v[218:221], v[10:13]
	s_setprio 0
	s_setprio 1
	v_mfma_f32_16x16x32_bf16 v[54:57], v[170:173], v[190:193], 0
	v_mfma_f32_16x16x32_bf16 v[50:53], v[182:185], v[190:193], 0
	v_mfma_f32_16x16x32_bf16 v[38:41], v[170:173], v[198:201], 0
	v_mfma_f32_16x16x32_bf16 v[34:37], v[182:185], v[198:201], 0
	v_mfma_f32_16x16x32_bf16 v[22:25], v[170:173], v[206:209], 0
	v_mfma_f32_16x16x32_bf16 v[18:21], v[182:185], v[206:209], 0
	v_mfma_f32_16x16x32_bf16 v[6:9], v[170:173], v[214:217], 0
	v_mfma_f32_16x16x32_bf16 v[2:5], v[182:185], v[214:217], 0
	v_mfma_f32_16x16x32_bf16 v[54:57], v[174:177], v[194:197], v[54:57]
	v_mfma_f32_16x16x32_bf16 v[50:53], v[186:189], v[194:197], v[50:53]
	v_mfma_f32_16x16x32_bf16 v[38:41], v[174:177], v[202:205], v[38:41]
	v_mfma_f32_16x16x32_bf16 v[34:37], v[186:189], v[202:205], v[34:37]
	v_mfma_f32_16x16x32_bf16 v[22:25], v[174:177], v[210:213], v[22:25]
	v_mfma_f32_16x16x32_bf16 v[18:21], v[186:189], v[210:213], v[18:21]
	v_mfma_f32_16x16x32_bf16 v[6:9], v[174:177], v[218:221], v[6:9]
	v_mfma_f32_16x16x32_bf16 v[2:5], v[186:189], v[218:221], v[2:5]
	s_setprio 0
	s_barrier
	s_add_i32 s33, 0, 0x18000
	s_add_i32 s51, 0, 0x1c000
	v_add_u32_e32 v166, s33, v152
	v_add_u32_e32 v186, s51, v152
	ds_read_b128 v[146:149], v166
	ds_read_b128 v[158:161], v166 offset:1024
	ds_read_b128 v[162:165], v166 offset:2048
	ds_read_b128 v[166:169], v166 offset:3072
	ds_read_b128 v[170:173], v186
	ds_read_b128 v[174:177], v186 offset:1024
	ds_read_b128 v[182:185], v186 offset:2048
	ds_read_b128 v[186:189], v186 offset:3072
	s_add_u32 s26, s26, 0x4000
	s_addc_u32 s27, s27, 0
	s_mov_b32 m0, s31
	v_lshl_add_u64 v[224:225], s[26:27], 0, v[130:131]
	ds_read_b128 v[190:193], v156 offset:32768
	ds_read_b128 v[194:197], v156 offset:33792
	ds_read_b128 v[198:201], v156 offset:34816
	ds_read_b128 v[202:205], v156 offset:35840
	ds_read_b128 v[206:209], v156 offset:36864
	ds_read_b128 v[210:213], v156 offset:37888
	ds_read_b128 v[214:217], v156 offset:38912
	ds_read_b128 v[218:221], v156 offset:39936
	global_load_lds_dwordx4 v[224:225], off
	v_lshl_add_u64 v[224:225], s[26:27], 0, v[134:135]
	s_mov_b32 m0, s34
	s_nop 0
	global_load_lds_dwordx4 v[224:225], off
	s_waitcnt vmcnt(8)
	s_waitcnt lgkmcnt(0)
	s_barrier
	s_setprio 1
	s_waitcnt lgkmcnt(0)
	v_mfma_f32_16x16x32_bf16 v[126:129], v[146:149], v[190:193], v[126:129]
	v_mfma_f32_16x16x32_bf16 v[122:125], v[162:165], v[190:193], v[122:125]
	v_mfma_f32_16x16x32_bf16 v[110:113], v[146:149], v[198:201], v[110:113]
	v_mfma_f32_16x16x32_bf16 v[106:109], v[162:165], v[198:201], v[106:109]
	v_mfma_f32_16x16x32_bf16 v[94:97], v[146:149], v[206:209], v[94:97]
	v_mfma_f32_16x16x32_bf16 v[90:93], v[162:165], v[206:209], v[90:93]
	v_mfma_f32_16x16x32_bf16 v[78:81], v[146:149], v[214:217], v[78:81]
	v_mfma_f32_16x16x32_bf16 v[74:77], v[162:165], v[214:217], v[74:77]
	v_mfma_f32_16x16x32_bf16 v[126:129], v[158:161], v[194:197], v[126:129]
	v_mfma_f32_16x16x32_bf16 v[122:125], v[166:169], v[194:197], v[122:125]
	v_mfma_f32_16x16x32_bf16 v[110:113], v[158:161], v[202:205], v[110:113]
	v_mfma_f32_16x16x32_bf16 v[106:109], v[166:169], v[202:205], v[106:109]
	v_mfma_f32_16x16x32_bf16 v[94:97], v[158:161], v[210:213], v[94:97]
	v_mfma_f32_16x16x32_bf16 v[90:93], v[166:169], v[210:213], v[90:93]
	v_mfma_f32_16x16x32_bf16 v[78:81], v[158:161], v[218:221], v[78:81]
	v_mfma_f32_16x16x32_bf16 v[74:77], v[166:169], v[218:221], v[74:77]
	s_setprio 0
	s_setprio 1
	v_mfma_f32_16x16x32_bf16 v[118:121], v[170:173], v[190:193], v[118:121]
	v_mfma_f32_16x16x32_bf16 v[114:117], v[182:185], v[190:193], v[114:117]
	v_mfma_f32_16x16x32_bf16 v[102:105], v[170:173], v[198:201], v[102:105]
	v_mfma_f32_16x16x32_bf16 v[98:101], v[182:185], v[198:201], v[98:101]
	v_mfma_f32_16x16x32_bf16 v[86:89], v[170:173], v[206:209], v[86:89]
	v_mfma_f32_16x16x32_bf16 v[82:85], v[182:185], v[206:209], v[82:85]
	v_mfma_f32_16x16x32_bf16 v[70:73], v[170:173], v[214:217], v[70:73]
	v_mfma_f32_16x16x32_bf16 v[66:69], v[182:185], v[214:217], v[66:69]
	v_mfma_f32_16x16x32_bf16 v[118:121], v[174:177], v[194:197], v[118:121]
	v_mfma_f32_16x16x32_bf16 v[114:117], v[186:189], v[194:197], v[114:117]
	v_mfma_f32_16x16x32_bf16 v[102:105], v[174:177], v[202:205], v[102:105]
	v_mfma_f32_16x16x32_bf16 v[98:101], v[186:189], v[202:205], v[98:101]
	v_mfma_f32_16x16x32_bf16 v[86:89], v[174:177], v[210:213], v[86:89]
	v_mfma_f32_16x16x32_bf16 v[82:85], v[186:189], v[210:213], v[82:85]
	v_mfma_f32_16x16x32_bf16 v[70:73], v[174:177], v[218:221], v[70:73]
	v_mfma_f32_16x16x32_bf16 v[66:69], v[186:189], v[218:221], v[66:69]
	s_setprio 0
	s_barrier
	s_add_i32 s26, s33, s28
	v_lshl_add_u64 v[178:179], v[178:179], 0, s[14:15]
	s_mov_b32 m0, s26
	ds_read_b128 v[190:193], v156 offset:49152
	ds_read_b128 v[194:197], v156 offset:50176
	ds_read_b128 v[198:201], v156 offset:51200
	ds_read_b128 v[202:205], v156 offset:52224
	ds_read_b128 v[206:209], v156 offset:53248
	ds_read_b128 v[210:213], v156 offset:54272
	ds_read_b128 v[214:217], v156 offset:55296
	ds_read_b128 v[218:221], v156 offset:56320
	global_load_lds_dwordx4 v[178:179], off
	s_add_i32 m0, s26, 0x2000
	s_add_u32 s24, s24, 0xb0080
	v_lshl_add_u64 v[178:179], v[222:223], 0, s[14:15]
	s_addc_u32 s25, s25, 0
	s_add_i32 s26, s51, s28
	global_load_lds_dwordx4 v[178:179], off
	v_lshl_add_u64 v[178:179], s[24:25], 0, v[132:133]
	s_mov_b32 m0, s26
	s_nop 0
	global_load_lds_dwordx4 v[178:179], off
	v_lshl_add_u64 v[178:179], s[24:25], 0, v[136:137]
	s_add_i32 m0, s26, 0x2000
	s_nop 0
	global_load_lds_dwordx4 v[178:179], off
	v_lshl_add_u64 v[178:179], s[22:23], 0, v[130:131]
	s_mov_b32 m0, s36
	s_nop 0
	global_load_lds_dwordx4 v[178:179], off
	v_lshl_add_u64 v[178:179], s[22:23], 0, v[134:135]
	s_mov_b32 m0, s37
	s_nop 0
	global_load_lds_dwordx4 v[178:179], off
	s_waitcnt vmcnt(8)
	s_waitcnt lgkmcnt(0)
	s_barrier
	s_setprio 1
	s_waitcnt lgkmcnt(0)
	v_mfma_f32_16x16x32_bf16 v[62:65], v[146:149], v[190:193], v[62:65]
	v_mfma_f32_16x16x32_bf16 v[58:61], v[162:165], v[190:193], v[58:61]
	v_mfma_f32_16x16x32_bf16 v[46:49], v[146:149], v[198:201], v[46:49]
	v_mfma_f32_16x16x32_bf16 v[42:45], v[162:165], v[198:201], v[42:45]
	v_mfma_f32_16x16x32_bf16 v[30:33], v[146:149], v[206:209], v[30:33]
	v_mfma_f32_16x16x32_bf16 v[26:29], v[162:165], v[206:209], v[26:29]
	v_mfma_f32_16x16x32_bf16 v[14:17], v[146:149], v[214:217], v[14:17]
	v_mfma_f32_16x16x32_bf16 v[10:13], v[162:165], v[214:217], v[10:13]
	v_mfma_f32_16x16x32_bf16 v[62:65], v[158:161], v[194:197], v[62:65]
	v_mfma_f32_16x16x32_bf16 v[58:61], v[166:169], v[194:197], v[58:61]
	v_mfma_f32_16x16x32_bf16 v[46:49], v[158:161], v[202:205], v[46:49]
	v_mfma_f32_16x16x32_bf16 v[42:45], v[166:169], v[202:205], v[42:45]
	v_mfma_f32_16x16x32_bf16 v[30:33], v[158:161], v[210:213], v[30:33]
	v_mfma_f32_16x16x32_bf16 v[26:29], v[166:169], v[210:213], v[26:29]
	v_mfma_f32_16x16x32_bf16 v[14:17], v[158:161], v[218:221], v[14:17]
	v_mfma_f32_16x16x32_bf16 v[10:13], v[166:169], v[218:221], v[10:13]
	s_setprio 0
	s_setprio 1
	v_mfma_f32_16x16x32_bf16 v[54:57], v[170:173], v[190:193], v[54:57]
	v_mfma_f32_16x16x32_bf16 v[50:53], v[182:185], v[190:193], v[50:53]
	v_mfma_f32_16x16x32_bf16 v[38:41], v[170:173], v[198:201], v[38:41]
	v_mfma_f32_16x16x32_bf16 v[34:37], v[182:185], v[198:201], v[34:37]
	v_mfma_f32_16x16x32_bf16 v[22:25], v[170:173], v[206:209], v[22:25]
	v_mfma_f32_16x16x32_bf16 v[18:21], v[182:185], v[206:209], v[18:21]
	v_mfma_f32_16x16x32_bf16 v[6:9], v[170:173], v[214:217], v[6:9]
	v_mfma_f32_16x16x32_bf16 v[2:5], v[182:185], v[214:217], v[2:5]
	v_mfma_f32_16x16x32_bf16 v[54:57], v[174:177], v[194:197], v[54:57]
	v_mfma_f32_16x16x32_bf16 v[50:53], v[186:189], v[194:197], v[50:53]
	v_mfma_f32_16x16x32_bf16 v[38:41], v[174:177], v[202:205], v[38:41]
	v_mfma_f32_16x16x32_bf16 v[34:37], v[186:189], v[202:205], v[34:37]
	v_mfma_f32_16x16x32_bf16 v[22:25], v[174:177], v[210:213], v[22:25]
	v_mfma_f32_16x16x32_bf16 v[18:21], v[186:189], v[210:213], v[18:21]
	v_mfma_f32_16x16x32_bf16 v[6:9], v[174:177], v[218:221], v[6:9]
	v_mfma_f32_16x16x32_bf16 v[2:5], v[186:189], v[218:221], v[2:5]
	s_setprio 0
	s_barrier
	s_add_i32 s53, s53, 2
	s_add_u32 s20, s20, 0x10000
	s_addc_u32 s21, s21, 0
	s_add_u32 s49, s49, 0x100
	s_addc_u32 s52, s52, 0

.LBB0_1358:
	ds_read_b128 v[160:163], v156
	ds_read_b128 v[164:167], v156 offset:1024
	ds_read_b128 v[168:171], v156 offset:2048
	ds_read_b128 v[172:175], v156 offset:3072
	ds_read_b128 v[176:179], v157
	ds_read_b128 v[182:185], v157 offset:1024
	ds_read_b128 v[186:189], v157 offset:2048
	ds_read_b128 v[190:193], v157 offset:3072
	s_add_i32 s55, s56, 1
	s_mul_i32 s2, s55, s47
	s_mul_hi_u32 s3, s55, s48
	s_add_i32 s3, s3, s2
	s_mul_i32 s2, s55, s48
	s_add_u32 s18, s2, s96
	s_addc_u32 s19, s3, s34
	v_cmp_gt_i64_e32 vcc, s[18:19], v[142:143]
	v_cmp_lt_i64_e64 s[2:3], s[18:19], v[140:141]
	s_cbranch_vccnz .LBB0_1360
	s_ashr_i32 s6, s18, 31
	s_lshr_b32 s6, s6, 29
	s_add_i32 s6, s18, s6
	s_ashr_i32 s7, s6, 3
	s_and_b32 s6, s6, -8
	s_sub_i32 s6, s18, s6
	s_cmp_lt_i32 s6, 0
	s_cselect_b32 s16, s49, 0x2c0
	s_mul_i32 s6, s6, s16
	s_add_i32 s6, s6, s7
	s_mul_hi_i32 s7, s6, 0x2e8ba2e9
	s_lshr_b32 s16, s7, 31
	s_ashr_i32 s7, s7, 5
	s_add_i32 s7, s7, s16
	s_lshl_b32 s16, s7, 3
	s_mulk_i32 s7, 0xb0
	s_sub_i32 s7, s6, s7
	s_ashr_i32 s6, s7, 3
	s_and_b32 s7, s7, 7
	s_add_i32 s16, s16, s7
.LBB0_1360:
	s_ashr_i32 s17, s16, 31
	s_lshl_b64 s[18:19], s[16:17], 19
	s_add_u32 s18, s92, s18
	s_addc_u32 s19, s93, s19
	s_and_b64 s[20:21], s[2:3], exec
	s_cselect_b32 s17, s19, s27
	s_cselect_b32 s57, s18, s26
	s_ashr_i32 s7, s6, 31
	s_lshl_b64 s[20:21], s[6:7], 19
	s_add_u32 s20, s35, s20
	s_addc_u32 s21, s36, s21
	s_and_b64 s[30:31], s[2:3], exec
	s_cselect_b32 s7, s21, s29
	s_cselect_b32 s58, s20, s28
	s_add_u32 s26, s26, 0x40080
	s_addc_u32 s27, s27, 0
	s_add_u32 s59, s28, 0x100

	s_addc_u32 s60, s29, 0
	s_mov_b32 s61, -2


	s_add_u32 s28, s26, 0xfffc0080
	s_addc_u32 s29, s27, -1
	s_cmp_eq_u32 s61, 12
	s_cselect_b32 s31, s17, s29
	s_cselect_b32 s30, s57, s28
	s_cselect_b32 s29, s7, s60
	s_cselect_b32 s28, s58, s59
	v_lshl_add_u64 v[226:227], s[26:27], 0, v[136:137]
	s_add_i32 m0, s25, 0xc000
	ds_read_b128 v[194:197], v158
	ds_read_b128 v[198:201], v158 offset:1024
	ds_read_b128 v[202:205], v158 offset:2048
	ds_read_b128 v[206:209], v158 offset:3072
	ds_read_b128 v[210:213], v158 offset:4096
	ds_read_b128 v[214:217], v158 offset:5120
	ds_read_b128 v[218:221], v158 offset:6144
	ds_read_b128 v[222:225], v158 offset:7168
	global_load_lds_dwordx4 v[226:227], off
	v_lshl_add_u64 v[226:227], s[26:27], 0, v[138:139]
	s_add_i32 m0, s25, 0xe000
	s_nop 0
	global_load_lds_dwordx4 v[226:227], off
	s_waitcnt vmcnt(8)
	s_waitcnt lgkmcnt(0)
	s_barrier
	s_setprio 1
	s_waitcnt lgkmcnt(0)
	v_mfma_f32_16x16x32_bf16 v[126:129], v[160:163], v[194:197], 0
	v_mfma_f32_16x16x32_bf16 v[118:121], v[168:171], v[194:197], 0
	v_mfma_f32_16x16x32_bf16 v[110:113], v[160:163], v[202:205], 0
	v_mfma_f32_16x16x32_bf16 v[102:105], v[168:171], v[202:205], 0
	v_mfma_f32_16x16x32_bf16 v[94:97], v[160:163], v[210:213], 0
	v_mfma_f32_16x16x32_bf16 v[86:89], v[168:171], v[210:213], 0
	v_mfma_f32_16x16x32_bf16 v[78:81], v[160:163], v[218:221], 0
	v_mfma_f32_16x16x32_bf16 v[70:73], v[168:171], v[218:221], 0
	v_mfma_f32_16x16x32_bf16 v[126:129], v[164:167], v[198:201], v[126:129]
	v_mfma_f32_16x16x32_bf16 v[118:121], v[172:175], v[198:201], v[118:121]
	v_mfma_f32_16x16x32_bf16 v[110:113], v[164:167], v[206:209], v[110:113]
	v_mfma_f32_16x16x32_bf16 v[102:105], v[172:175], v[206:209], v[102:105]
	v_mfma_f32_16x16x32_bf16 v[94:97], v[164:167], v[214:217], v[94:97]
	v_mfma_f32_16x16x32_bf16 v[86:89], v[172:175], v[214:217], v[86:89]
	v_mfma_f32_16x16x32_bf16 v[78:81], v[164:167], v[222:225], v[78:81]
	v_mfma_f32_16x16x32_bf16 v[70:73], v[172:175], v[222:225], v[70:73]
	s_setprio 0
	s_setprio 1
	v_mfma_f32_16x16x32_bf16 v[122:125], v[176:179], v[194:197], 0
	v_mfma_f32_16x16x32_bf16 v[114:117], v[186:189], v[194:197], 0
	v_mfma_f32_16x16x32_bf16 v[106:109], v[176:179], v[202:205], 0
	v_mfma_f32_16x16x32_bf16 v[98:101], v[186:189], v[202:205], 0
	v_mfma_f32_16x16x32_bf16 v[90:93], v[176:179], v[210:213], 0
	v_mfma_f32_16x16x32_bf16 v[82:85], v[186:189], v[210:213], 0
	v_mfma_f32_16x16x32_bf16 v[74:77], v[176:179], v[218:221], 0
	v_mfma_f32_16x16x32_bf16 v[66:69], v[186:189], v[218:221], 0
	v_mfma_f32_16x16x32_bf16 v[122:125], v[182:185], v[198:201], v[122:125]
	v_mfma_f32_16x16x32_bf16 v[114:117], v[190:193], v[198:201], v[114:117]
	v_mfma_f32_16x16x32_bf16 v[106:109], v[182:185], v[206:209], v[106:109]
	v_mfma_f32_16x16x32_bf16 v[98:101], v[190:193], v[206:209], v[98:101]
	v_mfma_f32_16x16x32_bf16 v[90:93], v[182:185], v[214:217], v[90:93]
	v_mfma_f32_16x16x32_bf16 v[82:85], v[190:193], v[214:217], v[82:85]
	v_mfma_f32_16x16x32_bf16 v[74:77], v[182:185], v[222:225], v[74:77]
	v_mfma_f32_16x16x32_bf16 v[66:69], v[190:193], v[222:225], v[66:69]
	s_setprio 0
	s_barrier
	s_add_i32 s33, s52, s23
	v_lshl_add_u64 v[226:227], s[28:29], 0, v[148:149]
	s_mov_b32 m0, s33
	ds_read_b128 v[194:197], v158 offset:16384
	ds_read_b128 v[198:201], v158 offset:17408
	ds_read_b128 v[202:205], v158 offset:18432
	ds_read_b128 v[206:209], v158 offset:19456
	ds_read_b128 v[210:213], v158 offset:20480
	ds_read_b128 v[214:217], v158 offset:21504
	ds_read_b128 v[218:221], v158 offset:22528
	ds_read_b128 v[222:225], v158 offset:23552
	global_load_lds_dwordx4 v[226:227], off
	s_add_i32 m0, s33, 0x2000
	s_add_u32 s62, s28, 0x40000
	v_lshl_add_u64 v[228:229], s[28:29], 0, v[152:153]
	s_addc_u32 s63, s29, 0
	s_add_i32 s33, s53, s23
	global_load_lds_dwordx4 v[228:229], off
	v_lshl_add_u64 v[230:231], s[62:63], 0, v[148:149]
	s_mov_b32 m0, s33
	v_lshl_add_u64 v[232:233], s[30:31], 0, v[150:151]
	global_load_lds_dwordx4 v[230:231], off
	v_lshl_add_u64 v[230:231], s[62:63], 0, v[152:153]
	s_add_i32 m0, s33, 0x2000
	s_nop 0
	global_load_lds_dwordx4 v[230:231], off
	v_lshl_add_u64 v[230:231], s[30:31], 0, v[146:147]
	s_mov_b32 m0, s25
	s_nop 0
	global_load_lds_dwordx4 v[230:231], off
	s_mov_b32 m0, s37
	s_nop 0
	global_load_lds_dwordx4 v[232:233], off
	s_waitcnt vmcnt(8)
	s_waitcnt lgkmcnt(0)
	s_barrier
	s_setprio 1
	s_waitcnt lgkmcnt(0)
	v_mfma_f32_16x16x32_bf16 v[62:65], v[160:163], v[194:197], 0
	v_mfma_f32_16x16x32_bf16 v[54:57], v[168:171], v[194:197], 0
	v_mfma_f32_16x16x32_bf16 v[46:49], v[160:163], v[202:205], 0
	v_mfma_f32_16x16x32_bf16 v[38:41], v[168:171], v[202:205], 0
	v_mfma_f32_16x16x32_bf16 v[30:33], v[160:163], v[210:213], 0
	v_mfma_f32_16x16x32_bf16 v[22:25], v[168:171], v[210:213], 0
	v_mfma_f32_16x16x32_bf16 v[14:17], v[160:163], v[218:221], 0
	v_mfma_f32_16x16x32_bf16 v[6:9], v[168:171], v[218:221], 0
	v_mfma_f32_16x16x32_bf16 v[62:65], v[164:167], v[198:201], v[62:65]
	v_mfma_f32_16x16x32_bf16 v[54:57], v[172:175], v[198:201], v[54:57]
	v_mfma_f32_16x16x32_bf16 v[46:49], v[164:167], v[206:209], v[46:49]
	v_mfma_f32_16x16x32_bf16 v[38:41], v[172:175], v[206:209], v[38:41]
	v_mfma_f32_16x16x32_bf16 v[30:33], v[164:167], v[214:217], v[30:33]
	v_mfma_f32_16x16x32_bf16 v[22:25], v[172:175], v[214:217], v[22:25]
	v_mfma_f32_16x16x32_bf16 v[14:17], v[164:167], v[222:225], v[14:17]
	v_mfma_f32_16x16x32_bf16 v[6:9], v[172:175], v[222:225], v[6:9]
	s_setprio 0
	s_setprio 1
	v_mfma_f32_16x16x32_bf16 v[58:61], v[176:179], v[194:197], 0
	v_mfma_f32_16x16x32_bf16 v[50:53], v[186:189], v[194:197], 0
	v_mfma_f32_16x16x32_bf16 v[42:45], v[176:179], v[202:205], 0
	v_mfma_f32_16x16x32_bf16 v[34:37], v[186:189], v[202:205], 0
	v_mfma_f32_16x16x32_bf16 v[26:29], v[176:179], v[210:213], 0
	v_mfma_f32_16x16x32_bf16 v[18:21], v[186:189], v[210:213], 0
	v_mfma_f32_16x16x32_bf16 v[10:13], v[176:179], v[218:221], 0
	v_mfma_f32_16x16x32_bf16 v[2:5], v[186:189], v[218:221], 0
	v_mfma_f32_16x16x32_bf16 v[58:61], v[182:185], v[198:201], v[58:61]
	v_mfma_f32_16x16x32_bf16 v[50:53], v[190:193], v[198:201], v[50:53]
	v_mfma_f32_16x16x32_bf16 v[42:45], v[182:185], v[206:209], v[42:45]
	v_mfma_f32_16x16x32_bf16 v[34:37], v[190:193], v[206:209], v[34:37]
	v_mfma_f32_16x16x32_bf16 v[26:29], v[182:185], v[214:217], v[26:29]
	v_mfma_f32_16x16x32_bf16 v[18:21], v[190:193], v[214:217], v[18:21]
	v_mfma_f32_16x16x32_bf16 v[10:13], v[182:185], v[222:225], v[10:13]
	v_mfma_f32_16x16x32_bf16 v[2:5], v[190:193], v[222:225], v[2:5]
	s_setprio 0
	s_barrier
	s_add_i32 s33, 0, 0x18000
	v_add_u32_e32 v130, s33, v154
	s_add_i32 s51, 0, 0x1c000
	ds_read_b128 v[160:163], v130
	ds_read_b128 v[164:167], v130 offset:1024
	ds_read_b128 v[168:171], v130 offset:2048
	ds_read_b128 v[172:175], v130 offset:3072
	v_add_u32_e32 v130, s51, v154
	ds_read_b128 v[176:179], v130
	ds_read_b128 v[182:185], v130 offset:1024
	ds_read_b128 v[186:189], v130 offset:2048
	ds_read_b128 v[190:193], v130 offset:3072
	s_add_u32 s30, s30, 0x40000
	s_addc_u32 s31, s31, 0
	s_mov_b32 m0, s38
	v_lshl_add_u64 v[234:235], s[30:31], 0, v[146:147]
	ds_read_b128 v[194:197], v158 offset:32768
	ds_read_b128 v[198:201], v158 offset:33792
	ds_read_b128 v[202:205], v158 offset:34816
	ds_read_b128 v[206:209], v158 offset:35840
	ds_read_b128 v[210:213], v158 offset:36864
	ds_read_b128 v[214:217], v158 offset:37888
	ds_read_b128 v[218:221], v158 offset:38912
	ds_read_b128 v[222:225], v158 offset:39936
	global_load_lds_dwordx4 v[234:235], off
	v_lshl_add_u64 v[234:235], s[30:31], 0, v[150:151]
	s_mov_b32 m0, s39
	s_nop 0
	global_load_lds_dwordx4 v[234:235], off
	s_waitcnt vmcnt(8)
	s_waitcnt lgkmcnt(0)
	s_barrier
	s_setprio 1
	s_waitcnt lgkmcnt(0)
	v_mfma_f32_16x16x32_bf16 v[126:129], v[160:163], v[194:197], v[126:129]
	v_mfma_f32_16x16x32_bf16 v[118:121], v[168:171], v[194:197], v[118:121]
	v_mfma_f32_16x16x32_bf16 v[110:113], v[160:163], v[202:205], v[110:113]
	v_mfma_f32_16x16x32_bf16 v[102:105], v[168:171], v[202:205], v[102:105]
	v_mfma_f32_16x16x32_bf16 v[94:97], v[160:163], v[210:213], v[94:97]
	v_mfma_f32_16x16x32_bf16 v[86:89], v[168:171], v[210:213], v[86:89]
	v_mfma_f32_16x16x32_bf16 v[78:81], v[160:163], v[218:221], v[78:81]
	v_mfma_f32_16x16x32_bf16 v[70:73], v[168:171], v[218:221], v[70:73]
	v_mfma_f32_16x16x32_bf16 v[126:129], v[164:167], v[198:201], v[126:129]
	v_mfma_f32_16x16x32_bf16 v[118:121], v[172:175], v[198:201], v[118:121]
	v_mfma_f32_16x16x32_bf16 v[110:113], v[164:167], v[206:209], v[110:113]
	v_mfma_f32_16x16x32_bf16 v[102:105], v[172:175], v[206:209], v[102:105]
	v_mfma_f32_16x16x32_bf16 v[94:97], v[164:167], v[214:217], v[94:97]
	v_mfma_f32_16x16x32_bf16 v[86:89], v[172:175], v[214:217], v[86:89]
	v_mfma_f32_16x16x32_bf16 v[78:81], v[164:167], v[222:225], v[78:81]
	v_mfma_f32_16x16x32_bf16 v[70:73], v[172:175], v[222:225], v[70:73]
	s_setprio 0
	s_setprio 1
	v_mfma_f32_16x16x32_bf16 v[122:125], v[176:179], v[194:197], v[122:125]
	v_mfma_f32_16x16x32_bf16 v[114:117], v[186:189], v[194:197], v[114:117]
	v_mfma_f32_16x16x32_bf16 v[106:109], v[176:179], v[202:205], v[106:109]
	v_mfma_f32_16x16x32_bf16 v[98:101], v[186:189], v[202:205], v[98:101]
	v_mfma_f32_16x16x32_bf16 v[90:93], v[176:179], v[210:213], v[90:93]
	v_mfma_f32_16x16x32_bf16 v[82:85], v[186:189], v[210:213], v[82:85]
	v_mfma_f32_16x16x32_bf16 v[74:77], v[176:179], v[218:221], v[74:77]
	v_mfma_f32_16x16x32_bf16 v[66:69], v[186:189], v[218:221], v[66:69]
	v_mfma_f32_16x16x32_bf16 v[122:125], v[182:185], v[198:201], v[122:125]
	v_mfma_f32_16x16x32_bf16 v[114:117], v[190:193], v[198:201], v[114:117]
	v_mfma_f32_16x16x32_bf16 v[106:109], v[182:185], v[206:209], v[106:109]
	v_mfma_f32_16x16x32_bf16 v[98:101], v[190:193], v[206:209], v[98:101]
	v_mfma_f32_16x16x32_bf16 v[90:93], v[182:185], v[214:217], v[90:93]
	v_mfma_f32_16x16x32_bf16 v[82:85], v[190:193], v[214:217], v[82:85]
	v_mfma_f32_16x16x32_bf16 v[74:77], v[182:185], v[222:225], v[74:77]
	v_mfma_f32_16x16x32_bf16 v[66:69], v[190:193], v[222:225], v[66:69]
	s_setprio 0
	s_barrier
	s_add_i32 s30, s33, s23
	v_lshl_add_u64 v[226:227], v[226:227], 0, s[14:15]
	s_mov_b32 m0, s30
	ds_read_b128 v[194:197], v158 offset:49152
	ds_read_b128 v[198:201], v158 offset:50176
	ds_read_b128 v[202:205], v158 offset:51200
	ds_read_b128 v[206:209], v158 offset:52224
	ds_read_b128 v[210:213], v158 offset:53248
	ds_read_b128 v[214:217], v158 offset:54272
	ds_read_b128 v[218:221], v158 offset:55296
	ds_read_b128 v[222:225], v158 offset:56320
	global_load_lds_dwordx4 v[226:227], off
	s_add_i32 m0, s30, 0x2000
	s_add_u32 s28, s28, 0x40080
	v_lshl_add_u64 v[226:227], v[228:229], 0, s[14:15]
	s_addc_u32 s29, s29, 0
	s_add_i32 s30, s51, s23
	global_load_lds_dwordx4 v[226:227], off
	v_lshl_add_u64 v[226:227], s[28:29], 0, v[148:149]
	s_mov_b32 m0, s30
	s_nop 0
	global_load_lds_dwordx4 v[226:227], off
	v_lshl_add_u64 v[226:227], s[28:29], 0, v[152:153]
	s_add_i32 m0, s30, 0x2000
	s_nop 0
	global_load_lds_dwordx4 v[226:227], off
	v_lshl_add_u64 v[226:227], v[230:231], 0, s[14:15]
	s_mov_b32 m0, s42
	s_nop 0
	global_load_lds_dwordx4 v[226:227], off
	v_lshl_add_u64 v[226:227], v[232:233], 0, s[14:15]
	s_mov_b32 m0, s43
	s_nop 0
	global_load_lds_dwordx4 v[226:227], off
	s_waitcnt vmcnt(8)
	s_waitcnt lgkmcnt(0)
	s_barrier
	s_setprio 1
	s_waitcnt lgkmcnt(0)
	v_mfma_f32_16x16x32_bf16 v[62:65], v[160:163], v[194:197], v[62:65]
	v_mfma_f32_16x16x32_bf16 v[54:57], v[168:171], v[194:197], v[54:57]
	v_mfma_f32_16x16x32_bf16 v[46:49], v[160:163], v[202:205], v[46:49]
	v_mfma_f32_16x16x32_bf16 v[38:41], v[168:171], v[202:205], v[38:41]
	v_mfma_f32_16x16x32_bf16 v[30:33], v[160:163], v[210:213], v[30:33]
	v_mfma_f32_16x16x32_bf16 v[22:25], v[168:171], v[210:213], v[22:25]
	v_mfma_f32_16x16x32_bf16 v[14:17], v[160:163], v[218:221], v[14:17]
	v_mfma_f32_16x16x32_bf16 v[6:9], v[168:171], v[218:221], v[6:9]
	v_mfma_f32_16x16x32_bf16 v[62:65], v[164:167], v[198:201], v[62:65]
	v_mfma_f32_16x16x32_bf16 v[54:57], v[172:175], v[198:201], v[54:57]
	v_mfma_f32_16x16x32_bf16 v[46:49], v[164:167], v[206:209], v[46:49]
	v_mfma_f32_16x16x32_bf16 v[38:41], v[172:175], v[206:209], v[38:41]
	v_mfma_f32_16x16x32_bf16 v[30:33], v[164:167], v[214:217], v[30:33]
	v_mfma_f32_16x16x32_bf16 v[22:25], v[172:175], v[214:217], v[22:25]
	v_mfma_f32_16x16x32_bf16 v[14:17], v[164:167], v[222:225], v[14:17]
	v_mfma_f32_16x16x32_bf16 v[6:9], v[172:175], v[222:225], v[6:9]
	s_setprio 0
	s_setprio 1
	v_mfma_f32_16x16x32_bf16 v[58:61], v[176:179], v[194:197], v[58:61]
	v_mfma_f32_16x16x32_bf16 v[50:53], v[186:189], v[194:197], v[50:53]
	v_mfma_f32_16x16x32_bf16 v[42:45], v[176:179], v[202:205], v[42:45]
	v_mfma_f32_16x16x32_bf16 v[34:37], v[186:189], v[202:205], v[34:37]
	v_mfma_f32_16x16x32_bf16 v[26:29], v[176:179], v[210:213], v[26:29]
	v_mfma_f32_16x16x32_bf16 v[18:21], v[186:189], v[210:213], v[18:21]
	v_mfma_f32_16x16x32_bf16 v[10:13], v[176:179], v[218:221], v[10:13]
	v_mfma_f32_16x16x32_bf16 v[2:5], v[186:189], v[218:221], v[2:5]
	v_mfma_f32_16x16x32_bf16 v[58:61], v[182:185], v[198:201], v[58:61]
	v_mfma_f32_16x16x32_bf16 v[50:53], v[190:193], v[198:201], v[50:53]
	v_mfma_f32_16x16x32_bf16 v[42:45], v[182:185], v[206:209], v[42:45]
	v_mfma_f32_16x16x32_bf16 v[34:37], v[190:193], v[206:209], v[34:37]
	v_mfma_f32_16x16x32_bf16 v[26:29], v[182:185], v[214:217], v[26:29]
	v_mfma_f32_16x16x32_bf16 v[18:21], v[190:193], v[214:217], v[18:21]
	v_mfma_f32_16x16x32_bf16 v[10:13], v[182:185], v[222:225], v[10:13]
	v_mfma_f32_16x16x32_bf16 v[2:5], v[190:193], v[222:225], v[2:5]
	s_setprio 0
	s_barrier
	s_add_i32 s61, s61, 2
	s_add_u32 s26, s26, 0x100
	s_addc_u32 s27, s27, 0
	s_add_u32 s59, s59, 0x100
	s_addc_u32 s60, s60, 0

.LBB0_1451:
	ds_read_b128 v[146:149], v152
	ds_read_b128 v[156:159], v152 offset:1024
	ds_read_b128 v[160:163], v152 offset:2048
	ds_read_b128 v[164:167], v152 offset:3072
	ds_read_b128 v[168:171], v153
	ds_read_b128 v[172:175], v153 offset:1024
	ds_read_b128 v[176:179], v153 offset:2048
	ds_read_b128 v[182:185], v153 offset:3072
	s_add_i32 s39, s39, 1
	s_mul_i32 s4, s39, s42
	s_mul_hi_u32 s5, s39, s43
	s_add_i32 s5, s5, s4
	s_mul_i32 s4, s39, s43
	s_add_u32 s4, s4, s96
	s_addc_u32 s5, s5, s46
	v_cmp_gt_i64_e32 vcc, s[4:5], v[144:145]
	v_cmp_lt_i64_e64 s[6:7], s[4:5], v[142:143]
	s_cbranch_vccnz .LBB0_1457
	s_ashr_i32 s5, s4, 31
	s_lshr_b32 s5, s5, 29
	s_add_i32 s20, s4, s5
	s_and_b32 s5, s20, -8
	s_sub_i32 s21, s4, s5
	s_cmp_gt_i32 s21, -1
	s_mov_b64 s[4:5], -1
	s_cbranch_scc0 .LBB0_1454
	s_lshl_b32 s26, s21, 7
	s_mov_b64 s[4:5], 0

.LBB0_1461:
	s_add_u32 s22, s22, 0xc000
	s_addc_u32 s23, s23, 0
	s_add_u32 s55, s24, 0x100

	s_addc_u32 s56, s25, 0
	s_mov_b32 s57, -2
	s_waitcnt lgkmcnt(0)


	s_add_u32 s24, s22, 0x4000
	s_addc_u32 s25, s23, 0
	s_cmp_eq_u32 s57, 40
	s_cselect_b32 s28, s6, s24
	s_cselect_b32 s29, s7, s25
	s_cselect_b32 s26, s20, s55
	s_cselect_b32 s27, s21, s56
	s_add_u32 s24, s28, 0x8000
	s_addc_u32 s25, s29, 0
	v_lshl_add_u64 v[218:219], s[22:23], 0, v[138:139]
	s_add_i32 m0, s35, 0xc000
	ds_read_b128 v[186:189], v154
	ds_read_b128 v[190:193], v154 offset:1024
	ds_read_b128 v[194:197], v154 offset:2048
	ds_read_b128 v[198:201], v154 offset:3072
	ds_read_b128 v[202:205], v154 offset:4096
	ds_read_b128 v[206:209], v154 offset:5120
	ds_read_b128 v[210:213], v154 offset:6144
	ds_read_b128 v[214:217], v154 offset:7168
	global_load_lds_dwordx4 v[218:219], off
	v_lshl_add_u64 v[218:219], s[22:23], 0, v[140:141]
	s_add_i32 m0, s35, 0xe000
	s_nop 0
	global_load_lds_dwordx4 v[218:219], off
	s_waitcnt vmcnt(8)
	s_waitcnt lgkmcnt(0)
	s_barrier
	s_setprio 1
	s_waitcnt lgkmcnt(0)
	v_mfma_f32_16x16x32_bf16 v[126:129], v[146:149], v[186:189], 0
	v_mfma_f32_16x16x32_bf16 v[122:125], v[160:163], v[186:189], 0
	v_mfma_f32_16x16x32_bf16 v[110:113], v[146:149], v[194:197], 0
	v_mfma_f32_16x16x32_bf16 v[106:109], v[160:163], v[194:197], 0
	v_mfma_f32_16x16x32_bf16 v[94:97], v[146:149], v[202:205], 0
	v_mfma_f32_16x16x32_bf16 v[90:93], v[160:163], v[202:205], 0
	v_mfma_f32_16x16x32_bf16 v[78:81], v[146:149], v[210:213], 0
	v_mfma_f32_16x16x32_bf16 v[74:77], v[160:163], v[210:213], 0
	v_mfma_f32_16x16x32_bf16 v[126:129], v[156:159], v[190:193], v[126:129]
	v_mfma_f32_16x16x32_bf16 v[122:125], v[164:167], v[190:193], v[122:125]
	v_mfma_f32_16x16x32_bf16 v[110:113], v[156:159], v[198:201], v[110:113]
	v_mfma_f32_16x16x32_bf16 v[106:109], v[164:167], v[198:201], v[106:109]
	v_mfma_f32_16x16x32_bf16 v[94:97], v[156:159], v[206:209], v[94:97]
	v_mfma_f32_16x16x32_bf16 v[90:93], v[164:167], v[206:209], v[90:93]
	v_mfma_f32_16x16x32_bf16 v[78:81], v[156:159], v[214:217], v[78:81]
	v_mfma_f32_16x16x32_bf16 v[74:77], v[164:167], v[214:217], v[74:77]
	s_setprio 0
	s_setprio 1
	v_mfma_f32_16x16x32_bf16 v[118:121], v[168:171], v[186:189], 0
	v_mfma_f32_16x16x32_bf16 v[114:117], v[176:179], v[186:189], 0
	v_mfma_f32_16x16x32_bf16 v[102:105], v[168:171], v[194:197], 0
	v_mfma_f32_16x16x32_bf16 v[98:101], v[176:179], v[194:197], 0
	v_mfma_f32_16x16x32_bf16 v[86:89], v[168:171], v[202:205], 0
	v_mfma_f32_16x16x32_bf16 v[82:85], v[176:179], v[202:205], 0
	v_mfma_f32_16x16x32_bf16 v[70:73], v[168:171], v[210:213], 0
	v_mfma_f32_16x16x32_bf16 v[66:69], v[176:179], v[210:213], 0
	v_mfma_f32_16x16x32_bf16 v[118:121], v[172:175], v[190:193], v[118:121]
	v_mfma_f32_16x16x32_bf16 v[114:117], v[182:185], v[190:193], v[114:117]
	v_mfma_f32_16x16x32_bf16 v[102:105], v[172:175], v[198:201], v[102:105]
	v_mfma_f32_16x16x32_bf16 v[98:101], v[182:185], v[198:201], v[98:101]
	v_mfma_f32_16x16x32_bf16 v[86:89], v[172:175], v[206:209], v[86:89]
	v_mfma_f32_16x16x32_bf16 v[82:85], v[182:185], v[206:209], v[82:85]
	v_mfma_f32_16x16x32_bf16 v[70:73], v[172:175], v[214:217], v[70:73]
	v_mfma_f32_16x16x32_bf16 v[66:69], v[182:185], v[214:217], v[66:69]
	s_setprio 0
	s_barrier
	s_add_i32 s33, s47, s34
	v_lshl_add_u64 v[218:219], s[26:27], 0, v[132:133]
	s_mov_b32 m0, s33
	ds_read_b128 v[186:189], v154 offset:16384
	ds_read_b128 v[190:193], v154 offset:17408
	ds_read_b128 v[194:197], v154 offset:18432
	ds_read_b128 v[198:201], v154 offset:19456
	ds_read_b128 v[202:205], v154 offset:20480
	ds_read_b128 v[206:209], v154 offset:21504
	ds_read_b128 v[210:213], v154 offset:22528
	ds_read_b128 v[214:217], v154 offset:23552
	global_load_lds_dwordx4 v[218:219], off
	s_add_i32 m0, s33, 0x2000
	s_add_u32 s58, s26, 0xb0000
	v_lshl_add_u64 v[220:221], s[26:27], 0, v[136:137]
	s_addc_u32 s59, s27, 0
	s_add_i32 s33, s48, s34
	global_load_lds_dwordx4 v[220:221], off
	v_lshl_add_u64 v[222:223], s[58:59], 0, v[132:133]
	s_mov_b32 m0, s33
	s_nop 0
	global_load_lds_dwordx4 v[222:223], off
	v_lshl_add_u64 v[222:223], s[58:59], 0, v[136:137]
	s_add_i32 m0, s33, 0x2000
	s_nop 0
	global_load_lds_dwordx4 v[222:223], off
	v_lshl_add_u64 v[222:223], s[28:29], 0, v[130:131]
	s_mov_b32 m0, s35
	s_nop 0
	global_load_lds_dwordx4 v[222:223], off
	v_lshl_add_u64 v[222:223], s[28:29], 0, v[134:135]
	s_mov_b32 m0, s36
	s_nop 0
	global_load_lds_dwordx4 v[222:223], off
	s_waitcnt vmcnt(8)
	s_waitcnt lgkmcnt(0)
	s_barrier
	s_setprio 1
	s_waitcnt lgkmcnt(0)
	v_mfma_f32_16x16x32_bf16 v[62:65], v[146:149], v[186:189], 0
	v_mfma_f32_16x16x32_bf16 v[58:61], v[160:163], v[186:189], 0
	v_mfma_f32_16x16x32_bf16 v[46:49], v[146:149], v[194:197], 0
	v_mfma_f32_16x16x32_bf16 v[42:45], v[160:163], v[194:197], 0
	v_mfma_f32_16x16x32_bf16 v[30:33], v[146:149], v[202:205], 0
	v_mfma_f32_16x16x32_bf16 v[26:29], v[160:163], v[202:205], 0
	v_mfma_f32_16x16x32_bf16 v[14:17], v[146:149], v[210:213], 0
	v_mfma_f32_16x16x32_bf16 v[10:13], v[160:163], v[210:213], 0
	v_mfma_f32_16x16x32_bf16 v[62:65], v[156:159], v[190:193], v[62:65]
	v_mfma_f32_16x16x32_bf16 v[58:61], v[164:167], v[190:193], v[58:61]
	v_mfma_f32_16x16x32_bf16 v[46:49], v[156:159], v[198:201], v[46:49]
	v_mfma_f32_16x16x32_bf16 v[42:45], v[164:167], v[198:201], v[42:45]
	v_mfma_f32_16x16x32_bf16 v[30:33], v[156:159], v[206:209], v[30:33]
	v_mfma_f32_16x16x32_bf16 v[26:29], v[164:167], v[206:209], v[26:29]
	v_mfma_f32_16x16x32_bf16 v[14:17], v[156:159], v[214:217], v[14:17]
	v_mfma_f32_16x16x32_bf16 v[10:13], v[164:167], v[214:217], v[10:13]
	s_setprio 0
	s_setprio 1
	v_mfma_f32_16x16x32_bf16 v[54:57], v[168:171], v[186:189], 0
	v_mfma_f32_16x16x32_bf16 v[50:53], v[176:179], v[186:189], 0
	v_mfma_f32_16x16x32_bf16 v[38:41], v[168:171], v[194:197], 0
	v_mfma_f32_16x16x32_bf16 v[34:37], v[176:179], v[194:197], 0
	v_mfma_f32_16x16x32_bf16 v[22:25], v[168:171], v[202:205], 0
	v_mfma_f32_16x16x32_bf16 v[18:21], v[176:179], v[202:205], 0
	v_mfma_f32_16x16x32_bf16 v[6:9], v[168:171], v[210:213], 0
	v_mfma_f32_16x16x32_bf16 v[2:5], v[176:179], v[210:213], 0
	v_mfma_f32_16x16x32_bf16 v[54:57], v[172:175], v[190:193], v[54:57]
	v_mfma_f32_16x16x32_bf16 v[50:53], v[182:185], v[190:193], v[50:53]
	v_mfma_f32_16x16x32_bf16 v[38:41], v[172:175], v[198:201], v[38:41]
	v_mfma_f32_16x16x32_bf16 v[34:37], v[182:185], v[198:201], v[34:37]
	v_mfma_f32_16x16x32_bf16 v[22:25], v[172:175], v[206:209], v[22:25]
	v_mfma_f32_16x16x32_bf16 v[18:21], v[182:185], v[206:209], v[18:21]
	v_mfma_f32_16x16x32_bf16 v[6:9], v[172:175], v[214:217], v[6:9]
	v_mfma_f32_16x16x32_bf16 v[2:5], v[182:185], v[214:217], v[2:5]
	s_setprio 0
	s_barrier
	s_add_i32 s33, 0, 0x18000
	s_add_i32 s51, 0, 0x1c000
	v_add_u32_e32 v164, s33, v150
	v_add_u32_e32 v182, s51, v150
	ds_read_b128 v[146:149], v164
	ds_read_b128 v[156:159], v164 offset:1024
	ds_read_b128 v[160:163], v164 offset:2048
	ds_read_b128 v[164:167], v164 offset:3072
	ds_read_b128 v[168:171], v182
	ds_read_b128 v[172:175], v182 offset:1024
	ds_read_b128 v[176:179], v182 offset:2048
	ds_read_b128 v[182:185], v182 offset:3072
	s_add_u32 s28, s28, 0x4000
	s_addc_u32 s29, s29, 0
	s_mov_b32 m0, s37
	v_lshl_add_u64 v[222:223], s[28:29], 0, v[130:131]
	ds_read_b128 v[186:189], v154 offset:32768
	ds_read_b128 v[190:193], v154 offset:33792
	ds_read_b128 v[194:197], v154 offset:34816
	ds_read_b128 v[198:201], v154 offset:35840
	ds_read_b128 v[202:205], v154 offset:36864
	ds_read_b128 v[206:209], v154 offset:37888
	ds_read_b128 v[210:213], v154 offset:38912
	ds_read_b128 v[214:217], v154 offset:39936
	global_load_lds_dwordx4 v[222:223], off
	v_lshl_add_u64 v[222:223], s[28:29], 0, v[134:135]
	s_mov_b32 m0, s38
	s_nop 0
	global_load_lds_dwordx4 v[222:223], off
	s_waitcnt vmcnt(8)
	s_waitcnt lgkmcnt(0)
	s_barrier
	s_setprio 1
	s_waitcnt lgkmcnt(0)
	v_mfma_f32_16x16x32_bf16 v[126:129], v[146:149], v[186:189], v[126:129]
	v_mfma_f32_16x16x32_bf16 v[122:125], v[160:163], v[186:189], v[122:125]
	v_mfma_f32_16x16x32_bf16 v[110:113], v[146:149], v[194:197], v[110:113]
	v_mfma_f32_16x16x32_bf16 v[106:109], v[160:163], v[194:197], v[106:109]
	v_mfma_f32_16x16x32_bf16 v[94:97], v[146:149], v[202:205], v[94:97]
	v_mfma_f32_16x16x32_bf16 v[90:93], v[160:163], v[202:205], v[90:93]
	v_mfma_f32_16x16x32_bf16 v[78:81], v[146:149], v[210:213], v[78:81]
	v_mfma_f32_16x16x32_bf16 v[74:77], v[160:163], v[210:213], v[74:77]
	v_mfma_f32_16x16x32_bf16 v[126:129], v[156:159], v[190:193], v[126:129]
	v_mfma_f32_16x16x32_bf16 v[122:125], v[164:167], v[190:193], v[122:125]
	v_mfma_f32_16x16x32_bf16 v[110:113], v[156:159], v[198:201], v[110:113]
	v_mfma_f32_16x16x32_bf16 v[106:109], v[164:167], v[198:201], v[106:109]
	v_mfma_f32_16x16x32_bf16 v[94:97], v[156:159], v[206:209], v[94:97]
	v_mfma_f32_16x16x32_bf16 v[90:93], v[164:167], v[206:209], v[90:93]
	v_mfma_f32_16x16x32_bf16 v[78:81], v[156:159], v[214:217], v[78:81]
	v_mfma_f32_16x16x32_bf16 v[74:77], v[164:167], v[214:217], v[74:77]
	s_setprio 0
	s_setprio 1
	v_mfma_f32_16x16x32_bf16 v[118:121], v[168:171], v[186:189], v[118:121]
	v_mfma_f32_16x16x32_bf16 v[114:117], v[176:179], v[186:189], v[114:117]
	v_mfma_f32_16x16x32_bf16 v[102:105], v[168:171], v[194:197], v[102:105]
	v_mfma_f32_16x16x32_bf16 v[98:101], v[176:179], v[194:197], v[98:101]
	v_mfma_f32_16x16x32_bf16 v[86:89], v[168:171], v[202:205], v[86:89]
	v_mfma_f32_16x16x32_bf16 v[82:85], v[176:179], v[202:205], v[82:85]
	v_mfma_f32_16x16x32_bf16 v[70:73], v[168:171], v[210:213], v[70:73]
	v_mfma_f32_16x16x32_bf16 v[66:69], v[176:179], v[210:213], v[66:69]
	v_mfma_f32_16x16x32_bf16 v[118:121], v[172:175], v[190:193], v[118:121]
	v_mfma_f32_16x16x32_bf16 v[114:117], v[182:185], v[190:193], v[114:117]
	v_mfma_f32_16x16x32_bf16 v[102:105], v[172:175], v[198:201], v[102:105]
	v_mfma_f32_16x16x32_bf16 v[98:101], v[182:185], v[198:201], v[98:101]
	v_mfma_f32_16x16x32_bf16 v[86:89], v[172:175], v[206:209], v[86:89]
	v_mfma_f32_16x16x32_bf16 v[82:85], v[182:185], v[206:209], v[82:85]
	v_mfma_f32_16x16x32_bf16 v[70:73], v[172:175], v[214:217], v[70:73]
	v_mfma_f32_16x16x32_bf16 v[66:69], v[182:185], v[214:217], v[66:69]
	s_setprio 0
	s_barrier
	s_add_i32 s28, s33, s34
	v_lshl_add_u64 v[218:219], v[218:219], 0, s[16:17]
	s_mov_b32 m0, s28
	ds_read_b128 v[186:189], v154 offset:49152
	ds_read_b128 v[190:193], v154 offset:50176
	ds_read_b128 v[194:197], v154 offset:51200
	ds_read_b128 v[198:201], v154 offset:52224
	ds_read_b128 v[202:205], v154 offset:53248
	ds_read_b128 v[206:209], v154 offset:54272
	ds_read_b128 v[210:213], v154 offset:55296
	ds_read_b128 v[214:217], v154 offset:56320
	global_load_lds_dwordx4 v[218:219], off
	s_add_i32 m0, s28, 0x2000
	s_add_u32 s26, s26, 0xb0080
	v_lshl_add_u64 v[218:219], v[220:221], 0, s[16:17]
	s_addc_u32 s27, s27, 0
	s_add_i32 s28, s51, s34
	global_load_lds_dwordx4 v[218:219], off
	v_lshl_add_u64 v[218:219], s[26:27], 0, v[132:133]
	s_mov_b32 m0, s28
	s_nop 0
	global_load_lds_dwordx4 v[218:219], off
	v_lshl_add_u64 v[218:219], s[26:27], 0, v[136:137]
	s_add_i32 m0, s28, 0x2000
	s_nop 0
	global_load_lds_dwordx4 v[218:219], off
	v_lshl_add_u64 v[218:219], s[24:25], 0, v[130:131]
	s_mov_b32 m0, s40
	s_nop 0
	global_load_lds_dwordx4 v[218:219], off
	v_lshl_add_u64 v[218:219], s[24:25], 0, v[134:135]
	s_mov_b32 m0, s41
	s_nop 0
	global_load_lds_dwordx4 v[218:219], off
	s_waitcnt vmcnt(8)
	s_waitcnt lgkmcnt(0)
	s_barrier
	s_setprio 1
	s_waitcnt lgkmcnt(0)
	v_mfma_f32_16x16x32_bf16 v[62:65], v[146:149], v[186:189], v[62:65]
	v_mfma_f32_16x16x32_bf16 v[58:61], v[160:163], v[186:189], v[58:61]
	v_mfma_f32_16x16x32_bf16 v[46:49], v[146:149], v[194:197], v[46:49]
	v_mfma_f32_16x16x32_bf16 v[42:45], v[160:163], v[194:197], v[42:45]
	v_mfma_f32_16x16x32_bf16 v[30:33], v[146:149], v[202:205], v[30:33]
	v_mfma_f32_16x16x32_bf16 v[26:29], v[160:163], v[202:205], v[26:29]
	v_mfma_f32_16x16x32_bf16 v[14:17], v[146:149], v[210:213], v[14:17]
	v_mfma_f32_16x16x32_bf16 v[10:13], v[160:163], v[210:213], v[10:13]
	v_mfma_f32_16x16x32_bf16 v[62:65], v[156:159], v[190:193], v[62:65]
	v_mfma_f32_16x16x32_bf16 v[58:61], v[164:167], v[190:193], v[58:61]
	v_mfma_f32_16x16x32_bf16 v[46:49], v[156:159], v[198:201], v[46:49]
	v_mfma_f32_16x16x32_bf16 v[42:45], v[164:167], v[198:201], v[42:45]
	v_mfma_f32_16x16x32_bf16 v[30:33], v[156:159], v[206:209], v[30:33]
	v_mfma_f32_16x16x32_bf16 v[26:29], v[164:167], v[206:209], v[26:29]
	v_mfma_f32_16x16x32_bf16 v[14:17], v[156:159], v[214:217], v[14:17]
	v_mfma_f32_16x16x32_bf16 v[10:13], v[164:167], v[214:217], v[10:13]
	s_setprio 0
	s_setprio 1
	v_mfma_f32_16x16x32_bf16 v[54:57], v[168:171], v[186:189], v[54:57]
	v_mfma_f32_16x16x32_bf16 v[50:53], v[176:179], v[186:189], v[50:53]
	v_mfma_f32_16x16x32_bf16 v[38:41], v[168:171], v[194:197], v[38:41]
	v_mfma_f32_16x16x32_bf16 v[34:37], v[176:179], v[194:197], v[34:37]
	v_mfma_f32_16x16x32_bf16 v[22:25], v[168:171], v[202:205], v[22:25]
	v_mfma_f32_16x16x32_bf16 v[18:21], v[176:179], v[202:205], v[18:21]
	v_mfma_f32_16x16x32_bf16 v[6:9], v[168:171], v[210:213], v[6:9]
	v_mfma_f32_16x16x32_bf16 v[2:5], v[176:179], v[210:213], v[2:5]
	v_mfma_f32_16x16x32_bf16 v[54:57], v[172:175], v[190:193], v[54:57]
	v_mfma_f32_16x16x32_bf16 v[50:53], v[182:185], v[190:193], v[50:53]
	v_mfma_f32_16x16x32_bf16 v[38:41], v[172:175], v[198:201], v[38:41]
	v_mfma_f32_16x16x32_bf16 v[34:37], v[182:185], v[198:201], v[34:37]
	v_mfma_f32_16x16x32_bf16 v[22:25], v[172:175], v[206:209], v[22:25]
	v_mfma_f32_16x16x32_bf16 v[18:21], v[182:185], v[206:209], v[18:21]
	v_mfma_f32_16x16x32_bf16 v[6:9], v[172:175], v[214:217], v[6:9]
	v_mfma_f32_16x16x32_bf16 v[2:5], v[182:185], v[214:217], v[2:5]
	s_setprio 0
	s_barrier
	s_add_i32 s57, s57, 2
	s_add_u32 s22, s22, 0x10000
	s_addc_u32 s23, s23, 0
	s_add_u32 s55, s55, 0x100
	s_addc_u32 s56, s56, 0

.LBB0_1827:
	ds_read_b128 v[146:149], v152
	ds_read_b128 v[156:159], v152 offset:1024
	ds_read_b128 v[160:163], v152 offset:2048
	ds_read_b128 v[164:167], v152 offset:3072
	ds_read_b128 v[168:171], v153
	ds_read_b128 v[172:175], v153 offset:1024
	ds_read_b128 v[176:179], v153 offset:2048
	ds_read_b128 v[182:185], v153 offset:3072
	s_add_i32 s40, s40, 1
	s_mul_i32 s4, s40, s43
	s_mul_hi_u32 s5, s40, s46
	s_add_i32 s5, s5, s4
	s_mul_i32 s4, s40, s46
	s_add_u32 s20, s4, s96
	s_addc_u32 s21, s5, s47
	v_cmp_gt_i64_e32 vcc, s[20:21], v[144:145]
	v_cmp_lt_i64_e64 s[4:5], s[20:21], v[142:143]
	s_cbranch_vccnz .LBB0_1833
	s_ashr_i32 s16, s20, 31
	s_lshr_b32 s16, s16, 29
	s_add_i32 s18, s20, s16
	s_and_b32 s16, s18, -8
	s_sub_i32 s19, s20, s16
	s_cmp_gt_i32 s19, -1
	s_mov_b64 s[16:17], -1
	s_cbranch_scc0 .LBB0_1830
	s_lshl_b32 s20, s19, 7
	s_mov_b64 s[16:17], 0

.LBB0_1833:
	s_ashr_i32 s19, s18, 31
	s_lshl_b64 s[20:21], s[18:19], 19
	s_add_u32 s20, s0, s20
	s_addc_u32 s21, s1, s21
	s_and_b64 s[22:23], s[4:5], exec
	s_cselect_b32 s19, s21, s31
	s_cselect_b32 s25, s20, s30
	s_ashr_i32 s17, s16, 31
	s_lshl_b64 s[22:23], s[16:17], 19
	v_readlane_b32 s34, v244, 43
	v_readlane_b32 s35, v244, 44
	s_add_u32 s22, s34, s22
	s_addc_u32 s23, s35, s23
	s_and_b64 s[34:35], s[4:5], exec
	s_cselect_b32 s17, s23, s29
	s_cselect_b32 s52, s22, s28
	s_add_u32 s53, s28, 0x100
	s_addc_u32 s54, s29, 0
	s_add_u32 s28, s30, 0x40080

	s_addc_u32 s29, s31, 0
	s_mov_b32 s55, -2
	s_waitcnt lgkmcnt(0)


	s_add_u32 s30, s28, 0xfffc0080
	s_addc_u32 s31, s29, -1
	s_cmp_eq_u32 s55, 12
	s_cselect_b32 s35, s19, s31
	s_cselect_b32 s34, s25, s30
	s_cselect_b32 s31, s17, s54
	s_cselect_b32 s30, s52, s53
	v_lshl_add_u64 v[218:219], s[28:29], 0, v[138:139]
	s_add_i32 m0, s27, 0xc000
	ds_read_b128 v[186:189], v154
	ds_read_b128 v[190:193], v154 offset:1024
	ds_read_b128 v[194:197], v154 offset:2048
	ds_read_b128 v[198:201], v154 offset:3072
	ds_read_b128 v[202:205], v154 offset:4096
	ds_read_b128 v[206:209], v154 offset:5120
	ds_read_b128 v[210:213], v154 offset:6144
	ds_read_b128 v[214:217], v154 offset:7168
	global_load_lds_dwordx4 v[218:219], off
	v_lshl_add_u64 v[218:219], s[28:29], 0, v[140:141]
	s_add_i32 m0, s27, 0xe000
	s_nop 0
	global_load_lds_dwordx4 v[218:219], off
	s_waitcnt vmcnt(8)
	s_waitcnt lgkmcnt(0)
	s_barrier
	s_setprio 1
	s_waitcnt lgkmcnt(0)
	v_mfma_f32_16x16x32_bf16 v[126:129], v[146:149], v[186:189], 0
	v_mfma_f32_16x16x32_bf16 v[122:125], v[160:163], v[186:189], 0
	v_mfma_f32_16x16x32_bf16 v[110:113], v[146:149], v[194:197], 0
	v_mfma_f32_16x16x32_bf16 v[106:109], v[160:163], v[194:197], 0
	v_mfma_f32_16x16x32_bf16 v[94:97], v[146:149], v[202:205], 0
	v_mfma_f32_16x16x32_bf16 v[90:93], v[160:163], v[202:205], 0
	v_mfma_f32_16x16x32_bf16 v[78:81], v[146:149], v[210:213], 0
	v_mfma_f32_16x16x32_bf16 v[74:77], v[160:163], v[210:213], 0
	v_mfma_f32_16x16x32_bf16 v[126:129], v[156:159], v[190:193], v[126:129]
	v_mfma_f32_16x16x32_bf16 v[122:125], v[164:167], v[190:193], v[122:125]
	v_mfma_f32_16x16x32_bf16 v[110:113], v[156:159], v[198:201], v[110:113]
	v_mfma_f32_16x16x32_bf16 v[106:109], v[164:167], v[198:201], v[106:109]
	v_mfma_f32_16x16x32_bf16 v[94:97], v[156:159], v[206:209], v[94:97]
	v_mfma_f32_16x16x32_bf16 v[90:93], v[164:167], v[206:209], v[90:93]
	v_mfma_f32_16x16x32_bf16 v[78:81], v[156:159], v[214:217], v[78:81]
	v_mfma_f32_16x16x32_bf16 v[74:77], v[164:167], v[214:217], v[74:77]
	s_setprio 0
	s_setprio 1
	v_mfma_f32_16x16x32_bf16 v[118:121], v[168:171], v[186:189], 0
	v_mfma_f32_16x16x32_bf16 v[114:117], v[176:179], v[186:189], 0
	v_mfma_f32_16x16x32_bf16 v[102:105], v[168:171], v[194:197], 0
	v_mfma_f32_16x16x32_bf16 v[98:101], v[176:179], v[194:197], 0
	v_mfma_f32_16x16x32_bf16 v[86:89], v[168:171], v[202:205], 0
	v_mfma_f32_16x16x32_bf16 v[82:85], v[176:179], v[202:205], 0
	v_mfma_f32_16x16x32_bf16 v[70:73], v[168:171], v[210:213], 0
	v_mfma_f32_16x16x32_bf16 v[66:69], v[176:179], v[210:213], 0
	v_mfma_f32_16x16x32_bf16 v[118:121], v[172:175], v[190:193], v[118:121]
	v_mfma_f32_16x16x32_bf16 v[114:117], v[182:185], v[190:193], v[114:117]
	v_mfma_f32_16x16x32_bf16 v[102:105], v[172:175], v[198:201], v[102:105]
	v_mfma_f32_16x16x32_bf16 v[98:101], v[182:185], v[198:201], v[98:101]
	v_mfma_f32_16x16x32_bf16 v[86:89], v[172:175], v[206:209], v[86:89]
	v_mfma_f32_16x16x32_bf16 v[82:85], v[182:185], v[206:209], v[82:85]
	v_mfma_f32_16x16x32_bf16 v[70:73], v[172:175], v[214:217], v[70:73]
	v_mfma_f32_16x16x32_bf16 v[66:69], v[182:185], v[214:217], v[66:69]
	s_setprio 0
	s_barrier
	s_add_i32 s33, s48, s36
	v_lshl_add_u64 v[218:219], s[30:31], 0, v[132:133]
	s_mov_b32 m0, s33
	ds_read_b128 v[186:189], v154 offset:16384
	ds_read_b128 v[190:193], v154 offset:17408
	ds_read_b128 v[194:197], v154 offset:18432
	ds_read_b128 v[198:201], v154 offset:19456
	ds_read_b128 v[202:205], v154 offset:20480
	ds_read_b128 v[206:209], v154 offset:21504
	ds_read_b128 v[210:213], v154 offset:22528
	ds_read_b128 v[214:217], v154 offset:23552
	global_load_lds_dwordx4 v[218:219], off
	s_add_i32 m0, s33, 0x2000
	s_add_u32 s56, s30, 0x40000
	v_lshl_add_u64 v[220:221], s[30:31], 0, v[136:137]
	s_addc_u32 s57, s31, 0
	s_add_i32 s33, s49, s36
	global_load_lds_dwordx4 v[220:221], off
	v_lshl_add_u64 v[222:223], s[56:57], 0, v[132:133]
	s_mov_b32 m0, s33
	v_lshl_add_u64 v[224:225], s[34:35], 0, v[134:135]
	global_load_lds_dwordx4 v[222:223], off
	v_lshl_add_u64 v[222:223], s[56:57], 0, v[136:137]
	s_add_i32 m0, s33, 0x2000
	s_nop 0
	global_load_lds_dwordx4 v[222:223], off
	v_lshl_add_u64 v[222:223], s[34:35], 0, v[130:131]
	s_mov_b32 m0, s27
	s_nop 0
	global_load_lds_dwordx4 v[222:223], off
	s_mov_b32 m0, s37
	s_nop 0
	global_load_lds_dwordx4 v[224:225], off
	s_waitcnt vmcnt(8)
	s_waitcnt lgkmcnt(0)
	s_barrier
	s_setprio 1
	s_waitcnt lgkmcnt(0)
	v_mfma_f32_16x16x32_bf16 v[62:65], v[146:149], v[186:189], 0
	v_mfma_f32_16x16x32_bf16 v[58:61], v[160:163], v[186:189], 0
	v_mfma_f32_16x16x32_bf16 v[46:49], v[146:149], v[194:197], 0
	v_mfma_f32_16x16x32_bf16 v[42:45], v[160:163], v[194:197], 0
	v_mfma_f32_16x16x32_bf16 v[30:33], v[146:149], v[202:205], 0
	v_mfma_f32_16x16x32_bf16 v[26:29], v[160:163], v[202:205], 0
	v_mfma_f32_16x16x32_bf16 v[14:17], v[146:149], v[210:213], 0
	v_mfma_f32_16x16x32_bf16 v[10:13], v[160:163], v[210:213], 0
	v_mfma_f32_16x16x32_bf16 v[62:65], v[156:159], v[190:193], v[62:65]
	v_mfma_f32_16x16x32_bf16 v[58:61], v[164:167], v[190:193], v[58:61]
	v_mfma_f32_16x16x32_bf16 v[46:49], v[156:159], v[198:201], v[46:49]
	v_mfma_f32_16x16x32_bf16 v[42:45], v[164:167], v[198:201], v[42:45]
	v_mfma_f32_16x16x32_bf16 v[30:33], v[156:159], v[206:209], v[30:33]
	v_mfma_f32_16x16x32_bf16 v[26:29], v[164:167], v[206:209], v[26:29]
	v_mfma_f32_16x16x32_bf16 v[14:17], v[156:159], v[214:217], v[14:17]
	v_mfma_f32_16x16x32_bf16 v[10:13], v[164:167], v[214:217], v[10:13]
	s_setprio 0
	s_setprio 1
	v_mfma_f32_16x16x32_bf16 v[54:57], v[168:171], v[186:189], 0
	v_mfma_f32_16x16x32_bf16 v[50:53], v[176:179], v[186:189], 0
	v_mfma_f32_16x16x32_bf16 v[38:41], v[168:171], v[194:197], 0
	v_mfma_f32_16x16x32_bf16 v[34:37], v[176:179], v[194:197], 0
	v_mfma_f32_16x16x32_bf16 v[22:25], v[168:171], v[202:205], 0
	v_mfma_f32_16x16x32_bf16 v[18:21], v[176:179], v[202:205], 0
	v_mfma_f32_16x16x32_bf16 v[6:9], v[168:171], v[210:213], 0
	v_mfma_f32_16x16x32_bf16 v[2:5], v[176:179], v[210:213], 0
	v_mfma_f32_16x16x32_bf16 v[54:57], v[172:175], v[190:193], v[54:57]
	v_mfma_f32_16x16x32_bf16 v[50:53], v[182:185], v[190:193], v[50:53]
	v_mfma_f32_16x16x32_bf16 v[38:41], v[172:175], v[198:201], v[38:41]
	v_mfma_f32_16x16x32_bf16 v[34:37], v[182:185], v[198:201], v[34:37]
	v_mfma_f32_16x16x32_bf16 v[22:25], v[172:175], v[206:209], v[22:25]
	v_mfma_f32_16x16x32_bf16 v[18:21], v[182:185], v[206:209], v[18:21]
	v_mfma_f32_16x16x32_bf16 v[6:9], v[172:175], v[214:217], v[6:9]
	v_mfma_f32_16x16x32_bf16 v[2:5], v[182:185], v[214:217], v[2:5]
	s_setprio 0
	s_barrier
	s_add_i32 s33, 0, 0x18000
	s_add_i32 s51, 0, 0x1c000
	v_add_u32_e32 v164, s33, v150
	v_add_u32_e32 v182, s51, v150
	ds_read_b128 v[146:149], v164
	ds_read_b128 v[156:159], v164 offset:1024
	ds_read_b128 v[160:163], v164 offset:2048
	ds_read_b128 v[164:167], v164 offset:3072
	ds_read_b128 v[168:171], v182
	ds_read_b128 v[172:175], v182 offset:1024
	ds_read_b128 v[176:179], v182 offset:2048
	ds_read_b128 v[182:185], v182 offset:3072
	s_add_u32 s34, s34, 0x40000
	s_addc_u32 s35, s35, 0
	s_mov_b32 m0, s38
	v_lshl_add_u64 v[226:227], s[34:35], 0, v[130:131]
	ds_read_b128 v[186:189], v154 offset:32768
	ds_read_b128 v[190:193], v154 offset:33792
	ds_read_b128 v[194:197], v154 offset:34816
	ds_read_b128 v[198:201], v154 offset:35840
	ds_read_b128 v[202:205], v154 offset:36864
	ds_read_b128 v[206:209], v154 offset:37888
	ds_read_b128 v[210:213], v154 offset:38912
	ds_read_b128 v[214:217], v154 offset:39936
	global_load_lds_dwordx4 v[226:227], off
	v_lshl_add_u64 v[226:227], s[34:35], 0, v[134:135]
	s_mov_b32 m0, s39
	s_nop 0
	global_load_lds_dwordx4 v[226:227], off
	s_waitcnt vmcnt(8)
	s_waitcnt lgkmcnt(0)
	s_barrier
	s_setprio 1
	s_waitcnt lgkmcnt(0)
	v_mfma_f32_16x16x32_bf16 v[126:129], v[146:149], v[186:189], v[126:129]
	v_mfma_f32_16x16x32_bf16 v[122:125], v[160:163], v[186:189], v[122:125]
	v_mfma_f32_16x16x32_bf16 v[110:113], v[146:149], v[194:197], v[110:113]
	v_mfma_f32_16x16x32_bf16 v[106:109], v[160:163], v[194:197], v[106:109]
	v_mfma_f32_16x16x32_bf16 v[94:97], v[146:149], v[202:205], v[94:97]
	v_mfma_f32_16x16x32_bf16 v[90:93], v[160:163], v[202:205], v[90:93]
	v_mfma_f32_16x16x32_bf16 v[78:81], v[146:149], v[210:213], v[78:81]
	v_mfma_f32_16x16x32_bf16 v[74:77], v[160:163], v[210:213], v[74:77]
	v_mfma_f32_16x16x32_bf16 v[126:129], v[156:159], v[190:193], v[126:129]
	v_mfma_f32_16x16x32_bf16 v[122:125], v[164:167], v[190:193], v[122:125]
	v_mfma_f32_16x16x32_bf16 v[110:113], v[156:159], v[198:201], v[110:113]
	v_mfma_f32_16x16x32_bf16 v[106:109], v[164:167], v[198:201], v[106:109]
	v_mfma_f32_16x16x32_bf16 v[94:97], v[156:159], v[206:209], v[94:97]
	v_mfma_f32_16x16x32_bf16 v[90:93], v[164:167], v[206:209], v[90:93]
	v_mfma_f32_16x16x32_bf16 v[78:81], v[156:159], v[214:217], v[78:81]
	v_mfma_f32_16x16x32_bf16 v[74:77], v[164:167], v[214:217], v[74:77]
	s_setprio 0
	s_setprio 1
	v_mfma_f32_16x16x32_bf16 v[118:121], v[168:171], v[186:189], v[118:121]
	v_mfma_f32_16x16x32_bf16 v[114:117], v[176:179], v[186:189], v[114:117]
	v_mfma_f32_16x16x32_bf16 v[102:105], v[168:171], v[194:197], v[102:105]
	v_mfma_f32_16x16x32_bf16 v[98:101], v[176:179], v[194:197], v[98:101]
	v_mfma_f32_16x16x32_bf16 v[86:89], v[168:171], v[202:205], v[86:89]
	v_mfma_f32_16x16x32_bf16 v[82:85], v[176:179], v[202:205], v[82:85]
	v_mfma_f32_16x16x32_bf16 v[70:73], v[168:171], v[210:213], v[70:73]
	v_mfma_f32_16x16x32_bf16 v[66:69], v[176:179], v[210:213], v[66:69]
	v_mfma_f32_16x16x32_bf16 v[118:121], v[172:175], v[190:193], v[118:121]
	v_mfma_f32_16x16x32_bf16 v[114:117], v[182:185], v[190:193], v[114:117]
	v_mfma_f32_16x16x32_bf16 v[102:105], v[172:175], v[198:201], v[102:105]
	v_mfma_f32_16x16x32_bf16 v[98:101], v[182:185], v[198:201], v[98:101]
	v_mfma_f32_16x16x32_bf16 v[86:89], v[172:175], v[206:209], v[86:89]
	v_mfma_f32_16x16x32_bf16 v[82:85], v[182:185], v[206:209], v[82:85]
	v_mfma_f32_16x16x32_bf16 v[70:73], v[172:175], v[214:217], v[70:73]
	v_mfma_f32_16x16x32_bf16 v[66:69], v[182:185], v[214:217], v[66:69]
	s_setprio 0
	s_barrier
	s_add_i32 s33, s33, s36
	v_lshl_add_u64 v[218:219], v[218:219], 0, s[12:13]
	s_mov_b32 m0, s33
	ds_read_b128 v[186:189], v154 offset:49152
	ds_read_b128 v[190:193], v154 offset:50176
	ds_read_b128 v[194:197], v154 offset:51200
	ds_read_b128 v[198:201], v154 offset:52224
	ds_read_b128 v[202:205], v154 offset:53248
	ds_read_b128 v[206:209], v154 offset:54272
	ds_read_b128 v[210:213], v154 offset:55296
	ds_read_b128 v[214:217], v154 offset:56320
	global_load_lds_dwordx4 v[218:219], off
	s_add_i32 m0, s33, 0x2000
	s_add_u32 s30, s30, 0x40080
	v_lshl_add_u64 v[218:219], v[220:221], 0, s[12:13]
	s_addc_u32 s31, s31, 0
	s_add_i32 s33, s51, s36
	global_load_lds_dwordx4 v[218:219], off
	v_lshl_add_u64 v[218:219], s[30:31], 0, v[132:133]
	s_mov_b32 m0, s33
	s_nop 0
	global_load_lds_dwordx4 v[218:219], off
	v_lshl_add_u64 v[218:219], s[30:31], 0, v[136:137]
	s_add_i32 m0, s33, 0x2000
	s_nop 0
	global_load_lds_dwordx4 v[218:219], off
	v_lshl_add_u64 v[218:219], v[222:223], 0, s[12:13]
	s_mov_b32 m0, s41
	s_nop 0
	global_load_lds_dwordx4 v[218:219], off
	v_lshl_add_u64 v[218:219], v[224:225], 0, s[12:13]
	s_mov_b32 m0, s42
	s_nop 0
	global_load_lds_dwordx4 v[218:219], off
	s_waitcnt vmcnt(8)
	s_waitcnt lgkmcnt(0)
	s_barrier
	s_setprio 1
	s_waitcnt lgkmcnt(0)
	v_mfma_f32_16x16x32_bf16 v[62:65], v[146:149], v[186:189], v[62:65]
	v_mfma_f32_16x16x32_bf16 v[58:61], v[160:163], v[186:189], v[58:61]
	v_mfma_f32_16x16x32_bf16 v[46:49], v[146:149], v[194:197], v[46:49]
	v_mfma_f32_16x16x32_bf16 v[42:45], v[160:163], v[194:197], v[42:45]
	v_mfma_f32_16x16x32_bf16 v[30:33], v[146:149], v[202:205], v[30:33]
	v_mfma_f32_16x16x32_bf16 v[26:29], v[160:163], v[202:205], v[26:29]
	v_mfma_f32_16x16x32_bf16 v[14:17], v[146:149], v[210:213], v[14:17]
	v_mfma_f32_16x16x32_bf16 v[10:13], v[160:163], v[210:213], v[10:13]
	v_mfma_f32_16x16x32_bf16 v[62:65], v[156:159], v[190:193], v[62:65]
	v_mfma_f32_16x16x32_bf16 v[58:61], v[164:167], v[190:193], v[58:61]
	v_mfma_f32_16x16x32_bf16 v[46:49], v[156:159], v[198:201], v[46:49]
	v_mfma_f32_16x16x32_bf16 v[42:45], v[164:167], v[198:201], v[42:45]
	v_mfma_f32_16x16x32_bf16 v[30:33], v[156:159], v[206:209], v[30:33]
	v_mfma_f32_16x16x32_bf16 v[26:29], v[164:167], v[206:209], v[26:29]
	v_mfma_f32_16x16x32_bf16 v[14:17], v[156:159], v[214:217], v[14:17]
	v_mfma_f32_16x16x32_bf16 v[10:13], v[164:167], v[214:217], v[10:13]
	s_setprio 0
	s_setprio 1
	v_mfma_f32_16x16x32_bf16 v[54:57], v[168:171], v[186:189], v[54:57]
	v_mfma_f32_16x16x32_bf16 v[50:53], v[176:179], v[186:189], v[50:53]
	v_mfma_f32_16x16x32_bf16 v[38:41], v[168:171], v[194:197], v[38:41]
	v_mfma_f32_16x16x32_bf16 v[34:37], v[176:179], v[194:197], v[34:37]
	v_mfma_f32_16x16x32_bf16 v[22:25], v[168:171], v[202:205], v[22:25]
	v_mfma_f32_16x16x32_bf16 v[18:21], v[176:179], v[202:205], v[18:21]
	v_mfma_f32_16x16x32_bf16 v[6:9], v[168:171], v[210:213], v[6:9]
	v_mfma_f32_16x16x32_bf16 v[2:5], v[176:179], v[210:213], v[2:5]
	v_mfma_f32_16x16x32_bf16 v[54:57], v[172:175], v[190:193], v[54:57]
	v_mfma_f32_16x16x32_bf16 v[50:53], v[182:185], v[190:193], v[50:53]
	v_mfma_f32_16x16x32_bf16 v[38:41], v[172:175], v[198:201], v[38:41]
	v_mfma_f32_16x16x32_bf16 v[34:37], v[182:185], v[198:201], v[34:37]
	v_mfma_f32_16x16x32_bf16 v[22:25], v[172:175], v[206:209], v[22:25]
	v_mfma_f32_16x16x32_bf16 v[18:21], v[182:185], v[206:209], v[18:21]
	v_mfma_f32_16x16x32_bf16 v[6:9], v[172:175], v[214:217], v[6:9]
	v_mfma_f32_16x16x32_bf16 v[2:5], v[182:185], v[214:217], v[2:5]
	s_setprio 0
	s_barrier
	s_add_i32 s55, s55, 2
	s_add_u32 s53, s53, 0x100
	s_addc_u32 s54, s54, 0
	s_add_u32 s28, s28, 0x100
	s_addc_u32 s29, s29, 0

.LBB0_1934:
	ds_read_b128 v[158:161], v154
	ds_read_b128 v[162:165], v154 offset:1024
	ds_read_b128 v[166:169], v154 offset:2048
	ds_read_b128 v[170:173], v154 offset:3072
	ds_read_b128 v[174:177], v155
	ds_read_b128 v[182:185], v155 offset:1024
	ds_read_b128 v[186:189], v155 offset:2048
	ds_read_b128 v[190:193], v155 offset:3072
	s_add_i32 s49, s52, 1
	s_mul_i32 s2, s49, s41
	s_mul_hi_u32 s3, s49, s42
	s_add_i32 s3, s3, s2
	s_mul_i32 s2, s49, s42
	s_add_u32 s14, s2, s96
	s_addc_u32 s15, s3, s28
	v_cmp_gt_i64_e32 vcc, s[14:15], v[150:151]
	v_cmp_lt_i64_e64 s[2:3], s[14:15], v[148:149]
	s_cbranch_vccnz .LBB0_1936
	s_ashr_i32 s10, s14, 31
	s_lshr_b32 s10, s10, 29
	s_add_i32 s10, s14, s10
	s_ashr_i32 s11, s10, 3
	s_and_b32 s10, s10, -8
	s_sub_i32 s10, s14, s10
	s_cmp_lt_i32 s10, 0
	s_cselect_b32 s12, s43, 0x2c0
	s_mul_i32 s10, s10, s12
	s_add_i32 s10, s10, s11
	s_mul_hi_i32 s11, s10, 0x2e8ba2e9
	s_lshr_b32 s12, s11, 31
	s_ashr_i32 s11, s11, 5
	s_add_i32 s11, s11, s12
	s_lshl_b32 s12, s11, 3
	s_mulk_i32 s11, 0xb0
	s_sub_i32 s11, s10, s11
	s_ashr_i32 s10, s11, 3
	s_and_b32 s11, s11, 7
	s_add_i32 s12, s12, s11
.LBB0_1936:
	s_ashr_i32 s13, s12, 31
	s_lshl_b64 s[14:15], s[12:13], 19
	s_add_u32 s14, s92, s14
	s_addc_u32 s15, s93, s15
	s_and_b64 s[16:17], s[2:3], exec
	s_cselect_b32 s13, s15, s23
	s_cselect_b32 s53, s14, s22
	s_ashr_i32 s11, s10, 31
	s_lshl_b64 s[16:17], s[10:11], 19
	s_add_u32 s16, s29, s16
	s_addc_u32 s17, s30, s17
	s_and_b64 s[26:27], s[2:3], exec
	s_cselect_b32 s11, s17, s25
	s_cselect_b32 s54, s16, s24
	s_add_u32 s22, s22, 0x40080
	s_addc_u32 s23, s23, 0
	s_add_u32 s55, s24, 0x100

	s_addc_u32 s56, s25, 0
	s_mov_b32 s57, -2


	s_add_u32 s24, s22, 0xfffc0080
	s_addc_u32 s25, s23, -1
	s_cmp_eq_u32 s57, 12
	s_cselect_b32 s27, s13, s25
	s_cselect_b32 s26, s53, s24
	s_cselect_b32 s25, s11, s56
	s_cselect_b32 s24, s54, s55
	v_lshl_add_u64 v[178:179], s[22:23], 0, v[144:145]
	s_add_i32 m0, s21, 0xc000
	ds_read_b128 v[194:197], v156
	ds_read_b128 v[198:201], v156 offset:1024
	ds_read_b128 v[202:205], v156 offset:2048
	ds_read_b128 v[206:209], v156 offset:3072
	ds_read_b128 v[210:213], v156 offset:4096
	ds_read_b128 v[214:217], v156 offset:5120
	ds_read_b128 v[218:221], v156 offset:6144
	ds_read_b128 v[222:225], v156 offset:7168
	global_load_lds_dwordx4 v[178:179], off
	v_lshl_add_u64 v[178:179], s[22:23], 0, v[146:147]
	s_add_i32 m0, s21, 0xe000
	s_nop 0
	global_load_lds_dwordx4 v[178:179], off
	s_waitcnt vmcnt(8)
	s_waitcnt lgkmcnt(0)
	s_barrier
	s_setprio 1
	s_waitcnt lgkmcnt(0)
	v_mfma_f32_16x16x32_bf16 v[126:129], v[158:161], v[194:197], 0
	v_mfma_f32_16x16x32_bf16 v[118:121], v[166:169], v[194:197], 0
	v_mfma_f32_16x16x32_bf16 v[110:113], v[158:161], v[202:205], 0
	v_mfma_f32_16x16x32_bf16 v[102:105], v[166:169], v[202:205], 0
	v_mfma_f32_16x16x32_bf16 v[94:97], v[158:161], v[210:213], 0
	v_mfma_f32_16x16x32_bf16 v[86:89], v[166:169], v[210:213], 0
	v_mfma_f32_16x16x32_bf16 v[78:81], v[158:161], v[218:221], 0
	v_mfma_f32_16x16x32_bf16 v[70:73], v[166:169], v[218:221], 0
	v_mfma_f32_16x16x32_bf16 v[126:129], v[162:165], v[198:201], v[126:129]
	v_mfma_f32_16x16x32_bf16 v[118:121], v[170:173], v[198:201], v[118:121]
	v_mfma_f32_16x16x32_bf16 v[110:113], v[162:165], v[206:209], v[110:113]
	v_mfma_f32_16x16x32_bf16 v[102:105], v[170:173], v[206:209], v[102:105]
	v_mfma_f32_16x16x32_bf16 v[94:97], v[162:165], v[214:217], v[94:97]
	v_mfma_f32_16x16x32_bf16 v[86:89], v[170:173], v[214:217], v[86:89]
	v_mfma_f32_16x16x32_bf16 v[78:81], v[162:165], v[222:225], v[78:81]
	v_mfma_f32_16x16x32_bf16 v[70:73], v[170:173], v[222:225], v[70:73]
	s_setprio 0
	s_setprio 1
	v_mfma_f32_16x16x32_bf16 v[122:125], v[174:177], v[194:197], 0
	v_mfma_f32_16x16x32_bf16 v[114:117], v[186:189], v[194:197], 0
	v_mfma_f32_16x16x32_bf16 v[106:109], v[174:177], v[202:205], 0
	v_mfma_f32_16x16x32_bf16 v[98:101], v[186:189], v[202:205], 0
	v_mfma_f32_16x16x32_bf16 v[90:93], v[174:177], v[210:213], 0
	v_mfma_f32_16x16x32_bf16 v[82:85], v[186:189], v[210:213], 0
	v_mfma_f32_16x16x32_bf16 v[74:77], v[174:177], v[218:221], 0
	v_mfma_f32_16x16x32_bf16 v[66:69], v[186:189], v[218:221], 0
	v_mfma_f32_16x16x32_bf16 v[122:125], v[182:185], v[198:201], v[122:125]
	v_mfma_f32_16x16x32_bf16 v[114:117], v[190:193], v[198:201], v[114:117]
	v_mfma_f32_16x16x32_bf16 v[106:109], v[182:185], v[206:209], v[106:109]
	v_mfma_f32_16x16x32_bf16 v[98:101], v[190:193], v[206:209], v[98:101]
	v_mfma_f32_16x16x32_bf16 v[90:93], v[182:185], v[214:217], v[90:93]
	v_mfma_f32_16x16x32_bf16 v[82:85], v[190:193], v[214:217], v[82:85]
	v_mfma_f32_16x16x32_bf16 v[74:77], v[182:185], v[222:225], v[74:77]
	v_mfma_f32_16x16x32_bf16 v[66:69], v[190:193], v[222:225], v[66:69]
	s_setprio 0
	s_barrier
	s_add_i32 s33, s46, s19
	v_lshl_add_u64 v[178:179], s[24:25], 0, v[132:133]
	s_mov_b32 m0, s33
	ds_read_b128 v[194:197], v156 offset:16384
	ds_read_b128 v[198:201], v156 offset:17408
	ds_read_b128 v[202:205], v156 offset:18432
	ds_read_b128 v[206:209], v156 offset:19456
	ds_read_b128 v[210:213], v156 offset:20480
	ds_read_b128 v[214:217], v156 offset:21504
	ds_read_b128 v[218:221], v156 offset:22528
	ds_read_b128 v[222:225], v156 offset:23552
	global_load_lds_dwordx4 v[178:179], off
	s_add_i32 m0, s33, 0x2000
	s_add_u32 s58, s24, 0x40000
	v_lshl_add_u64 v[226:227], s[24:25], 0, v[136:137]
	s_addc_u32 s59, s25, 0
	s_add_i32 s33, s47, s19
	global_load_lds_dwordx4 v[226:227], off
	v_lshl_add_u64 v[228:229], s[58:59], 0, v[132:133]
	s_mov_b32 m0, s33
	v_lshl_add_u64 v[230:231], s[26:27], 0, v[134:135]
	global_load_lds_dwordx4 v[228:229], off
	v_lshl_add_u64 v[228:229], s[58:59], 0, v[136:137]
	s_add_i32 m0, s33, 0x2000
	s_nop 0
	global_load_lds_dwordx4 v[228:229], off
	v_lshl_add_u64 v[228:229], s[26:27], 0, v[130:131]
	s_mov_b32 m0, s21
	s_nop 0
	global_load_lds_dwordx4 v[228:229], off
	s_mov_b32 m0, s31
	s_nop 0
	global_load_lds_dwordx4 v[230:231], off
	s_waitcnt vmcnt(8)
	s_waitcnt lgkmcnt(0)
	s_barrier
	s_setprio 1
	s_waitcnt lgkmcnt(0)
	v_mfma_f32_16x16x32_bf16 v[62:65], v[158:161], v[194:197], 0
	v_mfma_f32_16x16x32_bf16 v[54:57], v[166:169], v[194:197], 0
	v_mfma_f32_16x16x32_bf16 v[46:49], v[158:161], v[202:205], 0
	v_mfma_f32_16x16x32_bf16 v[38:41], v[166:169], v[202:205], 0
	v_mfma_f32_16x16x32_bf16 v[30:33], v[158:161], v[210:213], 0
	v_mfma_f32_16x16x32_bf16 v[22:25], v[166:169], v[210:213], 0
	v_mfma_f32_16x16x32_bf16 v[14:17], v[158:161], v[218:221], 0
	v_mfma_f32_16x16x32_bf16 v[6:9], v[166:169], v[218:221], 0
	v_mfma_f32_16x16x32_bf16 v[62:65], v[162:165], v[198:201], v[62:65]
	v_mfma_f32_16x16x32_bf16 v[54:57], v[170:173], v[198:201], v[54:57]
	v_mfma_f32_16x16x32_bf16 v[46:49], v[162:165], v[206:209], v[46:49]
	v_mfma_f32_16x16x32_bf16 v[38:41], v[170:173], v[206:209], v[38:41]
	v_mfma_f32_16x16x32_bf16 v[30:33], v[162:165], v[214:217], v[30:33]
	v_mfma_f32_16x16x32_bf16 v[22:25], v[170:173], v[214:217], v[22:25]
	v_mfma_f32_16x16x32_bf16 v[14:17], v[162:165], v[222:225], v[14:17]
	v_mfma_f32_16x16x32_bf16 v[6:9], v[170:173], v[222:225], v[6:9]
	s_setprio 0
	s_setprio 1
	v_mfma_f32_16x16x32_bf16 v[58:61], v[174:177], v[194:197], 0
	v_mfma_f32_16x16x32_bf16 v[50:53], v[186:189], v[194:197], 0
	v_mfma_f32_16x16x32_bf16 v[42:45], v[174:177], v[202:205], 0
	v_mfma_f32_16x16x32_bf16 v[34:37], v[186:189], v[202:205], 0
	v_mfma_f32_16x16x32_bf16 v[26:29], v[174:177], v[210:213], 0
	v_mfma_f32_16x16x32_bf16 v[18:21], v[186:189], v[210:213], 0
	v_mfma_f32_16x16x32_bf16 v[10:13], v[174:177], v[218:221], 0
	v_mfma_f32_16x16x32_bf16 v[2:5], v[186:189], v[218:221], 0
	v_mfma_f32_16x16x32_bf16 v[58:61], v[182:185], v[198:201], v[58:61]
	v_mfma_f32_16x16x32_bf16 v[50:53], v[190:193], v[198:201], v[50:53]
	v_mfma_f32_16x16x32_bf16 v[42:45], v[182:185], v[206:209], v[42:45]
	v_mfma_f32_16x16x32_bf16 v[34:37], v[190:193], v[206:209], v[34:37]
	v_mfma_f32_16x16x32_bf16 v[26:29], v[182:185], v[214:217], v[26:29]
	v_mfma_f32_16x16x32_bf16 v[18:21], v[190:193], v[214:217], v[18:21]
	v_mfma_f32_16x16x32_bf16 v[10:13], v[182:185], v[222:225], v[10:13]
	v_mfma_f32_16x16x32_bf16 v[2:5], v[190:193], v[222:225], v[2:5]
	s_setprio 0
	s_barrier
	s_add_i32 s33, 0, 0x18000
	s_add_i32 s51, 0, 0x1c000
	v_add_u32_e32 v170, s33, v152
	v_add_u32_e32 v181, s51, v152
	ds_read_b128 v[158:161], v170
	ds_read_b128 v[162:165], v170 offset:1024
	ds_read_b128 v[166:169], v170 offset:2048
	ds_read_b128 v[170:173], v170 offset:3072
	ds_read_b128 v[174:177], v181
	ds_read_b128 v[182:185], v181 offset:1024
	ds_read_b128 v[186:189], v181 offset:2048
	ds_read_b128 v[190:193], v181 offset:3072
	s_add_u32 s26, s26, 0x40000
	s_addc_u32 s27, s27, 0
	s_mov_b32 m0, s34
	v_lshl_add_u64 v[232:233], s[26:27], 0, v[130:131]
	ds_read_b128 v[194:197], v156 offset:32768
	ds_read_b128 v[198:201], v156 offset:33792
	ds_read_b128 v[202:205], v156 offset:34816
	ds_read_b128 v[206:209], v156 offset:35840
	ds_read_b128 v[210:213], v156 offset:36864
	ds_read_b128 v[214:217], v156 offset:37888
	ds_read_b128 v[218:221], v156 offset:38912
	ds_read_b128 v[222:225], v156 offset:39936
	global_load_lds_dwordx4 v[232:233], off
	v_lshl_add_u64 v[232:233], s[26:27], 0, v[134:135]
	s_mov_b32 m0, s35
	s_nop 0
	global_load_lds_dwordx4 v[232:233], off
	s_waitcnt vmcnt(8)
	s_waitcnt lgkmcnt(0)
	s_barrier
	s_setprio 1
	s_waitcnt lgkmcnt(0)
	v_mfma_f32_16x16x32_bf16 v[126:129], v[158:161], v[194:197], v[126:129]
	v_mfma_f32_16x16x32_bf16 v[118:121], v[166:169], v[194:197], v[118:121]
	v_mfma_f32_16x16x32_bf16 v[110:113], v[158:161], v[202:205], v[110:113]
	v_mfma_f32_16x16x32_bf16 v[102:105], v[166:169], v[202:205], v[102:105]
	v_mfma_f32_16x16x32_bf16 v[94:97], v[158:161], v[210:213], v[94:97]
	v_mfma_f32_16x16x32_bf16 v[86:89], v[166:169], v[210:213], v[86:89]
	v_mfma_f32_16x16x32_bf16 v[78:81], v[158:161], v[218:221], v[78:81]
	v_mfma_f32_16x16x32_bf16 v[70:73], v[166:169], v[218:221], v[70:73]
	v_mfma_f32_16x16x32_bf16 v[126:129], v[162:165], v[198:201], v[126:129]
	v_mfma_f32_16x16x32_bf16 v[118:121], v[170:173], v[198:201], v[118:121]
	v_mfma_f32_16x16x32_bf16 v[110:113], v[162:165], v[206:209], v[110:113]
	v_mfma_f32_16x16x32_bf16 v[102:105], v[170:173], v[206:209], v[102:105]
	v_mfma_f32_16x16x32_bf16 v[94:97], v[162:165], v[214:217], v[94:97]
	v_mfma_f32_16x16x32_bf16 v[86:89], v[170:173], v[214:217], v[86:89]
	v_mfma_f32_16x16x32_bf16 v[78:81], v[162:165], v[222:225], v[78:81]
	v_mfma_f32_16x16x32_bf16 v[70:73], v[170:173], v[222:225], v[70:73]
	s_setprio 0
	s_setprio 1
	v_mfma_f32_16x16x32_bf16 v[122:125], v[174:177], v[194:197], v[122:125]
	v_mfma_f32_16x16x32_bf16 v[114:117], v[186:189], v[194:197], v[114:117]
	v_mfma_f32_16x16x32_bf16 v[106:109], v[174:177], v[202:205], v[106:109]
	v_mfma_f32_16x16x32_bf16 v[98:101], v[186:189], v[202:205], v[98:101]
	v_mfma_f32_16x16x32_bf16 v[90:93], v[174:177], v[210:213], v[90:93]
	v_mfma_f32_16x16x32_bf16 v[82:85], v[186:189], v[210:213], v[82:85]
	v_mfma_f32_16x16x32_bf16 v[74:77], v[174:177], v[218:221], v[74:77]
	v_mfma_f32_16x16x32_bf16 v[66:69], v[186:189], v[218:221], v[66:69]
	v_mfma_f32_16x16x32_bf16 v[122:125], v[182:185], v[198:201], v[122:125]
	v_mfma_f32_16x16x32_bf16 v[114:117], v[190:193], v[198:201], v[114:117]
	v_mfma_f32_16x16x32_bf16 v[106:109], v[182:185], v[206:209], v[106:109]
	v_mfma_f32_16x16x32_bf16 v[98:101], v[190:193], v[206:209], v[98:101]
	v_mfma_f32_16x16x32_bf16 v[90:93], v[182:185], v[214:217], v[90:93]
	v_mfma_f32_16x16x32_bf16 v[82:85], v[190:193], v[214:217], v[82:85]
	v_mfma_f32_16x16x32_bf16 v[74:77], v[182:185], v[222:225], v[74:77]
	v_mfma_f32_16x16x32_bf16 v[66:69], v[190:193], v[222:225], v[66:69]
	s_setprio 0
	s_barrier
	s_add_i32 s26, s33, s19
	v_lshl_add_u64 v[178:179], v[178:179], 0, s[8:9]
	s_mov_b32 m0, s26
	ds_read_b128 v[194:197], v156 offset:49152
	ds_read_b128 v[198:201], v156 offset:50176
	ds_read_b128 v[202:205], v156 offset:51200
	ds_read_b128 v[206:209], v156 offset:52224
	ds_read_b128 v[210:213], v156 offset:53248
	ds_read_b128 v[214:217], v156 offset:54272
	ds_read_b128 v[218:221], v156 offset:55296
	ds_read_b128 v[222:225], v156 offset:56320
	global_load_lds_dwordx4 v[178:179], off
	s_add_i32 m0, s26, 0x2000
	s_add_u32 s24, s24, 0x40080
	v_lshl_add_u64 v[178:179], v[226:227], 0, s[8:9]
	s_addc_u32 s25, s25, 0
	s_add_i32 s26, s51, s19
	global_load_lds_dwordx4 v[178:179], off
	v_lshl_add_u64 v[178:179], s[24:25], 0, v[132:133]
	s_mov_b32 m0, s26
	s_nop 0
	global_load_lds_dwordx4 v[178:179], off
	v_lshl_add_u64 v[178:179], s[24:25], 0, v[136:137]
	s_add_i32 m0, s26, 0x2000
	s_nop 0
	global_load_lds_dwordx4 v[178:179], off
	v_lshl_add_u64 v[178:179], v[228:229], 0, s[8:9]
	s_mov_b32 m0, s38
	s_nop 0
	global_load_lds_dwordx4 v[178:179], off
	v_lshl_add_u64 v[178:179], v[230:231], 0, s[8:9]
	s_mov_b32 m0, s39
	s_nop 0
	global_load_lds_dwordx4 v[178:179], off
	s_waitcnt vmcnt(8)
	s_waitcnt lgkmcnt(0)
	s_barrier
	s_setprio 1
	s_waitcnt lgkmcnt(0)
	v_mfma_f32_16x16x32_bf16 v[62:65], v[158:161], v[194:197], v[62:65]
	v_mfma_f32_16x16x32_bf16 v[54:57], v[166:169], v[194:197], v[54:57]
	v_mfma_f32_16x16x32_bf16 v[46:49], v[158:161], v[202:205], v[46:49]
	v_mfma_f32_16x16x32_bf16 v[38:41], v[166:169], v[202:205], v[38:41]
	v_mfma_f32_16x16x32_bf16 v[30:33], v[158:161], v[210:213], v[30:33]
	v_mfma_f32_16x16x32_bf16 v[22:25], v[166:169], v[210:213], v[22:25]
	v_mfma_f32_16x16x32_bf16 v[14:17], v[158:161], v[218:221], v[14:17]
	v_mfma_f32_16x16x32_bf16 v[6:9], v[166:169], v[218:221], v[6:9]
	v_mfma_f32_16x16x32_bf16 v[62:65], v[162:165], v[198:201], v[62:65]
	v_mfma_f32_16x16x32_bf16 v[54:57], v[170:173], v[198:201], v[54:57]
	v_mfma_f32_16x16x32_bf16 v[46:49], v[162:165], v[206:209], v[46:49]
	v_mfma_f32_16x16x32_bf16 v[38:41], v[170:173], v[206:209], v[38:41]
	v_mfma_f32_16x16x32_bf16 v[30:33], v[162:165], v[214:217], v[30:33]
	v_mfma_f32_16x16x32_bf16 v[22:25], v[170:173], v[214:217], v[22:25]
	v_mfma_f32_16x16x32_bf16 v[14:17], v[162:165], v[222:225], v[14:17]
	v_mfma_f32_16x16x32_bf16 v[6:9], v[170:173], v[222:225], v[6:9]
	s_setprio 0
	s_setprio 1
	v_mfma_f32_16x16x32_bf16 v[58:61], v[174:177], v[194:197], v[58:61]
	v_mfma_f32_16x16x32_bf16 v[50:53], v[186:189], v[194:197], v[50:53]
	v_mfma_f32_16x16x32_bf16 v[42:45], v[174:177], v[202:205], v[42:45]
	v_mfma_f32_16x16x32_bf16 v[34:37], v[186:189], v[202:205], v[34:37]
	v_mfma_f32_16x16x32_bf16 v[26:29], v[174:177], v[210:213], v[26:29]
	v_mfma_f32_16x16x32_bf16 v[18:21], v[186:189], v[210:213], v[18:21]
	v_mfma_f32_16x16x32_bf16 v[10:13], v[174:177], v[218:221], v[10:13]
	v_mfma_f32_16x16x32_bf16 v[2:5], v[186:189], v[218:221], v[2:5]
	v_mfma_f32_16x16x32_bf16 v[58:61], v[182:185], v[198:201], v[58:61]
	v_mfma_f32_16x16x32_bf16 v[50:53], v[190:193], v[198:201], v[50:53]
	v_mfma_f32_16x16x32_bf16 v[42:45], v[182:185], v[206:209], v[42:45]
	v_mfma_f32_16x16x32_bf16 v[34:37], v[190:193], v[206:209], v[34:37]
	v_mfma_f32_16x16x32_bf16 v[26:29], v[182:185], v[214:217], v[26:29]
	v_mfma_f32_16x16x32_bf16 v[18:21], v[190:193], v[214:217], v[18:21]
	v_mfma_f32_16x16x32_bf16 v[10:13], v[182:185], v[222:225], v[10:13]
	v_mfma_f32_16x16x32_bf16 v[2:5], v[190:193], v[222:225], v[2:5]
	s_setprio 0
	s_barrier
	s_add_i32 s57, s57, 2
	s_add_u32 s22, s22, 0x100
	s_addc_u32 s23, s23, 0
	s_add_u32 s55, s55, 0x100
	s_addc_u32 s56, s56, 0

.LBB0_2026:
	ds_read_b128 v[144:147], v153
	ds_read_b128 v[156:159], v153 offset:1024
	ds_read_b128 v[160:163], v153 offset:2048
	ds_read_b128 v[164:167], v153 offset:3072
	ds_read_b128 v[168:171], v154
	ds_read_b128 v[172:175], v154 offset:1024
	ds_read_b128 v[176:179], v154 offset:2048
	ds_read_b128 v[180:183], v154 offset:3072
	s_add_i32 s28, s28, 1
	s_mul_i32 s0, s28, s31
	s_mul_hi_u32 s1, s28, s54
	s_add_i32 s1, s1, s0
	s_mul_i32 s0, s28, s54
	s_add_u32 s0, s0, s96
	s_addc_u32 s1, s1, s20
	v_cmp_gt_i64_e32 vcc, s[0:1], v[142:143]
	v_cmp_lt_i64_e64 s[2:3], s[0:1], v[140:141]
	s_cbranch_vccnz .LBB0_2032
	s_ashr_i32 s1, s0, 31
	s_lshr_b32 s1, s1, 29
	s_add_i32 s10, s0, s1
	s_and_b32 s1, s10, -8
	s_sub_i32 s11, s0, s1
	s_cmp_gt_i32 s11, -1
	s_mov_b64 s[0:1], -1
	s_cbranch_scc0 .LBB0_2029
	s_lshl_b32 s16, s11, 7
	s_mov_b64 s[0:1], 0

.LBB0_2036:
	s_add_u32 s40, s12, 0x100
	s_addc_u32 s41, s13, 0
	s_add_u32 s12, s14, 0xc000

	s_addc_u32 s13, s15, 0
	s_mov_b32 s42, -2


	s_add_u32 s14, s12, 0x4000
	s_addc_u32 s15, s13, 0
	s_cmp_eq_u32 s42, 40
	s_cselect_b32 s18, s2, s14
	s_cselect_b32 s19, s3, s15
	s_cselect_b32 s16, s10, s40
	s_cselect_b32 s17, s11, s41
	s_add_u32 s14, s18, 0x8000
	s_addc_u32 s15, s19, 0
	v_lshl_add_u64 v[148:149], s[12:13], 0, v[136:137]
	s_add_i32 m0, s24, 0xc000
	ds_read_b128 v[184:187], v155
	ds_read_b128 v[188:191], v155 offset:1024
	ds_read_b128 v[192:195], v155 offset:2048
	ds_read_b128 v[196:199], v155 offset:3072
	ds_read_b128 v[200:203], v155 offset:4096
	ds_read_b128 v[204:207], v155 offset:5120
	ds_read_b128 v[208:211], v155 offset:6144
	ds_read_b128 v[212:215], v155 offset:7168
	global_load_lds_dwordx4 v[148:149], off
	v_lshl_add_u64 v[148:149], s[12:13], 0, v[138:139]
	s_add_i32 m0, s24, 0xe000
	s_nop 0
	global_load_lds_dwordx4 v[148:149], off
	s_waitcnt vmcnt(8)
	s_waitcnt lgkmcnt(0)
	s_barrier
	s_setprio 1
	s_waitcnt lgkmcnt(0)
	v_mfma_f32_16x16x32_bf16 v[124:127], v[144:147], v[184:187], 0
	v_mfma_f32_16x16x32_bf16 v[120:123], v[160:163], v[184:187], 0
	v_mfma_f32_16x16x32_bf16 v[108:111], v[144:147], v[192:195], 0
	v_mfma_f32_16x16x32_bf16 v[104:107], v[160:163], v[192:195], 0
	v_mfma_f32_16x16x32_bf16 v[92:95], v[144:147], v[200:203], 0
	v_mfma_f32_16x16x32_bf16 v[88:91], v[160:163], v[200:203], 0
	v_mfma_f32_16x16x32_bf16 v[76:79], v[144:147], v[208:211], 0
	v_mfma_f32_16x16x32_bf16 v[72:75], v[160:163], v[208:211], 0
	v_mfma_f32_16x16x32_bf16 v[124:127], v[156:159], v[188:191], v[124:127]
	v_mfma_f32_16x16x32_bf16 v[120:123], v[164:167], v[188:191], v[120:123]
	v_mfma_f32_16x16x32_bf16 v[108:111], v[156:159], v[196:199], v[108:111]
	v_mfma_f32_16x16x32_bf16 v[104:107], v[164:167], v[196:199], v[104:107]
	v_mfma_f32_16x16x32_bf16 v[92:95], v[156:159], v[204:207], v[92:95]
	v_mfma_f32_16x16x32_bf16 v[88:91], v[164:167], v[204:207], v[88:91]
	v_mfma_f32_16x16x32_bf16 v[76:79], v[156:159], v[212:215], v[76:79]
	v_mfma_f32_16x16x32_bf16 v[72:75], v[164:167], v[212:215], v[72:75]
	s_setprio 0
	s_setprio 1
	v_mfma_f32_16x16x32_bf16 v[116:119], v[168:171], v[184:187], 0
	v_mfma_f32_16x16x32_bf16 v[112:115], v[176:179], v[184:187], 0
	v_mfma_f32_16x16x32_bf16 v[100:103], v[168:171], v[192:195], 0
	v_mfma_f32_16x16x32_bf16 v[96:99], v[176:179], v[192:195], 0
	v_mfma_f32_16x16x32_bf16 v[84:87], v[168:171], v[200:203], 0
	v_mfma_f32_16x16x32_bf16 v[80:83], v[176:179], v[200:203], 0
	v_mfma_f32_16x16x32_bf16 v[68:71], v[168:171], v[208:211], 0
	v_mfma_f32_16x16x32_bf16 v[64:67], v[176:179], v[208:211], 0
	v_mfma_f32_16x16x32_bf16 v[116:119], v[172:175], v[188:191], v[116:119]
	v_mfma_f32_16x16x32_bf16 v[112:115], v[180:183], v[188:191], v[112:115]
	v_mfma_f32_16x16x32_bf16 v[100:103], v[172:175], v[196:199], v[100:103]
	v_mfma_f32_16x16x32_bf16 v[96:99], v[180:183], v[196:199], v[96:99]
	v_mfma_f32_16x16x32_bf16 v[84:87], v[172:175], v[204:207], v[84:87]
	v_mfma_f32_16x16x32_bf16 v[80:83], v[180:183], v[204:207], v[80:83]
	v_mfma_f32_16x16x32_bf16 v[68:71], v[172:175], v[212:215], v[68:71]
	v_mfma_f32_16x16x32_bf16 v[64:67], v[180:183], v[212:215], v[64:67]
	s_setprio 0
	s_barrier
	s_add_i32 s33, s34, s23
	v_lshl_add_u64 v[148:149], s[16:17], 0, v[130:131]
	s_mov_b32 m0, s33
	ds_read_b128 v[184:187], v155 offset:16384
	ds_read_b128 v[188:191], v155 offset:17408
	ds_read_b128 v[192:195], v155 offset:18432
	ds_read_b128 v[196:199], v155 offset:19456
	ds_read_b128 v[200:203], v155 offset:20480
	ds_read_b128 v[204:207], v155 offset:21504
	ds_read_b128 v[208:211], v155 offset:22528
	ds_read_b128 v[212:215], v155 offset:23552
	global_load_lds_dwordx4 v[148:149], off
	s_add_i32 m0, s33, 0x2000
	s_add_u32 s46, s16, 0xb0000
	v_lshl_add_u64 v[216:217], s[16:17], 0, v[134:135]
	s_addc_u32 s47, s17, 0
	s_add_i32 s33, s35, s23
	global_load_lds_dwordx4 v[216:217], off
	v_lshl_add_u64 v[218:219], s[46:47], 0, v[130:131]
	s_mov_b32 m0, s33
	s_nop 0
	global_load_lds_dwordx4 v[218:219], off
	v_lshl_add_u64 v[218:219], s[46:47], 0, v[134:135]
	s_add_i32 m0, s33, 0x2000
	s_nop 0
	global_load_lds_dwordx4 v[218:219], off
	v_lshl_add_u64 v[218:219], s[18:19], 0, v[128:129]
	s_mov_b32 m0, s24
	s_nop 0
	global_load_lds_dwordx4 v[218:219], off
	v_lshl_add_u64 v[218:219], s[18:19], 0, v[132:133]
	s_mov_b32 m0, s25
	s_nop 0
	global_load_lds_dwordx4 v[218:219], off
	s_waitcnt vmcnt(8)
	s_waitcnt lgkmcnt(0)
	s_barrier
	s_setprio 1
	s_waitcnt lgkmcnt(0)
	v_mfma_f32_16x16x32_bf16 v[60:63], v[144:147], v[184:187], 0
	v_mfma_f32_16x16x32_bf16 v[56:59], v[160:163], v[184:187], 0
	v_mfma_f32_16x16x32_bf16 v[44:47], v[144:147], v[192:195], 0
	v_mfma_f32_16x16x32_bf16 v[40:43], v[160:163], v[192:195], 0
	v_mfma_f32_16x16x32_bf16 v[28:31], v[144:147], v[200:203], 0
	v_mfma_f32_16x16x32_bf16 v[24:27], v[160:163], v[200:203], 0
	v_mfma_f32_16x16x32_bf16 v[12:15], v[144:147], v[208:211], 0
	v_mfma_f32_16x16x32_bf16 v[8:11], v[160:163], v[208:211], 0
	v_mfma_f32_16x16x32_bf16 v[60:63], v[156:159], v[188:191], v[60:63]
	v_mfma_f32_16x16x32_bf16 v[56:59], v[164:167], v[188:191], v[56:59]
	v_mfma_f32_16x16x32_bf16 v[44:47], v[156:159], v[196:199], v[44:47]
	v_mfma_f32_16x16x32_bf16 v[40:43], v[164:167], v[196:199], v[40:43]
	v_mfma_f32_16x16x32_bf16 v[28:31], v[156:159], v[204:207], v[28:31]
	v_mfma_f32_16x16x32_bf16 v[24:27], v[164:167], v[204:207], v[24:27]
	v_mfma_f32_16x16x32_bf16 v[12:15], v[156:159], v[212:215], v[12:15]
	v_mfma_f32_16x16x32_bf16 v[8:11], v[164:167], v[212:215], v[8:11]
	s_setprio 0
	s_setprio 1
	v_mfma_f32_16x16x32_bf16 v[52:55], v[168:171], v[184:187], 0
	v_mfma_f32_16x16x32_bf16 v[48:51], v[176:179], v[184:187], 0
	v_mfma_f32_16x16x32_bf16 v[36:39], v[168:171], v[192:195], 0
	v_mfma_f32_16x16x32_bf16 v[32:35], v[176:179], v[192:195], 0
	v_mfma_f32_16x16x32_bf16 v[20:23], v[168:171], v[200:203], 0
	v_mfma_f32_16x16x32_bf16 v[16:19], v[176:179], v[200:203], 0
	v_mfma_f32_16x16x32_bf16 v[4:7], v[168:171], v[208:211], 0
	v_mfma_f32_16x16x32_bf16 v[0:3], v[176:179], v[208:211], 0
	v_mfma_f32_16x16x32_bf16 v[52:55], v[172:175], v[188:191], v[52:55]
	v_mfma_f32_16x16x32_bf16 v[48:51], v[180:183], v[188:191], v[48:51]
	v_mfma_f32_16x16x32_bf16 v[36:39], v[172:175], v[196:199], v[36:39]
	v_mfma_f32_16x16x32_bf16 v[32:35], v[180:183], v[196:199], v[32:35]
	v_mfma_f32_16x16x32_bf16 v[20:23], v[172:175], v[204:207], v[20:23]
	v_mfma_f32_16x16x32_bf16 v[16:19], v[180:183], v[204:207], v[16:19]
	v_mfma_f32_16x16x32_bf16 v[4:7], v[172:175], v[212:215], v[4:7]
	v_mfma_f32_16x16x32_bf16 v[0:3], v[180:183], v[212:215], v[0:3]
	s_setprio 0
	s_barrier
	s_add_i32 s33, 0, 0x18000
	s_add_i32 s43, 0, 0x1c000
	v_add_u32_e32 v164, s33, v151
	v_add_u32_e32 v180, s43, v151
	ds_read_b128 v[144:147], v164
	ds_read_b128 v[156:159], v164 offset:1024
	ds_read_b128 v[160:163], v164 offset:2048
	ds_read_b128 v[164:167], v164 offset:3072
	ds_read_b128 v[168:171], v180
	ds_read_b128 v[172:175], v180 offset:1024
	ds_read_b128 v[176:179], v180 offset:2048
	ds_read_b128 v[180:183], v180 offset:3072
	s_add_u32 s18, s18, 0x4000
	s_addc_u32 s19, s19, 0
	s_mov_b32 m0, s26
	v_lshl_add_u64 v[218:219], s[18:19], 0, v[128:129]
	ds_read_b128 v[184:187], v155 offset:32768
	ds_read_b128 v[188:191], v155 offset:33792
	ds_read_b128 v[192:195], v155 offset:34816
	ds_read_b128 v[196:199], v155 offset:35840
	ds_read_b128 v[200:203], v155 offset:36864
	ds_read_b128 v[204:207], v155 offset:37888
	ds_read_b128 v[208:211], v155 offset:38912
	ds_read_b128 v[212:215], v155 offset:39936
	global_load_lds_dwordx4 v[218:219], off
	v_lshl_add_u64 v[218:219], s[18:19], 0, v[132:133]
	s_mov_b32 m0, s27
	s_nop 0
	global_load_lds_dwordx4 v[218:219], off
	s_waitcnt vmcnt(8)
	s_waitcnt lgkmcnt(0)
	s_barrier
	s_setprio 1
	s_waitcnt lgkmcnt(0)
	v_mfma_f32_16x16x32_bf16 v[124:127], v[144:147], v[184:187], v[124:127]
	v_mfma_f32_16x16x32_bf16 v[120:123], v[160:163], v[184:187], v[120:123]
	v_mfma_f32_16x16x32_bf16 v[108:111], v[144:147], v[192:195], v[108:111]
	v_mfma_f32_16x16x32_bf16 v[104:107], v[160:163], v[192:195], v[104:107]
	v_mfma_f32_16x16x32_bf16 v[92:95], v[144:147], v[200:203], v[92:95]
	v_mfma_f32_16x16x32_bf16 v[88:91], v[160:163], v[200:203], v[88:91]
	v_mfma_f32_16x16x32_bf16 v[76:79], v[144:147], v[208:211], v[76:79]
	v_mfma_f32_16x16x32_bf16 v[72:75], v[160:163], v[208:211], v[72:75]
	v_mfma_f32_16x16x32_bf16 v[124:127], v[156:159], v[188:191], v[124:127]
	v_mfma_f32_16x16x32_bf16 v[120:123], v[164:167], v[188:191], v[120:123]
	v_mfma_f32_16x16x32_bf16 v[108:111], v[156:159], v[196:199], v[108:111]
	v_mfma_f32_16x16x32_bf16 v[104:107], v[164:167], v[196:199], v[104:107]
	v_mfma_f32_16x16x32_bf16 v[92:95], v[156:159], v[204:207], v[92:95]
	v_mfma_f32_16x16x32_bf16 v[88:91], v[164:167], v[204:207], v[88:91]
	v_mfma_f32_16x16x32_bf16 v[76:79], v[156:159], v[212:215], v[76:79]
	v_mfma_f32_16x16x32_bf16 v[72:75], v[164:167], v[212:215], v[72:75]
	s_setprio 0
	s_setprio 1
	v_mfma_f32_16x16x32_bf16 v[116:119], v[168:171], v[184:187], v[116:119]
	v_mfma_f32_16x16x32_bf16 v[112:115], v[176:179], v[184:187], v[112:115]
	v_mfma_f32_16x16x32_bf16 v[100:103], v[168:171], v[192:195], v[100:103]
	v_mfma_f32_16x16x32_bf16 v[96:99], v[176:179], v[192:195], v[96:99]
	v_mfma_f32_16x16x32_bf16 v[84:87], v[168:171], v[200:203], v[84:87]
	v_mfma_f32_16x16x32_bf16 v[80:83], v[176:179], v[200:203], v[80:83]
	v_mfma_f32_16x16x32_bf16 v[68:71], v[168:171], v[208:211], v[68:71]
	v_mfma_f32_16x16x32_bf16 v[64:67], v[176:179], v[208:211], v[64:67]
	v_mfma_f32_16x16x32_bf16 v[116:119], v[172:175], v[188:191], v[116:119]
	v_mfma_f32_16x16x32_bf16 v[112:115], v[180:183], v[188:191], v[112:115]
	v_mfma_f32_16x16x32_bf16 v[100:103], v[172:175], v[196:199], v[100:103]
	v_mfma_f32_16x16x32_bf16 v[96:99], v[180:183], v[196:199], v[96:99]
	v_mfma_f32_16x16x32_bf16 v[84:87], v[172:175], v[204:207], v[84:87]
	v_mfma_f32_16x16x32_bf16 v[80:83], v[180:183], v[204:207], v[80:83]
	v_mfma_f32_16x16x32_bf16 v[68:71], v[172:175], v[212:215], v[68:71]
	v_mfma_f32_16x16x32_bf16 v[64:67], v[180:183], v[212:215], v[64:67]
	s_setprio 0
	s_barrier
	s_add_i32 s18, s33, s23
	v_lshl_add_u64 v[148:149], v[148:149], 0, s[6:7]
	s_mov_b32 m0, s18
	ds_read_b128 v[184:187], v155 offset:49152
	ds_read_b128 v[188:191], v155 offset:50176
	ds_read_b128 v[192:195], v155 offset:51200
	ds_read_b128 v[196:199], v155 offset:52224
	ds_read_b128 v[200:203], v155 offset:53248
	ds_read_b128 v[204:207], v155 offset:54272
	ds_read_b128 v[208:211], v155 offset:55296
	ds_read_b128 v[212:215], v155 offset:56320
	global_load_lds_dwordx4 v[148:149], off
	s_add_i32 m0, s18, 0x2000
	s_add_u32 s16, s16, 0xb0080
	v_lshl_add_u64 v[148:149], v[216:217], 0, s[6:7]
	s_addc_u32 s17, s17, 0
	s_add_i32 s18, s43, s23
	global_load_lds_dwordx4 v[148:149], off
	v_lshl_add_u64 v[148:149], s[16:17], 0, v[130:131]
	s_mov_b32 m0, s18
	s_nop 0
	global_load_lds_dwordx4 v[148:149], off
	v_lshl_add_u64 v[148:149], s[16:17], 0, v[134:135]
	s_add_i32 m0, s18, 0x2000
	s_nop 0
	global_load_lds_dwordx4 v[148:149], off
	v_lshl_add_u64 v[148:149], s[14:15], 0, v[128:129]
	s_mov_b32 m0, s29
	s_nop 0
	global_load_lds_dwordx4 v[148:149], off
	v_lshl_add_u64 v[148:149], s[14:15], 0, v[132:133]
	s_mov_b32 m0, s30
	s_nop 0
	global_load_lds_dwordx4 v[148:149], off
	s_waitcnt vmcnt(8)
	s_waitcnt lgkmcnt(0)
	s_barrier
	s_setprio 1
	s_waitcnt lgkmcnt(0)
	v_mfma_f32_16x16x32_bf16 v[60:63], v[144:147], v[184:187], v[60:63]
	v_mfma_f32_16x16x32_bf16 v[56:59], v[160:163], v[184:187], v[56:59]
	v_mfma_f32_16x16x32_bf16 v[44:47], v[144:147], v[192:195], v[44:47]
	v_mfma_f32_16x16x32_bf16 v[40:43], v[160:163], v[192:195], v[40:43]
	v_mfma_f32_16x16x32_bf16 v[28:31], v[144:147], v[200:203], v[28:31]
	v_mfma_f32_16x16x32_bf16 v[24:27], v[160:163], v[200:203], v[24:27]
	v_mfma_f32_16x16x32_bf16 v[12:15], v[144:147], v[208:211], v[12:15]
	v_mfma_f32_16x16x32_bf16 v[8:11], v[160:163], v[208:211], v[8:11]
	v_mfma_f32_16x16x32_bf16 v[60:63], v[156:159], v[188:191], v[60:63]
	v_mfma_f32_16x16x32_bf16 v[56:59], v[164:167], v[188:191], v[56:59]
	v_mfma_f32_16x16x32_bf16 v[44:47], v[156:159], v[196:199], v[44:47]
	v_mfma_f32_16x16x32_bf16 v[40:43], v[164:167], v[196:199], v[40:43]
	v_mfma_f32_16x16x32_bf16 v[28:31], v[156:159], v[204:207], v[28:31]
	v_mfma_f32_16x16x32_bf16 v[24:27], v[164:167], v[204:207], v[24:27]
	v_mfma_f32_16x16x32_bf16 v[12:15], v[156:159], v[212:215], v[12:15]
	v_mfma_f32_16x16x32_bf16 v[8:11], v[164:167], v[212:215], v[8:11]
	s_setprio 0
	s_setprio 1
	v_mfma_f32_16x16x32_bf16 v[52:55], v[168:171], v[184:187], v[52:55]
	v_mfma_f32_16x16x32_bf16 v[48:51], v[176:179], v[184:187], v[48:51]
	v_mfma_f32_16x16x32_bf16 v[36:39], v[168:171], v[192:195], v[36:39]
	v_mfma_f32_16x16x32_bf16 v[32:35], v[176:179], v[192:195], v[32:35]
	v_mfma_f32_16x16x32_bf16 v[20:23], v[168:171], v[200:203], v[20:23]
	v_mfma_f32_16x16x32_bf16 v[16:19], v[176:179], v[200:203], v[16:19]
	v_mfma_f32_16x16x32_bf16 v[4:7], v[168:171], v[208:211], v[4:7]
	v_mfma_f32_16x16x32_bf16 v[0:3], v[176:179], v[208:211], v[0:3]
	v_mfma_f32_16x16x32_bf16 v[52:55], v[172:175], v[188:191], v[52:55]
	v_mfma_f32_16x16x32_bf16 v[48:51], v[180:183], v[188:191], v[48:51]
	v_mfma_f32_16x16x32_bf16 v[36:39], v[172:175], v[196:199], v[36:39]
	v_mfma_f32_16x16x32_bf16 v[32:35], v[180:183], v[196:199], v[32:35]
	v_mfma_f32_16x16x32_bf16 v[20:23], v[172:175], v[204:207], v[20:23]
	v_mfma_f32_16x16x32_bf16 v[16:19], v[180:183], v[204:207], v[16:19]
	v_mfma_f32_16x16x32_bf16 v[4:7], v[172:175], v[212:215], v[4:7]
	v_mfma_f32_16x16x32_bf16 v[0:3], v[180:183], v[212:215], v[0:3]
	s_setprio 0
	s_barrier
	s_add_i32 s42, s42, 2
	s_add_u32 s40, s40, 0x100
	s_addc_u32 s41, s41, 0
	s_add_u32 s12, s12, 0x10000
	s_addc_u32 s13, s13, 0
